# GEMM K-loops: the redundant s_waitcnt lgkmcnt(0) between each pre-MFMA barrier release and the first MFMA deleted (counter already drained before the barrier)
# baseline (speedup 1.0000x reference)
; #define PG8_STAGE(bufoff, gbase, voff) do { _Pragma("unroll") for (int _i = 0; _i < 2; ++_i) \
;         __builtin_amdgcn_global_load_lds((const unsigned*)((const char*)(gbase) + (voff)[_i]), (LAS unsigned*)(lds + (bufoff) + ldsw + _i * 8192), 16, 0, 0); } while (0)
; #define PG8_LDA(dst, b, h) do { _Pragma("unroll") for (int m = 0; m < 4; ++m) _Pragma("unroll") for (int k = 0; k < 2; ++k) dst[m][k] = *(const LAS bf16x8*)(lds + PG8_SA(b, h) + aoff + m * 2048 + k * 1024); } while (0)
; #define PG8_LDB(dst, b, h) do { _Pragma("unroll") for (int n = 0; n < 2; ++n) _Pragma("unroll") for (int k = 0; k < 2; ++k) dst[n][k] = *(const LAS bf16x8*)(lds + PG8_SB(b, h) + boff + n * 2048 + k * 1024); } while (0)
; #define PG8_MMA(ai, bj, At, Bt) do { __builtin_amdgcn_s_setprio(1); _Pragma("unroll") for (int m = 0; m < 4; ++m) _Pragma("unroll") for (int n = 0; n < 2; ++n) _Pragma("unroll") for (int k = 0; k < 2; ++k) \
;         acc[ai][bj][m][n] = __builtin_amdgcn_mfma_f32_16x16x32_bf16(Bt[n][k], At[m][k], acc[ai][bj][m][n], 0, 0, 0); __builtin_amdgcn_s_setprio(0); } while (0)
; #define PG8_WAIT_V(n) asm volatile("s_waitcnt vmcnt(" #n ")" ::: "memory")
; #define PG8_WAIT_L(n) asm volatile("s_waitcnt lgkmcnt(" #n ")" ::: "memory")
; #define PG8_BAR __builtin_amdgcn_s_barrier()
; template <int K, int LDA, int LDB, int KGRP, bool APERM, class Epi>
; __device__ __forceinline__ void gemm_phase(LAS unsigned char* lds, const Gemm g, const StaticOrder& S, const Epi& E, const int tid) {
;     ...
;         for (int t = 0; t < nt; t += 2) {
;             const bool last = (t == nt - 2);
;             const char* a1 = cA + (size_t)(t + 1) * kstep;
;             const char* a2 = last ? nA : cA + (size_t)(t + 2) * kstep; const char* b2 = last ? nB : cB + (size_t)(t + 2) * kstep;
;             const char* a3 = a2 + kstep; const char* b3 = b2 + kstep;
;             PG8_LDB(B0, 0, 0); PG8_LDB(B1, 0, 1); PG8_SCHED; PG8_LDA(At, 0, 0); PG8_STAGE(PG8_SA(1, 1), a1 + hstepA, voffA);
;             PG8_WAIT_V(8); PG8_WAIT_L(0); PG8_BAR; PG8_MMA(0, 0, At, B0); PG8_MMA(0, 1, At, B1); PG8_BAR; PG8_SCHED;
;             PG8_LDA(At, 0, 1); PG8_STAGE(PG8_SB(0, 0), b2, voffB); PG8_STAGE(PG8_SB(0, 1), b2 + hstepB, voffB); PG8_STAGE(PG8_SA(0, 0), a2, voffA);
;             PG8_WAIT_V(8); PG8_WAIT_L(0); PG8_BAR; PG8_MMA(1, 0, At, B0); PG8_MMA(1, 1, At, B1); PG8_BAR; PG8_SCHED;
.LBB0_263:
	s_add_u32 s3, s70, 0xfff80080
	s_addc_u32 s16, s71, -1
	s_add_i32 s53, 0, 0x10000
	s_cmp_eq_u32 s51, 28
	s_cselect_b32 s57, s18, s16
	s_cselect_b32 s56, s45, s3
	s_cselect_b32 s17, s46, s50
	s_cselect_b32 s16, s47, s48
	s_add_i32 s3, 0, 0x14000
	v_add_u32_e32 v106, s53, v175
	v_add_u32_e32 v168, s3, v175
	ds_read_b128 v[84:87], v106
	ds_read_b128 v[88:91], v106 offset:1024
	ds_read_b128 v[102:105], v106 offset:2048
	ds_read_b128 v[106:109], v106 offset:3072
	ds_read_b128 v[146:149], v168
	ds_read_b128 v[150:153], v168 offset:1024
	ds_read_b128 v[164:167], v168 offset:2048
	ds_read_b128 v[168:171], v168 offset:3072
	v_lshl_add_u64 v[172:173], s[70:71], 0, v[160:161]
	s_add_i32 m0, s28, 0xc000
	ds_read_b128 v[178:181], v177
	ds_read_b128 v[182:185], v177 offset:1024
	ds_read_b128 v[186:189], v177 offset:2048
	ds_read_b128 v[190:193], v177 offset:3072
	ds_read_b128 v[194:197], v177 offset:4096
	ds_read_b128 v[198:201], v177 offset:5120
	ds_read_b128 v[210:213], v177 offset:6144
	ds_read_b128 v[214:217], v177 offset:7168
	global_load_lds_dwordx4 v[172:173], off
	v_lshl_add_u64 v[172:173], s[70:71], 0, v[162:163]
	s_add_i32 m0, s28, 0xe000
	s_nop 0
	global_load_lds_dwordx4 v[172:173], off
	s_waitcnt vmcnt(8)
	s_waitcnt lgkmcnt(0)
	s_barrier
	s_setprio 1
	v_mfma_f32_16x16x32_bf16 v[142:145], v[84:87], v[178:181], v[142:145]
	v_mfma_f32_16x16x32_bf16 v[134:137], v[102:105], v[178:181], v[134:137]
	v_mfma_f32_16x16x32_bf16 v[126:129], v[84:87], v[186:189], v[126:129]
	v_mfma_f32_16x16x32_bf16 v[118:121], v[102:105], v[186:189], v[118:121]
	v_mfma_f32_16x16x32_bf16 v[110:113], v[84:87], v[194:197], v[110:113]
	v_mfma_f32_16x16x32_bf16 v[92:95], v[102:105], v[194:197], v[92:95]
	v_mfma_f32_16x16x32_bf16 v[76:79], v[84:87], v[210:213], v[76:79]
	v_mfma_f32_16x16x32_bf16 v[68:71], v[102:105], v[210:213], v[68:71]
	v_mfma_f32_16x16x32_bf16 v[142:145], v[88:91], v[182:185], v[142:145]
	v_mfma_f32_16x16x32_bf16 v[134:137], v[106:109], v[182:185], v[134:137]
	v_mfma_f32_16x16x32_bf16 v[126:129], v[88:91], v[190:193], v[126:129]
	v_mfma_f32_16x16x32_bf16 v[118:121], v[106:109], v[190:193], v[118:121]
	v_mfma_f32_16x16x32_bf16 v[110:113], v[88:91], v[198:201], v[110:113]
	v_mfma_f32_16x16x32_bf16 v[92:95], v[106:109], v[198:201], v[92:95]
	v_mfma_f32_16x16x32_bf16 v[76:79], v[88:91], v[214:217], v[76:79]
	v_mfma_f32_16x16x32_bf16 v[68:71], v[106:109], v[214:217], v[68:71]
	s_setprio 0
	s_setprio 1
	v_mfma_f32_16x16x32_bf16 v[138:141], v[146:149], v[178:181], v[138:141]
	v_mfma_f32_16x16x32_bf16 v[130:133], v[164:167], v[178:181], v[130:133]
	v_mfma_f32_16x16x32_bf16 v[122:125], v[146:149], v[186:189], v[122:125]
	v_mfma_f32_16x16x32_bf16 v[114:117], v[164:167], v[186:189], v[114:117]
	v_mfma_f32_16x16x32_bf16 v[98:101], v[146:149], v[194:197], v[98:101]
	v_mfma_f32_16x16x32_bf16 v[80:83], v[164:167], v[194:197], v[80:83]
	v_mfma_f32_16x16x32_bf16 v[72:75], v[146:149], v[210:213], v[72:75]
	v_mfma_f32_16x16x32_bf16 v[64:67], v[164:167], v[210:213], v[64:67]
	v_mfma_f32_16x16x32_bf16 v[138:141], v[150:153], v[182:185], v[138:141]
	v_mfma_f32_16x16x32_bf16 v[130:133], v[168:171], v[182:185], v[130:133]
	v_mfma_f32_16x16x32_bf16 v[122:125], v[150:153], v[190:193], v[122:125]
	v_mfma_f32_16x16x32_bf16 v[114:117], v[168:171], v[190:193], v[114:117]
	v_mfma_f32_16x16x32_bf16 v[98:101], v[150:153], v[198:201], v[98:101]
	v_mfma_f32_16x16x32_bf16 v[80:83], v[168:171], v[198:201], v[80:83]
	v_mfma_f32_16x16x32_bf16 v[72:75], v[150:153], v[214:217], v[72:75]
	v_mfma_f32_16x16x32_bf16 v[64:67], v[168:171], v[214:217], v[64:67]
	s_setprio 0
	s_barrier
	s_add_i32 s53, s53, s27
	v_lshl_add_u64 v[172:173], s[16:17], 0, v[96:97]
	s_mov_b32 m0, s53
	ds_read_b128 v[178:181], v177 offset:16384
	ds_read_b128 v[182:185], v177 offset:17408
	ds_read_b128 v[186:189], v177 offset:18432
	ds_read_b128 v[190:193], v177 offset:19456
	ds_read_b128 v[194:197], v177 offset:20480
	ds_read_b128 v[198:201], v177 offset:21504
	ds_read_b128 v[210:213], v177 offset:22528
	ds_read_b128 v[214:217], v177 offset:23552
	global_load_lds_dwordx4 v[172:173], off
	s_add_i32 m0, s53, 0x2000
	s_add_u32 s58, s16, 0x80000
	v_lshl_add_u64 v[218:219], s[16:17], 0, v[158:159]
	s_addc_u32 s59, s17, 0
	s_add_i32 s3, s3, s27
	global_load_lds_dwordx4 v[218:219], off
	v_lshl_add_u64 v[220:221], s[58:59], 0, v[96:97]
	s_mov_b32 m0, s3
	v_lshl_add_u64 v[222:223], s[56:57], 0, v[156:157]
	global_load_lds_dwordx4 v[220:221], off
	v_lshl_add_u64 v[220:221], s[58:59], 0, v[158:159]
	s_add_i32 m0, s3, 0x2000
	s_nop 0
	global_load_lds_dwordx4 v[220:221], off
	v_lshl_add_u64 v[220:221], s[56:57], 0, v[154:155]
	s_mov_b32 m0, s28
	s_nop 0
	global_load_lds_dwordx4 v[220:221], off
	s_mov_b32 m0, s29
	s_nop 0
	global_load_lds_dwordx4 v[222:223], off
	s_waitcnt vmcnt(8)
	s_waitcnt lgkmcnt(0)
	s_barrier
; #define PG8_STAGE(bufoff, gbase, voff) do { _Pragma("unroll") for (int _i = 0; _i < 2; ++_i) \
;         __builtin_amdgcn_global_load_lds((const unsigned*)((const char*)(gbase) + (voff)[_i]), (LAS unsigned*)(lds + (bufoff) + ldsw + _i * 8192), 16, 0, 0); } while (0)
; #define PG8_LDA(dst, b, h) do { _Pragma("unroll") for (int m = 0; m < 4; ++m) _Pragma("unroll") for (int k = 0; k < 2; ++k) dst[m][k] = *(const LAS bf16x8*)(lds + PG8_SA(b, h) + aoff + m * 2048 + k * 1024); } while (0)
; #define PG8_LDB(dst, b, h) do { _Pragma("unroll") for (int n = 0; n < 2; ++n) _Pragma("unroll") for (int k = 0; k < 2; ++k) dst[n][k] = *(const LAS bf16x8*)(lds + PG8_SB(b, h) + boff + n * 2048 + k * 1024); } while (0)
; #define PG8_MMA(ai, bj, At, Bt) do { __builtin_amdgcn_s_setprio(1); _Pragma("unroll") for (int m = 0; m < 4; ++m) _Pragma("unroll") for (int n = 0; n < 2; ++n) _Pragma("unroll") for (int k = 0; k < 2; ++k) \
;         acc[ai][bj][m][n] = __builtin_amdgcn_mfma_f32_16x16x32_bf16(Bt[n][k], At[m][k], acc[ai][bj][m][n], 0, 0, 0); __builtin_amdgcn_s_setprio(0); } while (0)
; #define PG8_WAIT_V(n) asm volatile("s_waitcnt vmcnt(" #n ")" ::: "memory")
; #define PG8_WAIT_L(n) asm volatile("s_waitcnt lgkmcnt(" #n ")" ::: "memory")
; #define PG8_BAR __builtin_amdgcn_s_barrier()
; #define PG8_SCHED __builtin_amdgcn_sched_barrier(0)
; template <int K, int LDA, int LDB, int KGRP, bool APERM, class Epi>
; __device__ __forceinline__ void gemm_phase(LAS unsigned char* lds, const Gemm g, const StaticOrder& S, const Epi& E, const int tid) {
;     ...
;             PG8_WAIT_V(8); PG8_WAIT_L(0); PG8_BAR; PG8_MMA(1, 0, At, B0); PG8_MMA(1, 1, At, B1); PG8_BAR; PG8_SCHED;
;             PG8_LDB(B0, 1, 0); PG8_LDB(B1, 1, 1); PG8_SCHED; PG8_LDA(At, 1, 0); PG8_STAGE(PG8_SA(0, 1), a2 + hstepA, voffA);
;             PG8_WAIT_V(8); PG8_WAIT_L(0); PG8_BAR; PG8_MMA(0, 0, At, B0); PG8_MMA(0, 1, At, B1); PG8_BAR; PG8_SCHED;
	s_setprio 1
	v_mfma_f32_16x16x32_bf16 v[60:63], v[84:87], v[178:181], v[60:63]
	v_mfma_f32_16x16x32_bf16 v[52:55], v[102:105], v[178:181], v[52:55]
	v_mfma_f32_16x16x32_bf16 v[44:47], v[84:87], v[186:189], v[44:47]
	v_mfma_f32_16x16x32_bf16 v[36:39], v[102:105], v[186:189], v[36:39]
	v_mfma_f32_16x16x32_bf16 v[28:31], v[84:87], v[194:197], v[28:31]
	v_mfma_f32_16x16x32_bf16 v[20:23], v[102:105], v[194:197], v[20:23]
	v_mfma_f32_16x16x32_bf16 v[12:15], v[84:87], v[210:213], v[12:15]
	v_mfma_f32_16x16x32_bf16 v[4:7], v[102:105], v[210:213], v[4:7]
	v_mfma_f32_16x16x32_bf16 v[60:63], v[88:91], v[182:185], v[60:63]
	v_mfma_f32_16x16x32_bf16 v[52:55], v[106:109], v[182:185], v[52:55]
	v_mfma_f32_16x16x32_bf16 v[44:47], v[88:91], v[190:193], v[44:47]
	v_mfma_f32_16x16x32_bf16 v[36:39], v[106:109], v[190:193], v[36:39]
	v_mfma_f32_16x16x32_bf16 v[28:31], v[88:91], v[198:201], v[28:31]
	v_mfma_f32_16x16x32_bf16 v[20:23], v[106:109], v[198:201], v[20:23]
	v_mfma_f32_16x16x32_bf16 v[12:15], v[88:91], v[214:217], v[12:15]
	v_mfma_f32_16x16x32_bf16 v[4:7], v[106:109], v[214:217], v[4:7]
	s_setprio 0
	s_setprio 1
	v_mfma_f32_16x16x32_bf16 v[56:59], v[146:149], v[178:181], v[56:59]
	v_mfma_f32_16x16x32_bf16 v[48:51], v[164:167], v[178:181], v[48:51]
	v_mfma_f32_16x16x32_bf16 v[40:43], v[146:149], v[186:189], v[40:43]
	v_mfma_f32_16x16x32_bf16 v[32:35], v[164:167], v[186:189], v[32:35]
	v_mfma_f32_16x16x32_bf16 v[24:27], v[146:149], v[194:197], v[24:27]
	v_mfma_f32_16x16x32_bf16 v[16:19], v[164:167], v[194:197], v[16:19]
	v_mfma_f32_16x16x32_bf16 v[8:11], v[146:149], v[210:213], v[8:11]
	v_mfma_f32_16x16x32_bf16 v[0:3], v[164:167], v[210:213], v[0:3]
	v_mfma_f32_16x16x32_bf16 v[56:59], v[150:153], v[182:185], v[56:59]
	v_mfma_f32_16x16x32_bf16 v[48:51], v[168:171], v[182:185], v[48:51]
	v_mfma_f32_16x16x32_bf16 v[40:43], v[150:153], v[190:193], v[40:43]
	v_mfma_f32_16x16x32_bf16 v[32:35], v[168:171], v[190:193], v[32:35]
	v_mfma_f32_16x16x32_bf16 v[24:27], v[150:153], v[198:201], v[24:27]
	v_mfma_f32_16x16x32_bf16 v[16:19], v[168:171], v[198:201], v[16:19]
	v_mfma_f32_16x16x32_bf16 v[8:11], v[150:153], v[214:217], v[8:11]
	v_mfma_f32_16x16x32_bf16 v[0:3], v[168:171], v[214:217], v[0:3]
	s_setprio 0
	s_barrier
	s_add_i32 s3, 0, 0x18000
	s_add_i32 s53, 0, 0x1c000
	v_add_u32_e32 v106, s3, v175
	v_add_u32_e32 v168, s53, v175
	ds_read_b128 v[84:87], v106
	ds_read_b128 v[88:91], v106 offset:1024
	ds_read_b128 v[102:105], v106 offset:2048
	ds_read_b128 v[106:109], v106 offset:3072
	ds_read_b128 v[146:149], v168
	ds_read_b128 v[150:153], v168 offset:1024
	ds_read_b128 v[164:167], v168 offset:2048
	ds_read_b128 v[168:171], v168 offset:3072
	s_add_u32 s56, s56, 0x80000
	s_addc_u32 s57, s57, 0
	s_mov_b32 m0, s30
	v_lshl_add_u64 v[224:225], s[56:57], 0, v[154:155]
	ds_read_b128 v[178:181], v177 offset:32768
	ds_read_b128 v[182:185], v177 offset:33792
	ds_read_b128 v[186:189], v177 offset:34816
	ds_read_b128 v[190:193], v177 offset:35840
	ds_read_b128 v[194:197], v177 offset:36864
	ds_read_b128 v[198:201], v177 offset:37888
	ds_read_b128 v[210:213], v177 offset:38912
	ds_read_b128 v[214:217], v177 offset:39936
	global_load_lds_dwordx4 v[224:225], off
	v_lshl_add_u64 v[224:225], s[56:57], 0, v[156:157]
	s_mov_b32 m0, s31
	s_nop 0
	global_load_lds_dwordx4 v[224:225], off
	s_waitcnt vmcnt(8)
	s_waitcnt lgkmcnt(0)
	s_barrier
	s_setprio 1
	v_mfma_f32_16x16x32_bf16 v[142:145], v[84:87], v[178:181], v[142:145]
	v_mfma_f32_16x16x32_bf16 v[134:137], v[102:105], v[178:181], v[134:137]
	v_mfma_f32_16x16x32_bf16 v[126:129], v[84:87], v[186:189], v[126:129]
	v_mfma_f32_16x16x32_bf16 v[118:121], v[102:105], v[186:189], v[118:121]
	v_mfma_f32_16x16x32_bf16 v[110:113], v[84:87], v[194:197], v[110:113]
	v_mfma_f32_16x16x32_bf16 v[92:95], v[102:105], v[194:197], v[92:95]
	v_mfma_f32_16x16x32_bf16 v[76:79], v[84:87], v[210:213], v[76:79]
	v_mfma_f32_16x16x32_bf16 v[68:71], v[102:105], v[210:213], v[68:71]
	v_mfma_f32_16x16x32_bf16 v[142:145], v[88:91], v[182:185], v[142:145]
	v_mfma_f32_16x16x32_bf16 v[134:137], v[106:109], v[182:185], v[134:137]
	v_mfma_f32_16x16x32_bf16 v[126:129], v[88:91], v[190:193], v[126:129]
	v_mfma_f32_16x16x32_bf16 v[118:121], v[106:109], v[190:193], v[118:121]
	v_mfma_f32_16x16x32_bf16 v[110:113], v[88:91], v[198:201], v[110:113]
	v_mfma_f32_16x16x32_bf16 v[92:95], v[106:109], v[198:201], v[92:95]
	v_mfma_f32_16x16x32_bf16 v[76:79], v[88:91], v[214:217], v[76:79]
	v_mfma_f32_16x16x32_bf16 v[68:71], v[106:109], v[214:217], v[68:71]
	s_setprio 0
	s_setprio 1
	v_mfma_f32_16x16x32_bf16 v[138:141], v[146:149], v[178:181], v[138:141]
	v_mfma_f32_16x16x32_bf16 v[130:133], v[164:167], v[178:181], v[130:133]
	v_mfma_f32_16x16x32_bf16 v[122:125], v[146:149], v[186:189], v[122:125]
	v_mfma_f32_16x16x32_bf16 v[114:117], v[164:167], v[186:189], v[114:117]
	v_mfma_f32_16x16x32_bf16 v[98:101], v[146:149], v[194:197], v[98:101]
	v_mfma_f32_16x16x32_bf16 v[80:83], v[164:167], v[194:197], v[80:83]
	v_mfma_f32_16x16x32_bf16 v[72:75], v[146:149], v[210:213], v[72:75]
	v_mfma_f32_16x16x32_bf16 v[64:67], v[164:167], v[210:213], v[64:67]
	v_mfma_f32_16x16x32_bf16 v[138:141], v[150:153], v[182:185], v[138:141]
	v_mfma_f32_16x16x32_bf16 v[130:133], v[168:171], v[182:185], v[130:133]
	v_mfma_f32_16x16x32_bf16 v[122:125], v[150:153], v[190:193], v[122:125]
	v_mfma_f32_16x16x32_bf16 v[114:117], v[168:171], v[190:193], v[114:117]
	v_mfma_f32_16x16x32_bf16 v[98:101], v[150:153], v[198:201], v[98:101]
	v_mfma_f32_16x16x32_bf16 v[80:83], v[168:171], v[198:201], v[80:83]
	v_mfma_f32_16x16x32_bf16 v[72:75], v[150:153], v[214:217], v[72:75]
	v_mfma_f32_16x16x32_bf16 v[64:67], v[168:171], v[214:217], v[64:67]
	s_setprio 0
	s_barrier
; #define PG8_STAGE(bufoff, gbase, voff) do { _Pragma("unroll") for (int _i = 0; _i < 2; ++_i) \
;         __builtin_amdgcn_global_load_lds((const unsigned*)((const char*)(gbase) + (voff)[_i]), (LAS unsigned*)(lds + (bufoff) + ldsw + _i * 8192), 16, 0, 0); } while (0)
; #define PG8_LDA(dst, b, h) do { _Pragma("unroll") for (int m = 0; m < 4; ++m) _Pragma("unroll") for (int k = 0; k < 2; ++k) dst[m][k] = *(const LAS bf16x8*)(lds + PG8_SA(b, h) + aoff + m * 2048 + k * 1024); } while (0)
; #define PG8_MMA(ai, bj, At, Bt) do { __builtin_amdgcn_s_setprio(1); _Pragma("unroll") for (int m = 0; m < 4; ++m) _Pragma("unroll") for (int n = 0; n < 2; ++n) _Pragma("unroll") for (int k = 0; k < 2; ++k) \
;         acc[ai][bj][m][n] = __builtin_amdgcn_mfma_f32_16x16x32_bf16(Bt[n][k], At[m][k], acc[ai][bj][m][n], 0, 0, 0); __builtin_amdgcn_s_setprio(0); } while (0)
; #define PG8_WAIT_V(n) asm volatile("s_waitcnt vmcnt(" #n ")" ::: "memory")
; #define PG8_WAIT_L(n) asm volatile("s_waitcnt lgkmcnt(" #n ")" ::: "memory")
; #define PG8_BAR __builtin_amdgcn_s_barrier()
; #define PG8_SCHED __builtin_amdgcn_sched_barrier(0)
; template <int K, int LDA, int LDB, int KGRP, bool APERM, class Epi>
; __device__ __forceinline__ void gemm_phase(LAS unsigned char* lds, const Gemm g, const StaticOrder& S, const Epi& E, const int tid) {
;     ...
;             PG8_LDA(At, 1, 1); PG8_STAGE(PG8_SB(1, 0), b3, voffB); PG8_STAGE(PG8_SB(1, 1), b3 + hstepB, voffB); PG8_STAGE(PG8_SA(1, 0), a3, voffA);
;             PG8_WAIT_V(8); PG8_WAIT_L(0); PG8_BAR; PG8_MMA(1, 0, At, B0); PG8_MMA(1, 1, At, B1); PG8_BAR; PG8_SCHED;
;         }
;         if (wr == 0) PG8_BAR;
	s_add_i32 s3, s3, s27
	v_lshl_add_u64 v[172:173], v[172:173], 0, s[38:39]
	s_mov_b32 m0, s3
	ds_read_b128 v[178:181], v177 offset:49152
	ds_read_b128 v[182:185], v177 offset:50176
	ds_read_b128 v[186:189], v177 offset:51200
	ds_read_b128 v[190:193], v177 offset:52224
	ds_read_b128 v[194:197], v177 offset:53248
	ds_read_b128 v[198:201], v177 offset:54272
	ds_read_b128 v[210:213], v177 offset:55296
	ds_read_b128 v[214:217], v177 offset:56320
	global_load_lds_dwordx4 v[172:173], off
	s_add_i32 m0, s3, 0x2000
	s_add_u32 s16, s16, 0x80080
	v_lshl_add_u64 v[172:173], v[218:219], 0, s[38:39]
	s_addc_u32 s17, s17, 0
	s_add_i32 s3, s53, s27
	global_load_lds_dwordx4 v[172:173], off
	v_lshl_add_u64 v[172:173], s[16:17], 0, v[96:97]
	s_mov_b32 m0, s3
	s_nop 0
	global_load_lds_dwordx4 v[172:173], off
	v_lshl_add_u64 v[172:173], s[16:17], 0, v[158:159]
	s_add_i32 m0, s3, 0x2000
	s_nop 0
	global_load_lds_dwordx4 v[172:173], off
	v_lshl_add_u64 v[172:173], v[220:221], 0, s[38:39]
	s_mov_b32 m0, s41
	s_nop 0
	global_load_lds_dwordx4 v[172:173], off
	v_lshl_add_u64 v[172:173], v[222:223], 0, s[38:39]
	s_mov_b32 m0, s42
	s_nop 0
	global_load_lds_dwordx4 v[172:173], off
	s_waitcnt vmcnt(8)
	s_waitcnt lgkmcnt(0)
	s_barrier
	s_setprio 1
	v_mfma_f32_16x16x32_bf16 v[60:63], v[84:87], v[178:181], v[60:63]
	v_mfma_f32_16x16x32_bf16 v[52:55], v[102:105], v[178:181], v[52:55]
	v_mfma_f32_16x16x32_bf16 v[44:47], v[84:87], v[186:189], v[44:47]
	v_mfma_f32_16x16x32_bf16 v[36:39], v[102:105], v[186:189], v[36:39]
	v_mfma_f32_16x16x32_bf16 v[28:31], v[84:87], v[194:197], v[28:31]
	v_mfma_f32_16x16x32_bf16 v[20:23], v[102:105], v[194:197], v[20:23]
	v_mfma_f32_16x16x32_bf16 v[12:15], v[84:87], v[210:213], v[12:15]
	v_mfma_f32_16x16x32_bf16 v[4:7], v[102:105], v[210:213], v[4:7]
	v_mfma_f32_16x16x32_bf16 v[60:63], v[88:91], v[182:185], v[60:63]
	v_mfma_f32_16x16x32_bf16 v[52:55], v[106:109], v[182:185], v[52:55]
	v_mfma_f32_16x16x32_bf16 v[44:47], v[88:91], v[190:193], v[44:47]
	v_mfma_f32_16x16x32_bf16 v[36:39], v[106:109], v[190:193], v[36:39]
	v_mfma_f32_16x16x32_bf16 v[28:31], v[88:91], v[198:201], v[28:31]
	v_mfma_f32_16x16x32_bf16 v[20:23], v[106:109], v[198:201], v[20:23]
	v_mfma_f32_16x16x32_bf16 v[12:15], v[88:91], v[214:217], v[12:15]
	v_mfma_f32_16x16x32_bf16 v[4:7], v[106:109], v[214:217], v[4:7]
	s_setprio 0
	s_setprio 1
	v_mfma_f32_16x16x32_bf16 v[56:59], v[146:149], v[178:181], v[56:59]
	v_mfma_f32_16x16x32_bf16 v[48:51], v[164:167], v[178:181], v[48:51]
	v_mfma_f32_16x16x32_bf16 v[40:43], v[146:149], v[186:189], v[40:43]
	v_mfma_f32_16x16x32_bf16 v[32:35], v[164:167], v[186:189], v[32:35]
	v_mfma_f32_16x16x32_bf16 v[24:27], v[146:149], v[194:197], v[24:27]
	v_mfma_f32_16x16x32_bf16 v[16:19], v[164:167], v[194:197], v[16:19]
	v_mfma_f32_16x16x32_bf16 v[8:11], v[146:149], v[210:213], v[8:11]
	v_mfma_f32_16x16x32_bf16 v[0:3], v[164:167], v[210:213], v[0:3]
	v_mfma_f32_16x16x32_bf16 v[56:59], v[150:153], v[182:185], v[56:59]
	v_mfma_f32_16x16x32_bf16 v[48:51], v[168:171], v[182:185], v[48:51]
	v_mfma_f32_16x16x32_bf16 v[40:43], v[150:153], v[190:193], v[40:43]
	v_mfma_f32_16x16x32_bf16 v[32:35], v[168:171], v[190:193], v[32:35]
	v_mfma_f32_16x16x32_bf16 v[24:27], v[150:153], v[198:201], v[24:27]
	v_mfma_f32_16x16x32_bf16 v[16:19], v[168:171], v[198:201], v[16:19]
	v_mfma_f32_16x16x32_bf16 v[8:11], v[150:153], v[214:217], v[8:11]
	v_mfma_f32_16x16x32_bf16 v[0:3], v[168:171], v[214:217], v[0:3]
	s_setprio 0
	s_barrier
	s_add_i32 s51, s51, 2
	s_add_u32 s70, s70, 0x100
	s_addc_u32 s71, s71, 0
	s_add_u32 s48, s48, 0x100
	s_addc_u32 s50, s50, 0
	s_cmp_gt_u32 s51, 29
	s_cbranch_scc0 .LBB0_263
	s_and_b64 vcc, exec, s[34:35]
	s_cbranch_vccz .LBB0_266
	s_barrier

; #define PG8_STAGE(bufoff, gbase, voff) do { _Pragma("unroll") for (int _i = 0; _i < 2; ++_i) \
;         __builtin_amdgcn_global_load_lds((const unsigned*)((const char*)(gbase) + (voff)[_i]), (LAS unsigned*)(lds + (bufoff) + ldsw + _i * 8192), 16, 0, 0); } while (0)
; #define PG8_LDA(dst, b, h) do { _Pragma("unroll") for (int m = 0; m < 4; ++m) _Pragma("unroll") for (int k = 0; k < 2; ++k) dst[m][k] = *(const LAS bf16x8*)(lds + PG8_SA(b, h) + aoff + m * 2048 + k * 1024); } while (0)
; #define PG8_LDB(dst, b, h) do { _Pragma("unroll") for (int n = 0; n < 2; ++n) _Pragma("unroll") for (int k = 0; k < 2; ++k) dst[n][k] = *(const LAS bf16x8*)(lds + PG8_SB(b, h) + boff + n * 2048 + k * 1024); } while (0)
; #define PG8_MMA(ai, bj, At, Bt) do { __builtin_amdgcn_s_setprio(1); _Pragma("unroll") for (int m = 0; m < 4; ++m) _Pragma("unroll") for (int n = 0; n < 2; ++n) _Pragma("unroll") for (int k = 0; k < 2; ++k) \
;         acc[ai][bj][m][n] = __builtin_amdgcn_mfma_f32_16x16x32_bf16(Bt[n][k], At[m][k], acc[ai][bj][m][n], 0, 0, 0); __builtin_amdgcn_s_setprio(0); } while (0)
; #define PG8_WAIT_V(n) asm volatile("s_waitcnt vmcnt(" #n ")" ::: "memory")
; #define PG8_WAIT_L(n) asm volatile("s_waitcnt lgkmcnt(" #n ")" ::: "memory")
; #define PG8_BAR __builtin_amdgcn_s_barrier()
; template <int K, int LDA, int LDB, int KGRP, bool APERM, class Epi>
; __device__ __forceinline__ void gemm_phase(LAS unsigned char* lds, const Gemm g, const StaticOrder& S, const Epi& E, const int tid) {
;     ...
;         for (int t = 0; t < nt; t += 2) {
;             const bool last = (t == nt - 2);
;             const char* a1 = cA + (size_t)(t + 1) * kstep;
;             const char* a2 = last ? nA : cA + (size_t)(t + 2) * kstep; const char* b2 = last ? nB : cB + (size_t)(t + 2) * kstep;
;             const char* a3 = a2 + kstep; const char* b3 = b2 + kstep;
;             PG8_LDB(B0, 0, 0); PG8_LDB(B1, 0, 1); PG8_SCHED; PG8_LDA(At, 0, 0); PG8_STAGE(PG8_SA(1, 1), a1 + hstepA, voffA);
;             PG8_WAIT_V(8); PG8_WAIT_L(0); PG8_BAR; PG8_MMA(0, 0, At, B0); PG8_MMA(0, 1, At, B1); PG8_BAR; PG8_SCHED;
;             PG8_LDA(At, 0, 1); PG8_STAGE(PG8_SB(0, 0), b2, voffB); PG8_STAGE(PG8_SB(0, 1), b2 + hstepB, voffB); PG8_STAGE(PG8_SA(0, 0), a2, voffA);
;             PG8_WAIT_V(8); PG8_WAIT_L(0); PG8_BAR; PG8_MMA(1, 0, At, B0); PG8_MMA(1, 1, At, B1); PG8_BAR; PG8_SCHED;
.LBB0_363:
	s_add_u32 s3, s8, 0xfff80080
	s_addc_u32 s16, s9, -1
	s_add_i32 s59, 0, 0x10000
	s_cmp_eq_u32 s58, 28
	s_cselect_b32 s57, s45, s16
	s_cselect_b32 s56, s46, s3
	v_add_u32_e32 v134, s59, v154
	s_cselect_b32 s17, s47, s51
	s_cselect_b32 s16, s48, s50
	s_add_i32 s3, 0, 0x14000
	ds_read_b128 v[160:163], v134
	ds_read_b128 v[164:167], v134 offset:1024
	ds_read_b128 v[168:171], v134 offset:2048
	ds_read_b128 v[172:175], v134 offset:3072
	v_add_u32_e32 v134, s3, v154
	ds_read_b128 v[176:179], v134
	ds_read_b128 v[180:183], v134 offset:1024
	ds_read_b128 v[184:187], v134 offset:2048
	ds_read_b128 v[188:191], v134 offset:3072
	v_lshl_add_u64 v[134:135], s[8:9], 0, v[130:131]
	s_add_i32 m0, s11, 0xc000
	ds_read_b128 v[192:195], v159
	ds_read_b128 v[196:199], v159 offset:1024
	ds_read_b128 v[210:213], v159 offset:2048
	ds_read_b128 v[214:217], v159 offset:3072
	ds_read_b128 v[218:221], v159 offset:4096
	ds_read_b128 v[222:225], v159 offset:5120
	ds_read_b128 v[226:229], v159 offset:6144
	ds_read_b128 v[230:233], v159 offset:7168
	global_load_lds_dwordx4 v[134:135], off
	v_lshl_add_u64 v[134:135], s[8:9], 0, v[132:133]
	s_add_i32 m0, s11, 0xe000
	s_nop 0
	global_load_lds_dwordx4 v[134:135], off
	s_waitcnt vmcnt(8)
	s_waitcnt lgkmcnt(0)
	s_barrier
	s_setprio 1
	v_mfma_f32_16x16x32_bf16 v[126:129], v[160:163], v[192:195], v[126:129]
	v_mfma_f32_16x16x32_bf16 v[122:125], v[168:171], v[192:195], v[122:125]
	v_mfma_f32_16x16x32_bf16 v[114:117], v[160:163], v[210:213], v[114:117]
	v_mfma_f32_16x16x32_bf16 v[106:109], v[168:171], v[210:213], v[106:109]
	v_mfma_f32_16x16x32_bf16 v[98:101], v[160:163], v[218:221], v[98:101]
	v_mfma_f32_16x16x32_bf16 v[88:91], v[168:171], v[218:221], v[88:91]
	v_mfma_f32_16x16x32_bf16 v[80:83], v[160:163], v[226:229], v[80:83]
	v_mfma_f32_16x16x32_bf16 v[72:75], v[168:171], v[226:229], v[72:75]
	v_mfma_f32_16x16x32_bf16 v[126:129], v[164:167], v[196:199], v[126:129]
	v_mfma_f32_16x16x32_bf16 v[122:125], v[172:175], v[196:199], v[122:125]
	v_mfma_f32_16x16x32_bf16 v[114:117], v[164:167], v[214:217], v[114:117]
	v_mfma_f32_16x16x32_bf16 v[106:109], v[172:175], v[214:217], v[106:109]
	v_mfma_f32_16x16x32_bf16 v[98:101], v[164:167], v[222:225], v[98:101]
	v_mfma_f32_16x16x32_bf16 v[88:91], v[172:175], v[222:225], v[88:91]
	v_mfma_f32_16x16x32_bf16 v[80:83], v[164:167], v[230:233], v[80:83]
	v_mfma_f32_16x16x32_bf16 v[72:75], v[172:175], v[230:233], v[72:75]
	s_setprio 0
	s_setprio 1
	v_mfma_f32_16x16x32_bf16 v[118:121], v[176:179], v[192:195], v[118:121]
	v_mfma_f32_16x16x32_bf16 v[110:113], v[184:187], v[192:195], v[110:113]
	v_mfma_f32_16x16x32_bf16 v[102:105], v[176:179], v[210:213], v[102:105]
	v_mfma_f32_16x16x32_bf16 v[92:95], v[184:187], v[210:213], v[92:95]
	v_mfma_f32_16x16x32_bf16 v[84:87], v[176:179], v[218:221], v[84:87]
	v_mfma_f32_16x16x32_bf16 v[76:79], v[184:187], v[218:221], v[76:79]
	v_mfma_f32_16x16x32_bf16 v[68:71], v[176:179], v[226:229], v[68:71]
	v_mfma_f32_16x16x32_bf16 v[64:67], v[184:187], v[226:229], v[64:67]
	v_mfma_f32_16x16x32_bf16 v[118:121], v[180:183], v[196:199], v[118:121]
	v_mfma_f32_16x16x32_bf16 v[110:113], v[188:191], v[196:199], v[110:113]
	v_mfma_f32_16x16x32_bf16 v[102:105], v[180:183], v[214:217], v[102:105]
	v_mfma_f32_16x16x32_bf16 v[92:95], v[188:191], v[214:217], v[92:95]
	v_mfma_f32_16x16x32_bf16 v[84:87], v[180:183], v[222:225], v[84:87]
	v_mfma_f32_16x16x32_bf16 v[76:79], v[188:191], v[222:225], v[76:79]
	v_mfma_f32_16x16x32_bf16 v[68:71], v[180:183], v[230:233], v[68:71]
	v_mfma_f32_16x16x32_bf16 v[64:67], v[188:191], v[230:233], v[64:67]
	s_setprio 0
	s_barrier
	s_add_i32 s59, s59, s29
	v_lshl_add_u64 v[134:135], s[16:17], 0, v[96:97]
	s_mov_b32 m0, s59
	ds_read_b128 v[192:195], v159 offset:16384
	ds_read_b128 v[196:199], v159 offset:17408
	ds_read_b128 v[210:213], v159 offset:18432
	ds_read_b128 v[214:217], v159 offset:19456
	ds_read_b128 v[218:221], v159 offset:20480
	ds_read_b128 v[222:225], v159 offset:21504
	ds_read_b128 v[226:229], v159 offset:22528
	ds_read_b128 v[230:233], v159 offset:23552
	global_load_lds_dwordx4 v[134:135], off
	s_add_i32 m0, s59, 0x2000
	s_add_u32 s68, s16, 0x80000
	v_lshl_add_u64 v[200:201], s[16:17], 0, v[150:151]
	s_addc_u32 s69, s17, 0
	s_add_i32 s3, s3, s29
	global_load_lds_dwordx4 v[200:201], off
	v_lshl_add_u64 v[234:235], s[68:69], 0, v[96:97]
	s_mov_b32 m0, s3
	v_lshl_add_u64 v[236:237], s[56:57], 0, v[148:149]
	global_load_lds_dwordx4 v[234:235], off
	v_lshl_add_u64 v[234:235], s[68:69], 0, v[150:151]
	s_add_i32 m0, s3, 0x2000
	s_nop 0
	global_load_lds_dwordx4 v[234:235], off
	v_lshl_add_u64 v[234:235], s[56:57], 0, v[146:147]
	s_mov_b32 m0, s11
	s_nop 0
	global_load_lds_dwordx4 v[234:235], off
	s_mov_b32 m0, s30
	s_nop 0
	global_load_lds_dwordx4 v[236:237], off
	s_waitcnt vmcnt(8)
	s_waitcnt lgkmcnt(0)
	s_barrier
; #define PG8_STAGE(bufoff, gbase, voff) do { _Pragma("unroll") for (int _i = 0; _i < 2; ++_i) \
;         __builtin_amdgcn_global_load_lds((const unsigned*)((const char*)(gbase) + (voff)[_i]), (LAS unsigned*)(lds + (bufoff) + ldsw + _i * 8192), 16, 0, 0); } while (0)
; #define PG8_LDA(dst, b, h) do { _Pragma("unroll") for (int m = 0; m < 4; ++m) _Pragma("unroll") for (int k = 0; k < 2; ++k) dst[m][k] = *(const LAS bf16x8*)(lds + PG8_SA(b, h) + aoff + m * 2048 + k * 1024); } while (0)
; #define PG8_LDB(dst, b, h) do { _Pragma("unroll") for (int n = 0; n < 2; ++n) _Pragma("unroll") for (int k = 0; k < 2; ++k) dst[n][k] = *(const LAS bf16x8*)(lds + PG8_SB(b, h) + boff + n * 2048 + k * 1024); } while (0)
; #define PG8_MMA(ai, bj, At, Bt) do { __builtin_amdgcn_s_setprio(1); _Pragma("unroll") for (int m = 0; m < 4; ++m) _Pragma("unroll") for (int n = 0; n < 2; ++n) _Pragma("unroll") for (int k = 0; k < 2; ++k) \
;         acc[ai][bj][m][n] = __builtin_amdgcn_mfma_f32_16x16x32_bf16(Bt[n][k], At[m][k], acc[ai][bj][m][n], 0, 0, 0); __builtin_amdgcn_s_setprio(0); } while (0)
; #define PG8_WAIT_V(n) asm volatile("s_waitcnt vmcnt(" #n ")" ::: "memory")
; #define PG8_WAIT_L(n) asm volatile("s_waitcnt lgkmcnt(" #n ")" ::: "memory")
; #define PG8_BAR __builtin_amdgcn_s_barrier()
; #define PG8_SCHED __builtin_amdgcn_sched_barrier(0)
; template <int K, int LDA, int LDB, int KGRP, bool APERM, class Epi>
; __device__ __forceinline__ void gemm_phase(LAS unsigned char* lds, const Gemm g, const StaticOrder& S, const Epi& E, const int tid) {
;     ...
;             PG8_WAIT_V(8); PG8_WAIT_L(0); PG8_BAR; PG8_MMA(1, 0, At, B0); PG8_MMA(1, 1, At, B1); PG8_BAR; PG8_SCHED;
;             PG8_LDB(B0, 1, 0); PG8_LDB(B1, 1, 1); PG8_SCHED; PG8_LDA(At, 1, 0); PG8_STAGE(PG8_SA(0, 1), a2 + hstepA, voffA);
;             PG8_WAIT_V(8); PG8_WAIT_L(0); PG8_BAR; PG8_MMA(0, 0, At, B0); PG8_MMA(0, 1, At, B1); PG8_BAR; PG8_SCHED;
	s_setprio 1
	v_mfma_f32_16x16x32_bf16 v[60:63], v[160:163], v[192:195], v[60:63]
	v_mfma_f32_16x16x32_bf16 v[56:59], v[168:171], v[192:195], v[56:59]
	v_mfma_f32_16x16x32_bf16 v[52:55], v[160:163], v[210:213], v[52:55]
	v_mfma_f32_16x16x32_bf16 v[44:47], v[168:171], v[210:213], v[44:47]
	v_mfma_f32_16x16x32_bf16 v[32:35], v[160:163], v[218:221], v[32:35]
	v_mfma_f32_16x16x32_bf16 v[24:27], v[168:171], v[218:221], v[24:27]
	v_mfma_f32_16x16x32_bf16 v[20:23], v[160:163], v[226:229], v[20:23]
	v_mfma_f32_16x16x32_bf16 v[12:15], v[168:171], v[226:229], v[12:15]
	v_mfma_f32_16x16x32_bf16 v[60:63], v[164:167], v[196:199], v[60:63]
	v_mfma_f32_16x16x32_bf16 v[56:59], v[172:175], v[196:199], v[56:59]
	v_mfma_f32_16x16x32_bf16 v[52:55], v[164:167], v[214:217], v[52:55]
	v_mfma_f32_16x16x32_bf16 v[44:47], v[172:175], v[214:217], v[44:47]
	v_mfma_f32_16x16x32_bf16 v[32:35], v[164:167], v[222:225], v[32:35]
	v_mfma_f32_16x16x32_bf16 v[24:27], v[172:175], v[222:225], v[24:27]
	v_mfma_f32_16x16x32_bf16 v[20:23], v[164:167], v[230:233], v[20:23]
	v_mfma_f32_16x16x32_bf16 v[12:15], v[172:175], v[230:233], v[12:15]
	s_setprio 0
	s_setprio 1
	v_mfma_f32_16x16x32_bf16 v[48:51], v[176:179], v[192:195], v[48:51]
	v_mfma_f32_16x16x32_bf16 v[40:43], v[184:187], v[192:195], v[40:43]
	v_mfma_f32_16x16x32_bf16 v[36:39], v[176:179], v[210:213], v[36:39]
	v_mfma_f32_16x16x32_bf16 v[28:31], v[184:187], v[210:213], v[28:31]
	v_mfma_f32_16x16x32_bf16 v[16:19], v[176:179], v[218:221], v[16:19]
	v_mfma_f32_16x16x32_bf16 v[8:11], v[184:187], v[218:221], v[8:11]
	v_mfma_f32_16x16x32_bf16 v[4:7], v[176:179], v[226:229], v[4:7]
	v_mfma_f32_16x16x32_bf16 v[0:3], v[184:187], v[226:229], v[0:3]
	v_mfma_f32_16x16x32_bf16 v[48:51], v[180:183], v[196:199], v[48:51]
	v_mfma_f32_16x16x32_bf16 v[40:43], v[188:191], v[196:199], v[40:43]
	v_mfma_f32_16x16x32_bf16 v[36:39], v[180:183], v[214:217], v[36:39]
	v_mfma_f32_16x16x32_bf16 v[28:31], v[188:191], v[214:217], v[28:31]
	v_mfma_f32_16x16x32_bf16 v[16:19], v[180:183], v[222:225], v[16:19]
	v_mfma_f32_16x16x32_bf16 v[8:11], v[188:191], v[222:225], v[8:11]
	v_mfma_f32_16x16x32_bf16 v[4:7], v[180:183], v[230:233], v[4:7]
	v_mfma_f32_16x16x32_bf16 v[0:3], v[188:191], v[230:233], v[0:3]
	s_setprio 0
	s_barrier
	s_add_i32 s3, 0, 0x18000
	s_add_i32 s59, 0, 0x1c000
	v_add_u32_e32 v172, s3, v154
	v_add_u32_e32 v188, s59, v154
	ds_read_b128 v[160:163], v172
	ds_read_b128 v[164:167], v172 offset:1024
	ds_read_b128 v[168:171], v172 offset:2048
	ds_read_b128 v[172:175], v172 offset:3072
	ds_read_b128 v[176:179], v188
	ds_read_b128 v[180:183], v188 offset:1024
	ds_read_b128 v[184:187], v188 offset:2048
	ds_read_b128 v[188:191], v188 offset:3072
	s_add_u32 s56, s56, 0x80000
	s_addc_u32 s57, s57, 0
	s_mov_b32 m0, s31
	v_lshl_add_u64 v[238:239], s[56:57], 0, v[146:147]
	ds_read_b128 v[192:195], v159 offset:32768
	ds_read_b128 v[196:199], v159 offset:33792
	ds_read_b128 v[210:213], v159 offset:34816
	ds_read_b128 v[214:217], v159 offset:35840
	ds_read_b128 v[218:221], v159 offset:36864
	ds_read_b128 v[222:225], v159 offset:37888
	ds_read_b128 v[226:229], v159 offset:38912
	ds_read_b128 v[230:233], v159 offset:39936
	global_load_lds_dwordx4 v[238:239], off
	v_lshl_add_u64 v[238:239], s[56:57], 0, v[148:149]
	s_mov_b32 m0, s37
	s_nop 0
	global_load_lds_dwordx4 v[238:239], off
	s_waitcnt vmcnt(8)
	s_waitcnt lgkmcnt(0)
	s_barrier
	s_setprio 1
	v_mfma_f32_16x16x32_bf16 v[126:129], v[160:163], v[192:195], v[126:129]
	v_mfma_f32_16x16x32_bf16 v[122:125], v[168:171], v[192:195], v[122:125]
	v_mfma_f32_16x16x32_bf16 v[114:117], v[160:163], v[210:213], v[114:117]
	v_mfma_f32_16x16x32_bf16 v[106:109], v[168:171], v[210:213], v[106:109]
	v_mfma_f32_16x16x32_bf16 v[98:101], v[160:163], v[218:221], v[98:101]
	v_mfma_f32_16x16x32_bf16 v[88:91], v[168:171], v[218:221], v[88:91]
	v_mfma_f32_16x16x32_bf16 v[80:83], v[160:163], v[226:229], v[80:83]
	v_mfma_f32_16x16x32_bf16 v[72:75], v[168:171], v[226:229], v[72:75]
	v_mfma_f32_16x16x32_bf16 v[126:129], v[164:167], v[196:199], v[126:129]
	v_mfma_f32_16x16x32_bf16 v[122:125], v[172:175], v[196:199], v[122:125]
	v_mfma_f32_16x16x32_bf16 v[114:117], v[164:167], v[214:217], v[114:117]
	v_mfma_f32_16x16x32_bf16 v[106:109], v[172:175], v[214:217], v[106:109]
	v_mfma_f32_16x16x32_bf16 v[98:101], v[164:167], v[222:225], v[98:101]
	v_mfma_f32_16x16x32_bf16 v[88:91], v[172:175], v[222:225], v[88:91]
	v_mfma_f32_16x16x32_bf16 v[80:83], v[164:167], v[230:233], v[80:83]
	v_mfma_f32_16x16x32_bf16 v[72:75], v[172:175], v[230:233], v[72:75]
	s_setprio 0
	s_setprio 1
	v_mfma_f32_16x16x32_bf16 v[118:121], v[176:179], v[192:195], v[118:121]
	v_mfma_f32_16x16x32_bf16 v[110:113], v[184:187], v[192:195], v[110:113]
	v_mfma_f32_16x16x32_bf16 v[102:105], v[176:179], v[210:213], v[102:105]
	v_mfma_f32_16x16x32_bf16 v[92:95], v[184:187], v[210:213], v[92:95]
	v_mfma_f32_16x16x32_bf16 v[84:87], v[176:179], v[218:221], v[84:87]
	v_mfma_f32_16x16x32_bf16 v[76:79], v[184:187], v[218:221], v[76:79]
	v_mfma_f32_16x16x32_bf16 v[68:71], v[176:179], v[226:229], v[68:71]
	v_mfma_f32_16x16x32_bf16 v[64:67], v[184:187], v[226:229], v[64:67]
	v_mfma_f32_16x16x32_bf16 v[118:121], v[180:183], v[196:199], v[118:121]
	v_mfma_f32_16x16x32_bf16 v[110:113], v[188:191], v[196:199], v[110:113]
	v_mfma_f32_16x16x32_bf16 v[102:105], v[180:183], v[214:217], v[102:105]
	v_mfma_f32_16x16x32_bf16 v[92:95], v[188:191], v[214:217], v[92:95]
	v_mfma_f32_16x16x32_bf16 v[84:87], v[180:183], v[222:225], v[84:87]
	v_mfma_f32_16x16x32_bf16 v[76:79], v[188:191], v[222:225], v[76:79]
	v_mfma_f32_16x16x32_bf16 v[68:71], v[180:183], v[230:233], v[68:71]
	v_mfma_f32_16x16x32_bf16 v[64:67], v[188:191], v[230:233], v[64:67]
	s_setprio 0
	s_barrier
; #define PG8_STAGE(bufoff, gbase, voff) do { _Pragma("unroll") for (int _i = 0; _i < 2; ++_i) \
;         __builtin_amdgcn_global_load_lds((const unsigned*)((const char*)(gbase) + (voff)[_i]), (LAS unsigned*)(lds + (bufoff) + ldsw + _i * 8192), 16, 0, 0); } while (0)
; #define PG8_LDA(dst, b, h) do { _Pragma("unroll") for (int m = 0; m < 4; ++m) _Pragma("unroll") for (int k = 0; k < 2; ++k) dst[m][k] = *(const LAS bf16x8*)(lds + PG8_SA(b, h) + aoff + m * 2048 + k * 1024); } while (0)
; #define PG8_MMA(ai, bj, At, Bt) do { __builtin_amdgcn_s_setprio(1); _Pragma("unroll") for (int m = 0; m < 4; ++m) _Pragma("unroll") for (int n = 0; n < 2; ++n) _Pragma("unroll") for (int k = 0; k < 2; ++k) \
;         acc[ai][bj][m][n] = __builtin_amdgcn_mfma_f32_16x16x32_bf16(Bt[n][k], At[m][k], acc[ai][bj][m][n], 0, 0, 0); __builtin_amdgcn_s_setprio(0); } while (0)
; #define PG8_WAIT_V(n) asm volatile("s_waitcnt vmcnt(" #n ")" ::: "memory")
; #define PG8_WAIT_L(n) asm volatile("s_waitcnt lgkmcnt(" #n ")" ::: "memory")
; #define PG8_BAR __builtin_amdgcn_s_barrier()
; #define PG8_SCHED __builtin_amdgcn_sched_barrier(0)
; template <int K, int LDA, int LDB, int KGRP, bool APERM, class Epi>
; __device__ __forceinline__ void gemm_phase(LAS unsigned char* lds, const Gemm g, const StaticOrder& S, const Epi& E, const int tid) {
;     ...
;             PG8_LDA(At, 1, 1); PG8_STAGE(PG8_SB(1, 0), b3, voffB); PG8_STAGE(PG8_SB(1, 1), b3 + hstepB, voffB); PG8_STAGE(PG8_SA(1, 0), a3, voffA);
;             PG8_WAIT_V(8); PG8_WAIT_L(0); PG8_BAR; PG8_MMA(1, 0, At, B0); PG8_MMA(1, 1, At, B1); PG8_BAR; PG8_SCHED;
;         }
;         if (wr == 0) PG8_BAR;
	s_add_i32 s3, s3, s29
	v_lshl_add_u64 v[134:135], v[134:135], 0, s[38:39]
	s_mov_b32 m0, s3
	ds_read_b128 v[192:195], v159 offset:49152
	ds_read_b128 v[196:199], v159 offset:50176
	ds_read_b128 v[210:213], v159 offset:51200
	ds_read_b128 v[214:217], v159 offset:52224
	ds_read_b128 v[218:221], v159 offset:53248
	ds_read_b128 v[222:225], v159 offset:54272
	ds_read_b128 v[226:229], v159 offset:55296
	ds_read_b128 v[230:233], v159 offset:56320
	global_load_lds_dwordx4 v[134:135], off
	s_add_i32 m0, s3, 0x2000
	s_add_u32 s16, s16, 0x80080
	v_lshl_add_u64 v[134:135], v[200:201], 0, s[38:39]
	s_addc_u32 s17, s17, 0
	s_add_i32 s3, s59, s29
	global_load_lds_dwordx4 v[134:135], off
	v_lshl_add_u64 v[134:135], s[16:17], 0, v[96:97]
	s_mov_b32 m0, s3
	s_nop 0
	global_load_lds_dwordx4 v[134:135], off
	v_lshl_add_u64 v[134:135], s[16:17], 0, v[150:151]
	s_add_i32 m0, s3, 0x2000
	s_nop 0
	global_load_lds_dwordx4 v[134:135], off
	v_lshl_add_u64 v[134:135], v[234:235], 0, s[38:39]
	s_mov_b32 m0, s41
	s_nop 0
	global_load_lds_dwordx4 v[134:135], off
	v_lshl_add_u64 v[134:135], v[236:237], 0, s[38:39]
	s_mov_b32 m0, s42
	s_nop 0
	global_load_lds_dwordx4 v[134:135], off
	s_waitcnt vmcnt(8)
	s_waitcnt lgkmcnt(0)
	s_barrier
	s_setprio 1
	v_mfma_f32_16x16x32_bf16 v[60:63], v[160:163], v[192:195], v[60:63]
	v_mfma_f32_16x16x32_bf16 v[56:59], v[168:171], v[192:195], v[56:59]
	v_mfma_f32_16x16x32_bf16 v[52:55], v[160:163], v[210:213], v[52:55]
	v_mfma_f32_16x16x32_bf16 v[44:47], v[168:171], v[210:213], v[44:47]
	v_mfma_f32_16x16x32_bf16 v[32:35], v[160:163], v[218:221], v[32:35]
	v_mfma_f32_16x16x32_bf16 v[24:27], v[168:171], v[218:221], v[24:27]
	v_mfma_f32_16x16x32_bf16 v[20:23], v[160:163], v[226:229], v[20:23]
	v_mfma_f32_16x16x32_bf16 v[12:15], v[168:171], v[226:229], v[12:15]
	v_mfma_f32_16x16x32_bf16 v[60:63], v[164:167], v[196:199], v[60:63]
	v_mfma_f32_16x16x32_bf16 v[56:59], v[172:175], v[196:199], v[56:59]
	v_mfma_f32_16x16x32_bf16 v[52:55], v[164:167], v[214:217], v[52:55]
	v_mfma_f32_16x16x32_bf16 v[44:47], v[172:175], v[214:217], v[44:47]
	v_mfma_f32_16x16x32_bf16 v[32:35], v[164:167], v[222:225], v[32:35]
	v_mfma_f32_16x16x32_bf16 v[24:27], v[172:175], v[222:225], v[24:27]
	v_mfma_f32_16x16x32_bf16 v[20:23], v[164:167], v[230:233], v[20:23]
	v_mfma_f32_16x16x32_bf16 v[12:15], v[172:175], v[230:233], v[12:15]
	s_setprio 0
	s_setprio 1
	v_mfma_f32_16x16x32_bf16 v[48:51], v[176:179], v[192:195], v[48:51]
	v_mfma_f32_16x16x32_bf16 v[40:43], v[184:187], v[192:195], v[40:43]
	v_mfma_f32_16x16x32_bf16 v[36:39], v[176:179], v[210:213], v[36:39]
	v_mfma_f32_16x16x32_bf16 v[28:31], v[184:187], v[210:213], v[28:31]
	v_mfma_f32_16x16x32_bf16 v[16:19], v[176:179], v[218:221], v[16:19]
	v_mfma_f32_16x16x32_bf16 v[8:11], v[184:187], v[218:221], v[8:11]
	v_mfma_f32_16x16x32_bf16 v[4:7], v[176:179], v[226:229], v[4:7]
	v_mfma_f32_16x16x32_bf16 v[0:3], v[184:187], v[226:229], v[0:3]
	v_mfma_f32_16x16x32_bf16 v[48:51], v[180:183], v[196:199], v[48:51]
	v_mfma_f32_16x16x32_bf16 v[40:43], v[188:191], v[196:199], v[40:43]
	v_mfma_f32_16x16x32_bf16 v[36:39], v[180:183], v[214:217], v[36:39]
	v_mfma_f32_16x16x32_bf16 v[28:31], v[188:191], v[214:217], v[28:31]
	v_mfma_f32_16x16x32_bf16 v[16:19], v[180:183], v[222:225], v[16:19]
	v_mfma_f32_16x16x32_bf16 v[8:11], v[188:191], v[222:225], v[8:11]
	v_mfma_f32_16x16x32_bf16 v[4:7], v[180:183], v[230:233], v[4:7]
	v_mfma_f32_16x16x32_bf16 v[0:3], v[188:191], v[230:233], v[0:3]
	s_setprio 0
	s_barrier
	s_add_i32 s58, s58, 2
	s_add_u32 s8, s8, 0x100
	s_addc_u32 s9, s9, 0
	s_add_u32 s50, s50, 0x100
	s_addc_u32 s51, s51, 0
	s_cmp_gt_u32 s58, 29
	s_cbranch_scc0 .LBB0_363
	s_and_b64 vcc, exec, s[52:53]
	s_cbranch_vccz .LBB0_366
	s_barrier

; #define PG8_STAGE(bufoff, gbase, voff) do { _Pragma("unroll") for (int _i = 0; _i < 2; ++_i) \
;         __builtin_amdgcn_global_load_lds((const unsigned*)((const char*)(gbase) + (voff)[_i]), (LAS unsigned*)(lds + (bufoff) + ldsw + _i * 8192), 16, 0, 0); } while (0)
; #define PG8_LDA(dst, b, h) do { _Pragma("unroll") for (int m = 0; m < 4; ++m) _Pragma("unroll") for (int k = 0; k < 2; ++k) dst[m][k] = *(const LAS bf16x8*)(lds + PG8_SA(b, h) + aoff + m * 2048 + k * 1024); } while (0)
; #define PG8_LDB(dst, b, h) do { _Pragma("unroll") for (int n = 0; n < 2; ++n) _Pragma("unroll") for (int k = 0; k < 2; ++k) dst[n][k] = *(const LAS bf16x8*)(lds + PG8_SB(b, h) + boff + n * 2048 + k * 1024); } while (0)
; #define PG8_MMA(ai, bj, At, Bt) do { __builtin_amdgcn_s_setprio(1); _Pragma("unroll") for (int m = 0; m < 4; ++m) _Pragma("unroll") for (int n = 0; n < 2; ++n) _Pragma("unroll") for (int k = 0; k < 2; ++k) \
;         acc[ai][bj][m][n] = __builtin_amdgcn_mfma_f32_16x16x32_bf16(Bt[n][k], At[m][k], acc[ai][bj][m][n], 0, 0, 0); __builtin_amdgcn_s_setprio(0); } while (0)
; #define PG8_WAIT_V(n) asm volatile("s_waitcnt vmcnt(" #n ")" ::: "memory")
; #define PG8_WAIT_L(n) asm volatile("s_waitcnt lgkmcnt(" #n ")" ::: "memory")
; #define PG8_BAR __builtin_amdgcn_s_barrier()
; template <int K, int LDA, int LDB, int KGRP, bool APERM, class Epi>
; __device__ __forceinline__ void gemm_phase(LAS unsigned char* lds, const Gemm g, const StaticOrder& S, const Epi& E, const int tid) {
;     ...
;         for (int t = 0; t < nt; t += 2) {
;             const bool last = (t == nt - 2);
;             const char* a1 = cA + (size_t)(t + 1) * kstep;
;             const char* a2 = last ? nA : cA + (size_t)(t + 2) * kstep; const char* b2 = last ? nB : cB + (size_t)(t + 2) * kstep;
;             const char* a3 = a2 + kstep; const char* b3 = b2 + kstep;
;             PG8_LDB(B0, 0, 0); PG8_LDB(B1, 0, 1); PG8_SCHED; PG8_LDA(At, 0, 0); PG8_STAGE(PG8_SA(1, 1), a1 + hstepA, voffA);
;             PG8_WAIT_V(8); PG8_WAIT_L(0); PG8_BAR; PG8_MMA(0, 0, At, B0); PG8_MMA(0, 1, At, B1); PG8_BAR; PG8_SCHED;
;             PG8_LDA(At, 0, 1); PG8_STAGE(PG8_SB(0, 0), b2, voffB); PG8_STAGE(PG8_SB(0, 1), b2 + hstepB, voffB); PG8_STAGE(PG8_SA(0, 0), a2, voffA);
;             PG8_WAIT_V(8); PG8_WAIT_L(0); PG8_BAR; PG8_MMA(1, 0, At, B0); PG8_MMA(1, 1, At, B1); PG8_BAR; PG8_SCHED;
.LBB0_391:
	s_add_u32 s3, s8, 0xfff80080
	s_addc_u32 s16, s9, -1
	s_add_i32 s53, 0, 0x10000
	s_cmp_eq_u32 s51, 28
	s_cselect_b32 s57, s44, s16
	s_cselect_b32 s56, s45, s3
	s_cselect_b32 s17, s46, s50
	s_cselect_b32 s16, s47, s48
	s_add_i32 s3, 0, 0x14000
	v_add_u32_e32 v142, s53, v159
	v_add_u32_e32 v156, s3, v159
	ds_read_b128 v[130:133], v142
	ds_read_b128 v[134:137], v142 offset:1024
	ds_read_b128 v[138:141], v142 offset:2048
	ds_read_b128 v[142:145], v142 offset:3072
	ds_read_b128 v[166:169], v156
	ds_read_b128 v[170:173], v156 offset:1024
	ds_read_b128 v[174:177], v156 offset:2048
	ds_read_b128 v[178:181], v156 offset:3072
	v_lshl_add_u64 v[156:157], s[8:9], 0, v[152:153]
	s_add_i32 m0, s30, 0xc000
	ds_read_b128 v[182:185], v164
	ds_read_b128 v[186:189], v164 offset:1024
	ds_read_b128 v[190:193], v164 offset:2048
	ds_read_b128 v[194:197], v164 offset:3072
	ds_read_b128 v[198:201], v164 offset:4096
	ds_read_b128 v[210:213], v164 offset:5120
	ds_read_b128 v[214:217], v164 offset:6144
	ds_read_b128 v[218:221], v164 offset:7168
	global_load_lds_dwordx4 v[156:157], off
	v_lshl_add_u64 v[156:157], s[8:9], 0, v[154:155]
	s_add_i32 m0, s30, 0xe000
	s_nop 0
	global_load_lds_dwordx4 v[156:157], off
	s_waitcnt vmcnt(8)
	s_waitcnt lgkmcnt(0)
	s_barrier
	s_setprio 1
	v_mfma_f32_16x16x32_bf16 v[126:129], v[130:133], v[182:185], v[126:129]
	v_mfma_f32_16x16x32_bf16 v[122:125], v[138:141], v[182:185], v[122:125]
	v_mfma_f32_16x16x32_bf16 v[114:117], v[130:133], v[190:193], v[114:117]
	v_mfma_f32_16x16x32_bf16 v[110:113], v[138:141], v[190:193], v[110:113]
	v_mfma_f32_16x16x32_bf16 v[102:105], v[130:133], v[198:201], v[102:105]
	v_mfma_f32_16x16x32_bf16 v[92:95], v[138:141], v[198:201], v[92:95]
	v_mfma_f32_16x16x32_bf16 v[84:87], v[130:133], v[214:217], v[84:87]
	v_mfma_f32_16x16x32_bf16 v[76:79], v[138:141], v[214:217], v[76:79]
	v_mfma_f32_16x16x32_bf16 v[126:129], v[134:137], v[186:189], v[126:129]
	v_mfma_f32_16x16x32_bf16 v[122:125], v[142:145], v[186:189], v[122:125]
	v_mfma_f32_16x16x32_bf16 v[114:117], v[134:137], v[194:197], v[114:117]
	v_mfma_f32_16x16x32_bf16 v[110:113], v[142:145], v[194:197], v[110:113]
	v_mfma_f32_16x16x32_bf16 v[102:105], v[134:137], v[210:213], v[102:105]
	v_mfma_f32_16x16x32_bf16 v[92:95], v[142:145], v[210:213], v[92:95]
	v_mfma_f32_16x16x32_bf16 v[84:87], v[134:137], v[218:221], v[84:87]
	v_mfma_f32_16x16x32_bf16 v[76:79], v[142:145], v[218:221], v[76:79]
	s_setprio 0
	s_setprio 1
	v_mfma_f32_16x16x32_bf16 v[118:121], v[166:169], v[182:185], v[118:121]
	v_mfma_f32_16x16x32_bf16 v[106:109], v[174:177], v[182:185], v[106:109]
	v_mfma_f32_16x16x32_bf16 v[98:101], v[166:169], v[190:193], v[98:101]
	v_mfma_f32_16x16x32_bf16 v[88:91], v[174:177], v[190:193], v[88:91]
	v_mfma_f32_16x16x32_bf16 v[80:83], v[166:169], v[198:201], v[80:83]
	v_mfma_f32_16x16x32_bf16 v[72:75], v[174:177], v[198:201], v[72:75]
	v_mfma_f32_16x16x32_bf16 v[68:71], v[166:169], v[214:217], v[68:71]
	v_mfma_f32_16x16x32_bf16 v[64:67], v[174:177], v[214:217], v[64:67]
	v_mfma_f32_16x16x32_bf16 v[118:121], v[170:173], v[186:189], v[118:121]
	v_mfma_f32_16x16x32_bf16 v[106:109], v[178:181], v[186:189], v[106:109]
	v_mfma_f32_16x16x32_bf16 v[98:101], v[170:173], v[194:197], v[98:101]
	v_mfma_f32_16x16x32_bf16 v[88:91], v[178:181], v[194:197], v[88:91]
	v_mfma_f32_16x16x32_bf16 v[80:83], v[170:173], v[210:213], v[80:83]
	v_mfma_f32_16x16x32_bf16 v[72:75], v[178:181], v[210:213], v[72:75]
	v_mfma_f32_16x16x32_bf16 v[68:71], v[170:173], v[218:221], v[68:71]
	v_mfma_f32_16x16x32_bf16 v[64:67], v[178:181], v[218:221], v[64:67]
	s_setprio 0
	s_barrier
	s_add_i32 s53, s53, s29
	v_lshl_add_u64 v[156:157], s[16:17], 0, v[96:97]
	s_mov_b32 m0, s53
	ds_read_b128 v[182:185], v164 offset:16384
	ds_read_b128 v[186:189], v164 offset:17408
	ds_read_b128 v[190:193], v164 offset:18432
	ds_read_b128 v[194:197], v164 offset:19456
	ds_read_b128 v[198:201], v164 offset:20480
	ds_read_b128 v[210:213], v164 offset:21504
	ds_read_b128 v[214:217], v164 offset:22528
	ds_read_b128 v[218:221], v164 offset:23552
	global_load_lds_dwordx4 v[156:157], off
	s_add_i32 m0, s53, 0x2000
	s_add_u32 s58, s16, 0x80000
	v_lshl_add_u64 v[222:223], s[16:17], 0, v[150:151]
	s_addc_u32 s59, s17, 0
	s_add_i32 s3, s3, s29
	global_load_lds_dwordx4 v[222:223], off
	v_lshl_add_u64 v[224:225], s[58:59], 0, v[96:97]
	s_mov_b32 m0, s3
	v_lshl_add_u64 v[226:227], s[56:57], 0, v[148:149]
	global_load_lds_dwordx4 v[224:225], off
	v_lshl_add_u64 v[224:225], s[58:59], 0, v[150:151]
	s_add_i32 m0, s3, 0x2000
	s_nop 0
	global_load_lds_dwordx4 v[224:225], off
	v_lshl_add_u64 v[224:225], s[56:57], 0, v[146:147]
	s_mov_b32 m0, s30
	s_nop 0
	global_load_lds_dwordx4 v[224:225], off
	s_mov_b32 m0, s31
	s_nop 0
	global_load_lds_dwordx4 v[226:227], off
	s_waitcnt vmcnt(8)
	s_waitcnt lgkmcnt(0)
	s_barrier
; #define PG8_STAGE(bufoff, gbase, voff) do { _Pragma("unroll") for (int _i = 0; _i < 2; ++_i) \
;         __builtin_amdgcn_global_load_lds((const unsigned*)((const char*)(gbase) + (voff)[_i]), (LAS unsigned*)(lds + (bufoff) + ldsw + _i * 8192), 16, 0, 0); } while (0)
; #define PG8_LDA(dst, b, h) do { _Pragma("unroll") for (int m = 0; m < 4; ++m) _Pragma("unroll") for (int k = 0; k < 2; ++k) dst[m][k] = *(const LAS bf16x8*)(lds + PG8_SA(b, h) + aoff + m * 2048 + k * 1024); } while (0)
; #define PG8_LDB(dst, b, h) do { _Pragma("unroll") for (int n = 0; n < 2; ++n) _Pragma("unroll") for (int k = 0; k < 2; ++k) dst[n][k] = *(const LAS bf16x8*)(lds + PG8_SB(b, h) + boff + n * 2048 + k * 1024); } while (0)
; #define PG8_MMA(ai, bj, At, Bt) do { __builtin_amdgcn_s_setprio(1); _Pragma("unroll") for (int m = 0; m < 4; ++m) _Pragma("unroll") for (int n = 0; n < 2; ++n) _Pragma("unroll") for (int k = 0; k < 2; ++k) \
;         acc[ai][bj][m][n] = __builtin_amdgcn_mfma_f32_16x16x32_bf16(Bt[n][k], At[m][k], acc[ai][bj][m][n], 0, 0, 0); __builtin_amdgcn_s_setprio(0); } while (0)
; #define PG8_WAIT_V(n) asm volatile("s_waitcnt vmcnt(" #n ")" ::: "memory")
; #define PG8_WAIT_L(n) asm volatile("s_waitcnt lgkmcnt(" #n ")" ::: "memory")
; #define PG8_BAR __builtin_amdgcn_s_barrier()
; #define PG8_SCHED __builtin_amdgcn_sched_barrier(0)
; template <int K, int LDA, int LDB, int KGRP, bool APERM, class Epi>
; __device__ __forceinline__ void gemm_phase(LAS unsigned char* lds, const Gemm g, const StaticOrder& S, const Epi& E, const int tid) {
;     ...
;             PG8_WAIT_V(8); PG8_WAIT_L(0); PG8_BAR; PG8_MMA(1, 0, At, B0); PG8_MMA(1, 1, At, B1); PG8_BAR; PG8_SCHED;
;             PG8_LDB(B0, 1, 0); PG8_LDB(B1, 1, 1); PG8_SCHED; PG8_LDA(At, 1, 0); PG8_STAGE(PG8_SA(0, 1), a2 + hstepA, voffA);
;             PG8_WAIT_V(8); PG8_WAIT_L(0); PG8_BAR; PG8_MMA(0, 0, At, B0); PG8_MMA(0, 1, At, B1); PG8_BAR; PG8_SCHED;
	s_setprio 1
	v_mfma_f32_16x16x32_bf16 v[60:63], v[130:133], v[182:185], v[60:63]
	v_mfma_f32_16x16x32_bf16 v[56:59], v[138:141], v[182:185], v[56:59]
	v_mfma_f32_16x16x32_bf16 v[52:55], v[130:133], v[190:193], v[52:55]
	v_mfma_f32_16x16x32_bf16 v[44:47], v[138:141], v[190:193], v[44:47]
	v_mfma_f32_16x16x32_bf16 v[36:39], v[130:133], v[198:201], v[36:39]
	v_mfma_f32_16x16x32_bf16 v[28:31], v[138:141], v[198:201], v[28:31]
	v_mfma_f32_16x16x32_bf16 v[20:23], v[130:133], v[214:217], v[20:23]
	v_mfma_f32_16x16x32_bf16 v[12:15], v[138:141], v[214:217], v[12:15]
	v_mfma_f32_16x16x32_bf16 v[60:63], v[134:137], v[186:189], v[60:63]
	v_mfma_f32_16x16x32_bf16 v[56:59], v[142:145], v[186:189], v[56:59]
	v_mfma_f32_16x16x32_bf16 v[52:55], v[134:137], v[194:197], v[52:55]
	v_mfma_f32_16x16x32_bf16 v[44:47], v[142:145], v[194:197], v[44:47]
	v_mfma_f32_16x16x32_bf16 v[36:39], v[134:137], v[210:213], v[36:39]
	v_mfma_f32_16x16x32_bf16 v[28:31], v[142:145], v[210:213], v[28:31]
	v_mfma_f32_16x16x32_bf16 v[20:23], v[134:137], v[218:221], v[20:23]
	v_mfma_f32_16x16x32_bf16 v[12:15], v[142:145], v[218:221], v[12:15]
	s_setprio 0
	s_setprio 1
	v_mfma_f32_16x16x32_bf16 v[48:51], v[166:169], v[182:185], v[48:51]
	v_mfma_f32_16x16x32_bf16 v[40:43], v[174:177], v[182:185], v[40:43]
	v_mfma_f32_16x16x32_bf16 v[32:35], v[166:169], v[190:193], v[32:35]
	v_mfma_f32_16x16x32_bf16 v[24:27], v[174:177], v[190:193], v[24:27]
	v_mfma_f32_16x16x32_bf16 v[16:19], v[166:169], v[198:201], v[16:19]
	v_mfma_f32_16x16x32_bf16 v[8:11], v[174:177], v[198:201], v[8:11]
	v_mfma_f32_16x16x32_bf16 v[4:7], v[166:169], v[214:217], v[4:7]
	v_mfma_f32_16x16x32_bf16 v[0:3], v[174:177], v[214:217], v[0:3]
	v_mfma_f32_16x16x32_bf16 v[48:51], v[170:173], v[186:189], v[48:51]
	v_mfma_f32_16x16x32_bf16 v[40:43], v[178:181], v[186:189], v[40:43]
	v_mfma_f32_16x16x32_bf16 v[32:35], v[170:173], v[194:197], v[32:35]
	v_mfma_f32_16x16x32_bf16 v[24:27], v[178:181], v[194:197], v[24:27]
	v_mfma_f32_16x16x32_bf16 v[16:19], v[170:173], v[210:213], v[16:19]
	v_mfma_f32_16x16x32_bf16 v[8:11], v[178:181], v[210:213], v[8:11]
	v_mfma_f32_16x16x32_bf16 v[4:7], v[170:173], v[218:221], v[4:7]
	v_mfma_f32_16x16x32_bf16 v[0:3], v[178:181], v[218:221], v[0:3]
	s_setprio 0
	s_barrier
	s_add_i32 s3, 0, 0x18000
	s_add_i32 s53, 0, 0x1c000
	v_add_u32_e32 v142, s3, v159
	v_add_u32_e32 v165, s53, v159
	ds_read_b128 v[130:133], v142
	ds_read_b128 v[134:137], v142 offset:1024
	ds_read_b128 v[138:141], v142 offset:2048
	ds_read_b128 v[142:145], v142 offset:3072
	ds_read_b128 v[166:169], v165
	ds_read_b128 v[170:173], v165 offset:1024
	ds_read_b128 v[174:177], v165 offset:2048
	ds_read_b128 v[178:181], v165 offset:3072
	s_add_u32 s56, s56, 0x80000
	s_addc_u32 s57, s57, 0
	s_mov_b32 m0, s37
	v_lshl_add_u64 v[228:229], s[56:57], 0, v[146:147]
	ds_read_b128 v[182:185], v164 offset:32768
	ds_read_b128 v[186:189], v164 offset:33792
	ds_read_b128 v[190:193], v164 offset:34816
	ds_read_b128 v[194:197], v164 offset:35840
	ds_read_b128 v[198:201], v164 offset:36864
	ds_read_b128 v[210:213], v164 offset:37888
	ds_read_b128 v[214:217], v164 offset:38912
	ds_read_b128 v[218:221], v164 offset:39936
	global_load_lds_dwordx4 v[228:229], off
	v_lshl_add_u64 v[228:229], s[56:57], 0, v[148:149]
	s_mov_b32 m0, s41
	s_nop 0
	global_load_lds_dwordx4 v[228:229], off
	s_waitcnt vmcnt(8)
	s_waitcnt lgkmcnt(0)
	s_barrier
	s_setprio 1
	v_mfma_f32_16x16x32_bf16 v[126:129], v[130:133], v[182:185], v[126:129]
	v_mfma_f32_16x16x32_bf16 v[122:125], v[138:141], v[182:185], v[122:125]
	v_mfma_f32_16x16x32_bf16 v[114:117], v[130:133], v[190:193], v[114:117]
	v_mfma_f32_16x16x32_bf16 v[110:113], v[138:141], v[190:193], v[110:113]
	v_mfma_f32_16x16x32_bf16 v[102:105], v[130:133], v[198:201], v[102:105]
	v_mfma_f32_16x16x32_bf16 v[92:95], v[138:141], v[198:201], v[92:95]
	v_mfma_f32_16x16x32_bf16 v[84:87], v[130:133], v[214:217], v[84:87]
	v_mfma_f32_16x16x32_bf16 v[76:79], v[138:141], v[214:217], v[76:79]
	v_mfma_f32_16x16x32_bf16 v[126:129], v[134:137], v[186:189], v[126:129]
	v_mfma_f32_16x16x32_bf16 v[122:125], v[142:145], v[186:189], v[122:125]
	v_mfma_f32_16x16x32_bf16 v[114:117], v[134:137], v[194:197], v[114:117]
	v_mfma_f32_16x16x32_bf16 v[110:113], v[142:145], v[194:197], v[110:113]
	v_mfma_f32_16x16x32_bf16 v[102:105], v[134:137], v[210:213], v[102:105]
	v_mfma_f32_16x16x32_bf16 v[92:95], v[142:145], v[210:213], v[92:95]
	v_mfma_f32_16x16x32_bf16 v[84:87], v[134:137], v[218:221], v[84:87]
	v_mfma_f32_16x16x32_bf16 v[76:79], v[142:145], v[218:221], v[76:79]
	s_setprio 0
	s_setprio 1
	v_mfma_f32_16x16x32_bf16 v[118:121], v[166:169], v[182:185], v[118:121]
	v_mfma_f32_16x16x32_bf16 v[106:109], v[174:177], v[182:185], v[106:109]
	v_mfma_f32_16x16x32_bf16 v[98:101], v[166:169], v[190:193], v[98:101]
	v_mfma_f32_16x16x32_bf16 v[88:91], v[174:177], v[190:193], v[88:91]
	v_mfma_f32_16x16x32_bf16 v[80:83], v[166:169], v[198:201], v[80:83]
	v_mfma_f32_16x16x32_bf16 v[72:75], v[174:177], v[198:201], v[72:75]
	v_mfma_f32_16x16x32_bf16 v[68:71], v[166:169], v[214:217], v[68:71]
	v_mfma_f32_16x16x32_bf16 v[64:67], v[174:177], v[214:217], v[64:67]
	v_mfma_f32_16x16x32_bf16 v[118:121], v[170:173], v[186:189], v[118:121]
	v_mfma_f32_16x16x32_bf16 v[106:109], v[178:181], v[186:189], v[106:109]
	v_mfma_f32_16x16x32_bf16 v[98:101], v[170:173], v[194:197], v[98:101]
	v_mfma_f32_16x16x32_bf16 v[88:91], v[178:181], v[194:197], v[88:91]
	v_mfma_f32_16x16x32_bf16 v[80:83], v[170:173], v[210:213], v[80:83]
	v_mfma_f32_16x16x32_bf16 v[72:75], v[178:181], v[210:213], v[72:75]
	v_mfma_f32_16x16x32_bf16 v[68:71], v[170:173], v[218:221], v[68:71]
	v_mfma_f32_16x16x32_bf16 v[64:67], v[178:181], v[218:221], v[64:67]
	s_setprio 0
	s_barrier
; #define PG8_STAGE(bufoff, gbase, voff) do { _Pragma("unroll") for (int _i = 0; _i < 2; ++_i) \
;         __builtin_amdgcn_global_load_lds((const unsigned*)((const char*)(gbase) + (voff)[_i]), (LAS unsigned*)(lds + (bufoff) + ldsw + _i * 8192), 16, 0, 0); } while (0)
; #define PG8_LDA(dst, b, h) do { _Pragma("unroll") for (int m = 0; m < 4; ++m) _Pragma("unroll") for (int k = 0; k < 2; ++k) dst[m][k] = *(const LAS bf16x8*)(lds + PG8_SA(b, h) + aoff + m * 2048 + k * 1024); } while (0)
; #define PG8_MMA(ai, bj, At, Bt) do { __builtin_amdgcn_s_setprio(1); _Pragma("unroll") for (int m = 0; m < 4; ++m) _Pragma("unroll") for (int n = 0; n < 2; ++n) _Pragma("unroll") for (int k = 0; k < 2; ++k) \
;         acc[ai][bj][m][n] = __builtin_amdgcn_mfma_f32_16x16x32_bf16(Bt[n][k], At[m][k], acc[ai][bj][m][n], 0, 0, 0); __builtin_amdgcn_s_setprio(0); } while (0)
; #define PG8_WAIT_V(n) asm volatile("s_waitcnt vmcnt(" #n ")" ::: "memory")
; #define PG8_WAIT_L(n) asm volatile("s_waitcnt lgkmcnt(" #n ")" ::: "memory")
; #define PG8_BAR __builtin_amdgcn_s_barrier()
; #define PG8_SCHED __builtin_amdgcn_sched_barrier(0)
; template <int K, int LDA, int LDB, int KGRP, bool APERM, class Epi>
; __device__ __forceinline__ void gemm_phase(LAS unsigned char* lds, const Gemm g, const StaticOrder& S, const Epi& E, const int tid) {
;     ...
;             PG8_LDA(At, 1, 1); PG8_STAGE(PG8_SB(1, 0), b3, voffB); PG8_STAGE(PG8_SB(1, 1), b3 + hstepB, voffB); PG8_STAGE(PG8_SA(1, 0), a3, voffA);
;             PG8_WAIT_V(8); PG8_WAIT_L(0); PG8_BAR; PG8_MMA(1, 0, At, B0); PG8_MMA(1, 1, At, B1); PG8_BAR; PG8_SCHED;
;         }
;         if (wr == 0) PG8_BAR;
	s_add_i32 s3, s3, s29
	v_lshl_add_u64 v[156:157], v[156:157], 0, s[38:39]
	s_mov_b32 m0, s3
	ds_read_b128 v[182:185], v164 offset:49152
	ds_read_b128 v[186:189], v164 offset:50176
	ds_read_b128 v[190:193], v164 offset:51200
	ds_read_b128 v[194:197], v164 offset:52224
	ds_read_b128 v[198:201], v164 offset:53248
	ds_read_b128 v[210:213], v164 offset:54272
	ds_read_b128 v[214:217], v164 offset:55296
	ds_read_b128 v[218:221], v164 offset:56320
	global_load_lds_dwordx4 v[156:157], off
	s_add_i32 m0, s3, 0x2000
	s_add_u32 s16, s16, 0x80080
	v_lshl_add_u64 v[156:157], v[222:223], 0, s[38:39]
	s_addc_u32 s17, s17, 0
	s_add_i32 s3, s53, s29
	global_load_lds_dwordx4 v[156:157], off
	v_lshl_add_u64 v[156:157], s[16:17], 0, v[96:97]
	s_mov_b32 m0, s3
	s_nop 0
	global_load_lds_dwordx4 v[156:157], off
	v_lshl_add_u64 v[156:157], s[16:17], 0, v[150:151]
	s_add_i32 m0, s3, 0x2000
	s_nop 0
	global_load_lds_dwordx4 v[156:157], off
	v_lshl_add_u64 v[156:157], v[224:225], 0, s[38:39]
	s_mov_b32 m0, s18
	s_nop 0
	global_load_lds_dwordx4 v[156:157], off
	v_lshl_add_u64 v[156:157], v[226:227], 0, s[38:39]
	s_mov_b32 m0, s23
	s_nop 0
	global_load_lds_dwordx4 v[156:157], off
	s_waitcnt vmcnt(8)
	s_waitcnt lgkmcnt(0)
	s_barrier
	s_setprio 1
	v_mfma_f32_16x16x32_bf16 v[60:63], v[130:133], v[182:185], v[60:63]
	v_mfma_f32_16x16x32_bf16 v[56:59], v[138:141], v[182:185], v[56:59]
	v_mfma_f32_16x16x32_bf16 v[52:55], v[130:133], v[190:193], v[52:55]
	v_mfma_f32_16x16x32_bf16 v[44:47], v[138:141], v[190:193], v[44:47]
	v_mfma_f32_16x16x32_bf16 v[36:39], v[130:133], v[198:201], v[36:39]
	v_mfma_f32_16x16x32_bf16 v[28:31], v[138:141], v[198:201], v[28:31]
	v_mfma_f32_16x16x32_bf16 v[20:23], v[130:133], v[214:217], v[20:23]
	v_mfma_f32_16x16x32_bf16 v[12:15], v[138:141], v[214:217], v[12:15]
	v_mfma_f32_16x16x32_bf16 v[60:63], v[134:137], v[186:189], v[60:63]
	v_mfma_f32_16x16x32_bf16 v[56:59], v[142:145], v[186:189], v[56:59]
	v_mfma_f32_16x16x32_bf16 v[52:55], v[134:137], v[194:197], v[52:55]
	v_mfma_f32_16x16x32_bf16 v[44:47], v[142:145], v[194:197], v[44:47]
	v_mfma_f32_16x16x32_bf16 v[36:39], v[134:137], v[210:213], v[36:39]
	v_mfma_f32_16x16x32_bf16 v[28:31], v[142:145], v[210:213], v[28:31]
	v_mfma_f32_16x16x32_bf16 v[20:23], v[134:137], v[218:221], v[20:23]
	v_mfma_f32_16x16x32_bf16 v[12:15], v[142:145], v[218:221], v[12:15]
	s_setprio 0
	s_setprio 1
	v_mfma_f32_16x16x32_bf16 v[48:51], v[166:169], v[182:185], v[48:51]
	v_mfma_f32_16x16x32_bf16 v[40:43], v[174:177], v[182:185], v[40:43]
	v_mfma_f32_16x16x32_bf16 v[32:35], v[166:169], v[190:193], v[32:35]
	v_mfma_f32_16x16x32_bf16 v[24:27], v[174:177], v[190:193], v[24:27]
	v_mfma_f32_16x16x32_bf16 v[16:19], v[166:169], v[198:201], v[16:19]
	v_mfma_f32_16x16x32_bf16 v[8:11], v[174:177], v[198:201], v[8:11]
	v_mfma_f32_16x16x32_bf16 v[4:7], v[166:169], v[214:217], v[4:7]
	v_mfma_f32_16x16x32_bf16 v[0:3], v[174:177], v[214:217], v[0:3]
	v_mfma_f32_16x16x32_bf16 v[48:51], v[170:173], v[186:189], v[48:51]
	v_mfma_f32_16x16x32_bf16 v[40:43], v[178:181], v[186:189], v[40:43]
	v_mfma_f32_16x16x32_bf16 v[32:35], v[170:173], v[194:197], v[32:35]
	v_mfma_f32_16x16x32_bf16 v[24:27], v[178:181], v[194:197], v[24:27]
	v_mfma_f32_16x16x32_bf16 v[16:19], v[170:173], v[210:213], v[16:19]
	v_mfma_f32_16x16x32_bf16 v[8:11], v[178:181], v[210:213], v[8:11]
	v_mfma_f32_16x16x32_bf16 v[4:7], v[170:173], v[218:221], v[4:7]
	v_mfma_f32_16x16x32_bf16 v[0:3], v[178:181], v[218:221], v[0:3]
	s_setprio 0
	s_barrier
	s_add_i32 s51, s51, 2
	s_add_u32 s8, s8, 0x100
	s_addc_u32 s9, s9, 0
	s_add_u32 s48, s48, 0x100
	s_addc_u32 s50, s50, 0
	s_cmp_gt_u32 s51, 29
	s_cbranch_scc0 .LBB0_391
	s_and_b64 vcc, exec, s[34:35]
	s_cbranch_vccz .LBB0_394
	s_barrier

; #define PG8_STAGE(bufoff, gbase, voff) do { _Pragma("unroll") for (int _i = 0; _i < 2; ++_i) \
;         __builtin_amdgcn_global_load_lds((const unsigned*)((const char*)(gbase) + (voff)[_i]), (LAS unsigned*)(lds + (bufoff) + ldsw + _i * 8192), 16, 0, 0); } while (0)
; #define PG8_LDA(dst, b, h) do { _Pragma("unroll") for (int m = 0; m < 4; ++m) _Pragma("unroll") for (int k = 0; k < 2; ++k) dst[m][k] = *(const LAS bf16x8*)(lds + PG8_SA(b, h) + aoff + m * 2048 + k * 1024); } while (0)
; #define PG8_LDB(dst, b, h) do { _Pragma("unroll") for (int n = 0; n < 2; ++n) _Pragma("unroll") for (int k = 0; k < 2; ++k) dst[n][k] = *(const LAS bf16x8*)(lds + PG8_SB(b, h) + boff + n * 2048 + k * 1024); } while (0)
; #define PG8_MMA(ai, bj, At, Bt) do { __builtin_amdgcn_s_setprio(1); _Pragma("unroll") for (int m = 0; m < 4; ++m) _Pragma("unroll") for (int n = 0; n < 2; ++n) _Pragma("unroll") for (int k = 0; k < 2; ++k) \
;         acc[ai][bj][m][n] = __builtin_amdgcn_mfma_f32_16x16x32_bf16(Bt[n][k], At[m][k], acc[ai][bj][m][n], 0, 0, 0); __builtin_amdgcn_s_setprio(0); } while (0)
; #define PG8_WAIT_V(n) asm volatile("s_waitcnt vmcnt(" #n ")" ::: "memory")
; #define PG8_WAIT_L(n) asm volatile("s_waitcnt lgkmcnt(" #n ")" ::: "memory")
; #define PG8_BAR __builtin_amdgcn_s_barrier()
; template <int K, int LDA, int LDB, int KGRP, bool APERM, class Epi>
; __device__ __forceinline__ void gemm_phase(LAS unsigned char* lds, const Gemm g, const StaticOrder& S, const Epi& E, const int tid) {
;     ...
;         for (int t = 0; t < nt; t += 2) {
;             const bool last = (t == nt - 2);
;             const char* a1 = cA + (size_t)(t + 1) * kstep;
;             const char* a2 = last ? nA : cA + (size_t)(t + 2) * kstep; const char* b2 = last ? nB : cB + (size_t)(t + 2) * kstep;
;             const char* a3 = a2 + kstep; const char* b3 = b2 + kstep;
;             PG8_LDB(B0, 0, 0); PG8_LDB(B1, 0, 1); PG8_SCHED; PG8_LDA(At, 0, 0); PG8_STAGE(PG8_SA(1, 1), a1 + hstepA, voffA);
;             PG8_WAIT_V(8); PG8_WAIT_L(0); PG8_BAR; PG8_MMA(0, 0, At, B0); PG8_MMA(0, 1, At, B1); PG8_BAR; PG8_SCHED;
;             PG8_LDA(At, 0, 1); PG8_STAGE(PG8_SB(0, 0), b2, voffB); PG8_STAGE(PG8_SB(0, 1), b2 + hstepB, voffB); PG8_STAGE(PG8_SA(0, 0), a2, voffA);
;             PG8_WAIT_V(8); PG8_WAIT_L(0); PG8_BAR; PG8_MMA(1, 0, At, B0); PG8_MMA(1, 1, At, B1); PG8_BAR; PG8_SCHED;
.LBB0_566:
	s_add_u32 s50, s16, 0xfff80080
	s_addc_u32 s51, s17, -1
	s_add_i32 s58, 0, 0x10000
	s_cmp_eq_u32 s48, 28
	s_cselect_b32 s57, s3, s51
	s_cselect_b32 s56, s9, s50
	s_cselect_b32 s55, s18, s47
	s_cselect_b32 s54, s45, s46
	s_add_i32 s59, 0, 0x14000
	v_add_u32_e32 v156, s58, v149
	v_add_u32_e32 v172, s59, v149
	ds_read_b128 v[140:143], v156
	ds_read_b128 v[144:147], v156 offset:1024
	ds_read_b128 v[152:155], v156 offset:2048
	ds_read_b128 v[156:159], v156 offset:3072
	ds_read_b128 v[160:163], v172
	ds_read_b128 v[164:167], v172 offset:1024
	ds_read_b128 v[168:171], v172 offset:2048
	ds_read_b128 v[172:175], v172 offset:3072
	v_lshl_add_u64 v[200:201], s[16:17], 0, v[136:137]
	s_add_i32 m0, s29, 0xc000
	ds_read_b128 v[176:179], v151
	ds_read_b128 v[180:183], v151 offset:1024
	ds_read_b128 v[184:187], v151 offset:2048
	ds_read_b128 v[188:191], v151 offset:3072
	ds_read_b128 v[192:195], v151 offset:4096
	ds_read_b128 v[196:199], v151 offset:5120
	ds_read_b128 v[210:213], v151 offset:6144
	ds_read_b128 v[214:217], v151 offset:7168
	global_load_lds_dwordx4 v[200:201], off
	v_lshl_add_u64 v[200:201], s[16:17], 0, v[138:139]
	s_add_i32 m0, s29, 0xe000
	s_nop 0
	global_load_lds_dwordx4 v[200:201], off
	s_waitcnt vmcnt(8)
	s_waitcnt lgkmcnt(0)
	s_barrier
	s_setprio 1
	v_mfma_f32_16x16x32_bf16 v[114:117], v[140:143], v[176:179], v[114:117]
	v_mfma_f32_16x16x32_bf16 v[118:121], v[152:155], v[176:179], v[118:121]
	v_mfma_f32_16x16x32_bf16 v[98:101], v[140:143], v[184:187], v[98:101]
	v_mfma_f32_16x16x32_bf16 v[102:105], v[152:155], v[184:187], v[102:105]
	v_mfma_f32_16x16x32_bf16 v[80:83], v[140:143], v[192:195], v[80:83]
	v_mfma_f32_16x16x32_bf16 v[84:87], v[152:155], v[192:195], v[84:87]
	v_mfma_f32_16x16x32_bf16 v[48:51], v[140:143], v[210:213], v[48:51]
	v_mfma_f32_16x16x32_bf16 v[52:55], v[152:155], v[210:213], v[52:55]
	v_mfma_f32_16x16x32_bf16 v[114:117], v[144:147], v[180:183], v[114:117]
	v_mfma_f32_16x16x32_bf16 v[118:121], v[156:159], v[180:183], v[118:121]
	v_mfma_f32_16x16x32_bf16 v[98:101], v[144:147], v[188:191], v[98:101]
	v_mfma_f32_16x16x32_bf16 v[102:105], v[156:159], v[188:191], v[102:105]
	v_mfma_f32_16x16x32_bf16 v[80:83], v[144:147], v[196:199], v[80:83]
	v_mfma_f32_16x16x32_bf16 v[84:87], v[156:159], v[196:199], v[84:87]
	v_mfma_f32_16x16x32_bf16 v[48:51], v[144:147], v[214:217], v[48:51]
	v_mfma_f32_16x16x32_bf16 v[52:55], v[156:159], v[214:217], v[52:55]
	s_setprio 0
	s_setprio 1
	v_mfma_f32_16x16x32_bf16 v[122:125], v[160:163], v[176:179], v[122:125]
	v_mfma_f32_16x16x32_bf16 v[126:129], v[168:171], v[176:179], v[126:129]
	v_mfma_f32_16x16x32_bf16 v[106:109], v[160:163], v[184:187], v[106:109]
	v_mfma_f32_16x16x32_bf16 v[110:113], v[168:171], v[184:187], v[110:113]
	v_mfma_f32_16x16x32_bf16 v[88:91], v[160:163], v[192:195], v[88:91]
	v_mfma_f32_16x16x32_bf16 v[92:95], v[168:171], v[192:195], v[92:95]
	v_mfma_f32_16x16x32_bf16 v[68:71], v[160:163], v[210:213], v[68:71]
	v_mfma_f32_16x16x32_bf16 v[76:79], v[168:171], v[210:213], v[76:79]
	v_mfma_f32_16x16x32_bf16 v[122:125], v[164:167], v[180:183], v[122:125]
	v_mfma_f32_16x16x32_bf16 v[126:129], v[172:175], v[180:183], v[126:129]
	v_mfma_f32_16x16x32_bf16 v[106:109], v[164:167], v[188:191], v[106:109]
	v_mfma_f32_16x16x32_bf16 v[110:113], v[172:175], v[188:191], v[110:113]
	v_mfma_f32_16x16x32_bf16 v[88:91], v[164:167], v[196:199], v[88:91]
	v_mfma_f32_16x16x32_bf16 v[92:95], v[172:175], v[196:199], v[92:95]
	v_mfma_f32_16x16x32_bf16 v[68:71], v[164:167], v[214:217], v[68:71]
	v_mfma_f32_16x16x32_bf16 v[76:79], v[172:175], v[214:217], v[76:79]
	s_setprio 0
	s_barrier
	s_add_i32 s50, s58, s28
	v_lshl_add_u64 v[200:201], s[54:55], 0, v[96:97]
	s_mov_b32 m0, s50
	ds_read_b128 v[176:179], v151 offset:16384
	ds_read_b128 v[180:183], v151 offset:17408
	ds_read_b128 v[184:187], v151 offset:18432
	ds_read_b128 v[188:191], v151 offset:19456
	ds_read_b128 v[192:195], v151 offset:20480
	ds_read_b128 v[196:199], v151 offset:21504
	ds_read_b128 v[210:213], v151 offset:22528
	ds_read_b128 v[214:217], v151 offset:23552
	global_load_lds_dwordx4 v[200:201], off
	s_add_i32 m0, s50, 0x2000
	s_add_u32 s50, s54, 0x80000
	v_lshl_add_u64 v[218:219], s[54:55], 0, v[134:135]
	s_addc_u32 s51, s55, 0
	s_add_i32 s58, s59, s28
	global_load_lds_dwordx4 v[218:219], off
	v_lshl_add_u64 v[220:221], s[50:51], 0, v[96:97]
	s_mov_b32 m0, s58
	v_lshl_add_u64 v[222:223], s[56:57], 0, v[132:133]
	global_load_lds_dwordx4 v[220:221], off
	v_lshl_add_u64 v[220:221], s[50:51], 0, v[134:135]
	s_add_i32 m0, s58, 0x2000
	s_nop 0
	global_load_lds_dwordx4 v[220:221], off
	v_lshl_add_u64 v[220:221], s[56:57], 0, v[130:131]
	s_mov_b32 m0, s29
	s_nop 0
	global_load_lds_dwordx4 v[220:221], off
	s_mov_b32 m0, s30
	s_nop 0
	global_load_lds_dwordx4 v[222:223], off
	s_waitcnt vmcnt(8)
	s_waitcnt lgkmcnt(0)
	s_barrier
; #define PG8_STAGE(bufoff, gbase, voff) do { _Pragma("unroll") for (int _i = 0; _i < 2; ++_i) \
;         __builtin_amdgcn_global_load_lds((const unsigned*)((const char*)(gbase) + (voff)[_i]), (LAS unsigned*)(lds + (bufoff) + ldsw + _i * 8192), 16, 0, 0); } while (0)
; #define PG8_LDA(dst, b, h) do { _Pragma("unroll") for (int m = 0; m < 4; ++m) _Pragma("unroll") for (int k = 0; k < 2; ++k) dst[m][k] = *(const LAS bf16x8*)(lds + PG8_SA(b, h) + aoff + m * 2048 + k * 1024); } while (0)
; #define PG8_LDB(dst, b, h) do { _Pragma("unroll") for (int n = 0; n < 2; ++n) _Pragma("unroll") for (int k = 0; k < 2; ++k) dst[n][k] = *(const LAS bf16x8*)(lds + PG8_SB(b, h) + boff + n * 2048 + k * 1024); } while (0)
; #define PG8_MMA(ai, bj, At, Bt) do { __builtin_amdgcn_s_setprio(1); _Pragma("unroll") for (int m = 0; m < 4; ++m) _Pragma("unroll") for (int n = 0; n < 2; ++n) _Pragma("unroll") for (int k = 0; k < 2; ++k) \
;         acc[ai][bj][m][n] = __builtin_amdgcn_mfma_f32_16x16x32_bf16(Bt[n][k], At[m][k], acc[ai][bj][m][n], 0, 0, 0); __builtin_amdgcn_s_setprio(0); } while (0)
; #define PG8_WAIT_V(n) asm volatile("s_waitcnt vmcnt(" #n ")" ::: "memory")
; #define PG8_WAIT_L(n) asm volatile("s_waitcnt lgkmcnt(" #n ")" ::: "memory")
; #define PG8_BAR __builtin_amdgcn_s_barrier()
; #define PG8_SCHED __builtin_amdgcn_sched_barrier(0)
; template <int K, int LDA, int LDB, int KGRP, bool APERM, class Epi>
; __device__ __forceinline__ void gemm_phase(LAS unsigned char* lds, const Gemm g, const StaticOrder& S, const Epi& E, const int tid) {
;     ...
;             PG8_WAIT_V(8); PG8_WAIT_L(0); PG8_BAR; PG8_MMA(1, 0, At, B0); PG8_MMA(1, 1, At, B1); PG8_BAR; PG8_SCHED;
;             PG8_LDB(B0, 1, 0); PG8_LDB(B1, 1, 1); PG8_SCHED; PG8_LDA(At, 1, 0); PG8_STAGE(PG8_SA(0, 1), a2 + hstepA, voffA);
;             PG8_WAIT_V(8); PG8_WAIT_L(0); PG8_BAR; PG8_MMA(0, 0, At, B0); PG8_MMA(0, 1, At, B1); PG8_BAR; PG8_SCHED;
	s_setprio 1
	v_mfma_f32_16x16x32_bf16 v[36:39], v[140:143], v[176:179], v[36:39]
	v_mfma_f32_16x16x32_bf16 v[44:47], v[152:155], v[176:179], v[44:47]
	v_mfma_f32_16x16x32_bf16 v[12:15], v[140:143], v[184:187], v[12:15]
	v_mfma_f32_16x16x32_bf16 v[20:23], v[152:155], v[184:187], v[20:23]
	v_mfma_f32_16x16x32_bf16 v[24:27], v[140:143], v[192:195], v[24:27]
	v_mfma_f32_16x16x32_bf16 v[28:31], v[152:155], v[192:195], v[28:31]
	v_mfma_f32_16x16x32_bf16 v[0:3], v[140:143], v[210:213], v[0:3]
	v_mfma_f32_16x16x32_bf16 v[4:7], v[152:155], v[210:213], v[4:7]
	v_mfma_f32_16x16x32_bf16 v[36:39], v[144:147], v[180:183], v[36:39]
	v_mfma_f32_16x16x32_bf16 v[44:47], v[156:159], v[180:183], v[44:47]
	v_mfma_f32_16x16x32_bf16 v[12:15], v[144:147], v[188:191], v[12:15]
	v_mfma_f32_16x16x32_bf16 v[20:23], v[156:159], v[188:191], v[20:23]
	v_mfma_f32_16x16x32_bf16 v[24:27], v[144:147], v[196:199], v[24:27]
	v_mfma_f32_16x16x32_bf16 v[28:31], v[156:159], v[196:199], v[28:31]
	v_mfma_f32_16x16x32_bf16 v[0:3], v[144:147], v[214:217], v[0:3]
	v_mfma_f32_16x16x32_bf16 v[4:7], v[156:159], v[214:217], v[4:7]
	s_setprio 0
	s_setprio 1
	v_mfma_f32_16x16x32_bf16 v[56:59], v[160:163], v[176:179], v[56:59]
	v_mfma_f32_16x16x32_bf16 v[60:63], v[168:171], v[176:179], v[60:63]
	v_mfma_f32_16x16x32_bf16 v[64:67], v[160:163], v[184:187], v[64:67]
	v_mfma_f32_16x16x32_bf16 v[72:75], v[168:171], v[184:187], v[72:75]
	v_mfma_f32_16x16x32_bf16 v[32:35], v[160:163], v[192:195], v[32:35]
	v_mfma_f32_16x16x32_bf16 v[40:43], v[168:171], v[192:195], v[40:43]
	v_mfma_f32_16x16x32_bf16 v[8:11], v[160:163], v[210:213], v[8:11]
	v_mfma_f32_16x16x32_bf16 v[16:19], v[168:171], v[210:213], v[16:19]
	v_mfma_f32_16x16x32_bf16 v[56:59], v[164:167], v[180:183], v[56:59]
	v_mfma_f32_16x16x32_bf16 v[60:63], v[172:175], v[180:183], v[60:63]
	v_mfma_f32_16x16x32_bf16 v[64:67], v[164:167], v[188:191], v[64:67]
	v_mfma_f32_16x16x32_bf16 v[72:75], v[172:175], v[188:191], v[72:75]
	v_mfma_f32_16x16x32_bf16 v[32:35], v[164:167], v[196:199], v[32:35]
	v_mfma_f32_16x16x32_bf16 v[40:43], v[172:175], v[196:199], v[40:43]
	v_mfma_f32_16x16x32_bf16 v[8:11], v[164:167], v[214:217], v[8:11]
	v_mfma_f32_16x16x32_bf16 v[16:19], v[172:175], v[214:217], v[16:19]
	s_setprio 0
	s_barrier
	s_add_i32 s58, 0, 0x18000
	s_add_i32 s59, 0, 0x1c000
	v_add_u32_e32 v156, s58, v149
	v_add_u32_e32 v172, s59, v149
	ds_read_b128 v[140:143], v156
	ds_read_b128 v[144:147], v156 offset:1024
	ds_read_b128 v[152:155], v156 offset:2048
	ds_read_b128 v[156:159], v156 offset:3072
	ds_read_b128 v[160:163], v172
	ds_read_b128 v[164:167], v172 offset:1024
	ds_read_b128 v[168:171], v172 offset:2048
	ds_read_b128 v[172:175], v172 offset:3072
	s_add_u32 s50, s56, 0x80000
	s_addc_u32 s51, s57, 0
	s_mov_b32 m0, s31
	v_lshl_add_u64 v[224:225], s[50:51], 0, v[130:131]
	ds_read_b128 v[176:179], v151 offset:32768
	ds_read_b128 v[180:183], v151 offset:33792
	ds_read_b128 v[184:187], v151 offset:34816
	ds_read_b128 v[188:191], v151 offset:35840
	ds_read_b128 v[192:195], v151 offset:36864
	ds_read_b128 v[196:199], v151 offset:37888
	ds_read_b128 v[210:213], v151 offset:38912
	ds_read_b128 v[214:217], v151 offset:39936
	global_load_lds_dwordx4 v[224:225], off
	v_lshl_add_u64 v[224:225], s[50:51], 0, v[132:133]
	s_mov_b32 m0, s37
	s_nop 0
	global_load_lds_dwordx4 v[224:225], off
	s_waitcnt vmcnt(8)
	s_waitcnt lgkmcnt(0)
	s_barrier
	s_setprio 1
	v_mfma_f32_16x16x32_bf16 v[114:117], v[140:143], v[176:179], v[114:117]
	v_mfma_f32_16x16x32_bf16 v[118:121], v[152:155], v[176:179], v[118:121]
	v_mfma_f32_16x16x32_bf16 v[98:101], v[140:143], v[184:187], v[98:101]
	v_mfma_f32_16x16x32_bf16 v[102:105], v[152:155], v[184:187], v[102:105]
	v_mfma_f32_16x16x32_bf16 v[80:83], v[140:143], v[192:195], v[80:83]
	v_mfma_f32_16x16x32_bf16 v[84:87], v[152:155], v[192:195], v[84:87]
	v_mfma_f32_16x16x32_bf16 v[48:51], v[140:143], v[210:213], v[48:51]
	v_mfma_f32_16x16x32_bf16 v[52:55], v[152:155], v[210:213], v[52:55]
	v_mfma_f32_16x16x32_bf16 v[114:117], v[144:147], v[180:183], v[114:117]
	v_mfma_f32_16x16x32_bf16 v[118:121], v[156:159], v[180:183], v[118:121]
	v_mfma_f32_16x16x32_bf16 v[98:101], v[144:147], v[188:191], v[98:101]
	v_mfma_f32_16x16x32_bf16 v[102:105], v[156:159], v[188:191], v[102:105]
	v_mfma_f32_16x16x32_bf16 v[80:83], v[144:147], v[196:199], v[80:83]
	v_mfma_f32_16x16x32_bf16 v[84:87], v[156:159], v[196:199], v[84:87]
	v_mfma_f32_16x16x32_bf16 v[48:51], v[144:147], v[214:217], v[48:51]
	v_mfma_f32_16x16x32_bf16 v[52:55], v[156:159], v[214:217], v[52:55]
	s_setprio 0
	s_setprio 1
	v_mfma_f32_16x16x32_bf16 v[122:125], v[160:163], v[176:179], v[122:125]
	v_mfma_f32_16x16x32_bf16 v[126:129], v[168:171], v[176:179], v[126:129]
	v_mfma_f32_16x16x32_bf16 v[106:109], v[160:163], v[184:187], v[106:109]
	v_mfma_f32_16x16x32_bf16 v[110:113], v[168:171], v[184:187], v[110:113]
	v_mfma_f32_16x16x32_bf16 v[88:91], v[160:163], v[192:195], v[88:91]
	v_mfma_f32_16x16x32_bf16 v[92:95], v[168:171], v[192:195], v[92:95]
	v_mfma_f32_16x16x32_bf16 v[68:71], v[160:163], v[210:213], v[68:71]
	v_mfma_f32_16x16x32_bf16 v[76:79], v[168:171], v[210:213], v[76:79]
	v_mfma_f32_16x16x32_bf16 v[122:125], v[164:167], v[180:183], v[122:125]
	v_mfma_f32_16x16x32_bf16 v[126:129], v[172:175], v[180:183], v[126:129]
	v_mfma_f32_16x16x32_bf16 v[106:109], v[164:167], v[188:191], v[106:109]
	v_mfma_f32_16x16x32_bf16 v[110:113], v[172:175], v[188:191], v[110:113]
	v_mfma_f32_16x16x32_bf16 v[88:91], v[164:167], v[196:199], v[88:91]
	v_mfma_f32_16x16x32_bf16 v[92:95], v[172:175], v[196:199], v[92:95]
	v_mfma_f32_16x16x32_bf16 v[68:71], v[164:167], v[214:217], v[68:71]
	v_mfma_f32_16x16x32_bf16 v[76:79], v[172:175], v[214:217], v[76:79]
	s_setprio 0
	s_barrier
; #define PG8_STAGE(bufoff, gbase, voff) do { _Pragma("unroll") for (int _i = 0; _i < 2; ++_i) \
;         __builtin_amdgcn_global_load_lds((const unsigned*)((const char*)(gbase) + (voff)[_i]), (LAS unsigned*)(lds + (bufoff) + ldsw + _i * 8192), 16, 0, 0); } while (0)
; #define PG8_LDA(dst, b, h) do { _Pragma("unroll") for (int m = 0; m < 4; ++m) _Pragma("unroll") for (int k = 0; k < 2; ++k) dst[m][k] = *(const LAS bf16x8*)(lds + PG8_SA(b, h) + aoff + m * 2048 + k * 1024); } while (0)
; #define PG8_MMA(ai, bj, At, Bt) do { __builtin_amdgcn_s_setprio(1); _Pragma("unroll") for (int m = 0; m < 4; ++m) _Pragma("unroll") for (int n = 0; n < 2; ++n) _Pragma("unroll") for (int k = 0; k < 2; ++k) \
;         acc[ai][bj][m][n] = __builtin_amdgcn_mfma_f32_16x16x32_bf16(Bt[n][k], At[m][k], acc[ai][bj][m][n], 0, 0, 0); __builtin_amdgcn_s_setprio(0); } while (0)
; #define PG8_WAIT_V(n) asm volatile("s_waitcnt vmcnt(" #n ")" ::: "memory")
; #define PG8_WAIT_L(n) asm volatile("s_waitcnt lgkmcnt(" #n ")" ::: "memory")
; #define PG8_BAR __builtin_amdgcn_s_barrier()
; #define PG8_SCHED __builtin_amdgcn_sched_barrier(0)
; template <int K, int LDA, int LDB, int KGRP, bool APERM, class Epi>
; __device__ __forceinline__ void gemm_phase(LAS unsigned char* lds, const Gemm g, const StaticOrder& S, const Epi& E, const int tid) {
;     ...
;             PG8_LDA(At, 1, 1); PG8_STAGE(PG8_SB(1, 0), b3, voffB); PG8_STAGE(PG8_SB(1, 1), b3 + hstepB, voffB); PG8_STAGE(PG8_SA(1, 0), a3, voffA);
;             PG8_WAIT_V(8); PG8_WAIT_L(0); PG8_BAR; PG8_MMA(1, 0, At, B0); PG8_MMA(1, 1, At, B1); PG8_BAR; PG8_SCHED;
;         }
;         if (wr == 0) PG8_BAR;
	s_add_i32 s50, s58, s28
	v_lshl_add_u64 v[200:201], v[200:201], 0, s[38:39]
	s_mov_b32 m0, s50
	ds_read_b128 v[176:179], v151 offset:49152
	ds_read_b128 v[180:183], v151 offset:50176
	ds_read_b128 v[184:187], v151 offset:51200
	ds_read_b128 v[188:191], v151 offset:52224
	ds_read_b128 v[192:195], v151 offset:53248
	ds_read_b128 v[196:199], v151 offset:54272
	ds_read_b128 v[210:213], v151 offset:55296
	ds_read_b128 v[214:217], v151 offset:56320
	global_load_lds_dwordx4 v[200:201], off
	s_add_i32 m0, s50, 0x2000
	s_add_u32 s50, s54, 0x80080
	v_lshl_add_u64 v[200:201], v[218:219], 0, s[38:39]
	s_addc_u32 s51, s55, 0
	s_add_i32 s54, s59, s28
	global_load_lds_dwordx4 v[200:201], off
	v_lshl_add_u64 v[200:201], s[50:51], 0, v[96:97]
	s_mov_b32 m0, s54
	s_nop 0
	global_load_lds_dwordx4 v[200:201], off
	v_lshl_add_u64 v[200:201], s[50:51], 0, v[134:135]
	s_add_i32 m0, s54, 0x2000
	s_nop 0
	global_load_lds_dwordx4 v[200:201], off
	v_lshl_add_u64 v[200:201], v[220:221], 0, s[38:39]
	s_mov_b32 m0, s41
	s_nop 0
	global_load_lds_dwordx4 v[200:201], off
	v_lshl_add_u64 v[200:201], v[222:223], 0, s[38:39]
	s_mov_b32 m0, s42
	s_nop 0
	global_load_lds_dwordx4 v[200:201], off
	s_waitcnt vmcnt(8)
	s_waitcnt lgkmcnt(0)
	s_barrier
	s_setprio 1
	v_mfma_f32_16x16x32_bf16 v[36:39], v[140:143], v[176:179], v[36:39]
	v_mfma_f32_16x16x32_bf16 v[44:47], v[152:155], v[176:179], v[44:47]
	v_mfma_f32_16x16x32_bf16 v[12:15], v[140:143], v[184:187], v[12:15]
	v_mfma_f32_16x16x32_bf16 v[20:23], v[152:155], v[184:187], v[20:23]
	v_mfma_f32_16x16x32_bf16 v[24:27], v[140:143], v[192:195], v[24:27]
	v_mfma_f32_16x16x32_bf16 v[28:31], v[152:155], v[192:195], v[28:31]
	v_mfma_f32_16x16x32_bf16 v[0:3], v[140:143], v[210:213], v[0:3]
	v_mfma_f32_16x16x32_bf16 v[4:7], v[152:155], v[210:213], v[4:7]
	v_mfma_f32_16x16x32_bf16 v[36:39], v[144:147], v[180:183], v[36:39]
	v_mfma_f32_16x16x32_bf16 v[44:47], v[156:159], v[180:183], v[44:47]
	v_mfma_f32_16x16x32_bf16 v[12:15], v[144:147], v[188:191], v[12:15]
	v_mfma_f32_16x16x32_bf16 v[20:23], v[156:159], v[188:191], v[20:23]
	v_mfma_f32_16x16x32_bf16 v[24:27], v[144:147], v[196:199], v[24:27]
	v_mfma_f32_16x16x32_bf16 v[28:31], v[156:159], v[196:199], v[28:31]
	v_mfma_f32_16x16x32_bf16 v[0:3], v[144:147], v[214:217], v[0:3]
	v_mfma_f32_16x16x32_bf16 v[4:7], v[156:159], v[214:217], v[4:7]
	s_setprio 0
	s_setprio 1
	v_mfma_f32_16x16x32_bf16 v[56:59], v[160:163], v[176:179], v[56:59]
	v_mfma_f32_16x16x32_bf16 v[60:63], v[168:171], v[176:179], v[60:63]
	v_mfma_f32_16x16x32_bf16 v[64:67], v[160:163], v[184:187], v[64:67]
	v_mfma_f32_16x16x32_bf16 v[72:75], v[168:171], v[184:187], v[72:75]
	v_mfma_f32_16x16x32_bf16 v[32:35], v[160:163], v[192:195], v[32:35]
	v_mfma_f32_16x16x32_bf16 v[40:43], v[168:171], v[192:195], v[40:43]
	v_mfma_f32_16x16x32_bf16 v[8:11], v[160:163], v[210:213], v[8:11]
	v_mfma_f32_16x16x32_bf16 v[16:19], v[168:171], v[210:213], v[16:19]
	v_mfma_f32_16x16x32_bf16 v[56:59], v[164:167], v[180:183], v[56:59]
	v_mfma_f32_16x16x32_bf16 v[60:63], v[172:175], v[180:183], v[60:63]
	v_mfma_f32_16x16x32_bf16 v[64:67], v[164:167], v[188:191], v[64:67]
	v_mfma_f32_16x16x32_bf16 v[72:75], v[172:175], v[188:191], v[72:75]
	v_mfma_f32_16x16x32_bf16 v[32:35], v[164:167], v[196:199], v[32:35]
	v_mfma_f32_16x16x32_bf16 v[40:43], v[172:175], v[196:199], v[40:43]
	v_mfma_f32_16x16x32_bf16 v[8:11], v[164:167], v[214:217], v[8:11]
	v_mfma_f32_16x16x32_bf16 v[16:19], v[172:175], v[214:217], v[16:19]
	s_setprio 0
	s_barrier
	s_add_i32 s48, s48, 2
	s_add_u32 s16, s16, 0x100
	s_addc_u32 s17, s17, 0
	s_add_u32 s46, s46, 0x100
	s_addc_u32 s47, s47, 0
	s_cmp_gt_u32 s48, 29
	s_cbranch_scc0 .LBB0_566
	s_and_b64 vcc, exec, s[34:35]
	s_cbranch_vccz .LBB0_569
	s_barrier

; #define PG8_STAGE(bufoff, gbase, voff) do { _Pragma("unroll") for (int _i = 0; _i < 2; ++_i) \
;         __builtin_amdgcn_global_load_lds((const unsigned*)((const char*)(gbase) + (voff)[_i]), (LAS unsigned*)(lds + (bufoff) + ldsw + _i * 8192), 16, 0, 0); } while (0)
; #define PG8_LDA(dst, b, h) do { _Pragma("unroll") for (int m = 0; m < 4; ++m) _Pragma("unroll") for (int k = 0; k < 2; ++k) dst[m][k] = *(const LAS bf16x8*)(lds + PG8_SA(b, h) + aoff + m * 2048 + k * 1024); } while (0)
; #define PG8_LDB(dst, b, h) do { _Pragma("unroll") for (int n = 0; n < 2; ++n) _Pragma("unroll") for (int k = 0; k < 2; ++k) dst[n][k] = *(const LAS bf16x8*)(lds + PG8_SB(b, h) + boff + n * 2048 + k * 1024); } while (0)
; #define PG8_MMA(ai, bj, At, Bt) do { __builtin_amdgcn_s_setprio(1); _Pragma("unroll") for (int m = 0; m < 4; ++m) _Pragma("unroll") for (int n = 0; n < 2; ++n) _Pragma("unroll") for (int k = 0; k < 2; ++k) \
;         acc[ai][bj][m][n] = __builtin_amdgcn_mfma_f32_16x16x32_bf16(Bt[n][k], At[m][k], acc[ai][bj][m][n], 0, 0, 0); __builtin_amdgcn_s_setprio(0); } while (0)
; #define PG8_WAIT_V(n) asm volatile("s_waitcnt vmcnt(" #n ")" ::: "memory")
; #define PG8_WAIT_L(n) asm volatile("s_waitcnt lgkmcnt(" #n ")" ::: "memory")
; #define PG8_BAR __builtin_amdgcn_s_barrier()
; #define PG8_SCHED __builtin_amdgcn_sched_barrier(0)
; template <int K, int LDA, int LDB, int KGRP, bool APERM, class Epi>
; __device__ __forceinline__ void gemm_phase(LAS unsigned char* lds, const Gemm g, const StaticOrder& S, const Epi& E, const int tid) {
;     ...
;             const bool last = (t == nt - 2);
;             const char* a1 = cA + (size_t)(t + 1) * kstep;
;             const char* a2 = last ? nA : cA + (size_t)(t + 2) * kstep; const char* b2 = last ? nB : cB + (size_t)(t + 2) * kstep;
;             const char* a3 = a2 + kstep; const char* b3 = b2 + kstep;
;             PG8_LDB(B0, 0, 0); PG8_LDB(B1, 0, 1); PG8_SCHED; PG8_LDA(At, 0, 0); PG8_STAGE(PG8_SA(1, 1), a1 + hstepA, voffA);
;             PG8_WAIT_V(8); PG8_WAIT_L(0); PG8_BAR; PG8_MMA(0, 0, At, B0); PG8_MMA(0, 1, At, B1); PG8_BAR; PG8_SCHED;
;             PG8_LDA(At, 0, 1); PG8_STAGE(PG8_SB(0, 0), b2, voffB); PG8_STAGE(PG8_SB(0, 1), b2 + hstepB, voffB); PG8_STAGE(PG8_SA(0, 0), a2, voffA);
;             PG8_WAIT_V(8); PG8_WAIT_L(0); PG8_BAR; PG8_MMA(1, 0, At, B0); PG8_MMA(1, 1, At, B1); PG8_BAR; PG8_SCHED;
.LBB0_767:
	s_add_u32 s3, s8, 0xfff80080
	s_addc_u32 s16, s9, -1
	s_add_i32 s45, 0, 0x10000
	s_cmp_eq_u32 s44, 4
	s_cselect_b32 s55, s75, s16
	s_cselect_b32 s54, s74, s3
	s_cselect_b32 s17, s11, s43
	s_cselect_b32 s16, s18, s42
	s_add_i32 s3, 0, 0x14000
	v_add_u32_e32 v142, s45, v186
	v_add_u32_e32 v168, s3, v186
	ds_read_b128 v[122:125], v142
	ds_read_b128 v[134:137], v142 offset:1024
	ds_read_b128 v[138:141], v142 offset:2048
	ds_read_b128 v[142:145], v142 offset:3072
	ds_read_b128 v[146:149], v168
	ds_read_b128 v[150:153], v168 offset:1024
	ds_read_b128 v[164:167], v168 offset:2048
	ds_read_b128 v[168:171], v168 offset:3072
	v_lshl_add_u64 v[218:219], s[8:9], 0, v[160:161]
	s_add_i32 m0, s23, 0xc000
	ds_read_b128 v[172:175], v188
	ds_read_b128 v[176:179], v188 offset:1024
	ds_read_b128 v[180:183], v188 offset:2048
	ds_read_b128 v[190:193], v188 offset:3072
	ds_read_b128 v[194:197], v188 offset:4096
	ds_read_b128 v[198:201], v188 offset:5120
	ds_read_b128 v[210:213], v188 offset:6144
	ds_read_b128 v[214:217], v188 offset:7168
	global_load_lds_dwordx4 v[218:219], off
	v_lshl_add_u64 v[218:219], s[8:9], 0, v[162:163]
	s_add_i32 m0, s23, 0xe000
	s_nop 0
	global_load_lds_dwordx4 v[218:219], off
	s_waitcnt vmcnt(8)
	s_waitcnt lgkmcnt(0)
	s_barrier
	s_setprio 1
	v_mfma_f32_16x16x32_bf16 v[130:133], v[122:125], v[172:175], v[130:133]
	v_mfma_f32_16x16x32_bf16 v[126:129], v[138:141], v[172:175], v[126:129]
	v_mfma_f32_16x16x32_bf16 v[110:113], v[122:125], v[180:183], v[110:113]
	v_mfma_f32_16x16x32_bf16 v[106:109], v[138:141], v[180:183], v[106:109]
	v_mfma_f32_16x16x32_bf16 v[92:95], v[122:125], v[194:197], v[92:95]
	v_mfma_f32_16x16x32_bf16 v[88:91], v[138:141], v[194:197], v[88:91]
	v_mfma_f32_16x16x32_bf16 v[76:79], v[122:125], v[210:213], v[76:79]
	v_mfma_f32_16x16x32_bf16 v[72:75], v[138:141], v[210:213], v[72:75]
	v_mfma_f32_16x16x32_bf16 v[130:133], v[134:137], v[176:179], v[130:133]
	v_mfma_f32_16x16x32_bf16 v[126:129], v[142:145], v[176:179], v[126:129]
	v_mfma_f32_16x16x32_bf16 v[110:113], v[134:137], v[190:193], v[110:113]
	v_mfma_f32_16x16x32_bf16 v[106:109], v[142:145], v[190:193], v[106:109]
	v_mfma_f32_16x16x32_bf16 v[92:95], v[134:137], v[198:201], v[92:95]
	v_mfma_f32_16x16x32_bf16 v[88:91], v[142:145], v[198:201], v[88:91]
	v_mfma_f32_16x16x32_bf16 v[76:79], v[134:137], v[214:217], v[76:79]
	v_mfma_f32_16x16x32_bf16 v[72:75], v[142:145], v[214:217], v[72:75]
	s_setprio 0
	s_setprio 1
	v_mfma_f32_16x16x32_bf16 v[118:121], v[146:149], v[172:175], v[118:121]
	v_mfma_f32_16x16x32_bf16 v[114:117], v[164:167], v[172:175], v[114:117]
	v_mfma_f32_16x16x32_bf16 v[102:105], v[146:149], v[180:183], v[102:105]
	v_mfma_f32_16x16x32_bf16 v[98:101], v[164:167], v[180:183], v[98:101]
	v_mfma_f32_16x16x32_bf16 v[84:87], v[146:149], v[194:197], v[84:87]
	v_mfma_f32_16x16x32_bf16 v[80:83], v[164:167], v[194:197], v[80:83]
	v_mfma_f32_16x16x32_bf16 v[68:71], v[146:149], v[210:213], v[68:71]
	v_mfma_f32_16x16x32_bf16 v[64:67], v[164:167], v[210:213], v[64:67]
	v_mfma_f32_16x16x32_bf16 v[118:121], v[150:153], v[176:179], v[118:121]
	v_mfma_f32_16x16x32_bf16 v[114:117], v[168:171], v[176:179], v[114:117]
	v_mfma_f32_16x16x32_bf16 v[102:105], v[150:153], v[190:193], v[102:105]
	v_mfma_f32_16x16x32_bf16 v[98:101], v[168:171], v[190:193], v[98:101]
	v_mfma_f32_16x16x32_bf16 v[84:87], v[150:153], v[198:201], v[84:87]
	v_mfma_f32_16x16x32_bf16 v[80:83], v[168:171], v[198:201], v[80:83]
	v_mfma_f32_16x16x32_bf16 v[68:71], v[150:153], v[214:217], v[68:71]
	v_mfma_f32_16x16x32_bf16 v[64:67], v[168:171], v[214:217], v[64:67]
	s_setprio 0
	s_barrier
	s_add_i32 s45, s45, s2
	v_lshl_add_u64 v[218:219], s[16:17], 0, v[96:97]
	s_mov_b32 m0, s45
	ds_read_b128 v[172:175], v188 offset:16384
	ds_read_b128 v[176:179], v188 offset:17408
	ds_read_b128 v[180:183], v188 offset:18432
	ds_read_b128 v[190:193], v188 offset:19456
	ds_read_b128 v[194:197], v188 offset:20480
	ds_read_b128 v[198:201], v188 offset:21504
	ds_read_b128 v[210:213], v188 offset:22528
	ds_read_b128 v[214:217], v188 offset:23552
	global_load_lds_dwordx4 v[218:219], off
	s_add_i32 m0, s45, 0x2000
	s_add_u32 s50, s16, 0x20000
	v_lshl_add_u64 v[220:221], s[16:17], 0, v[158:159]
	s_addc_u32 s51, s17, 0
	s_add_i32 s3, s3, s2
	global_load_lds_dwordx4 v[220:221], off
	v_lshl_add_u64 v[222:223], s[50:51], 0, v[96:97]
	s_mov_b32 m0, s3
	v_lshl_add_u64 v[224:225], s[54:55], 0, v[156:157]
	global_load_lds_dwordx4 v[222:223], off
	v_lshl_add_u64 v[222:223], s[50:51], 0, v[158:159]
	s_add_i32 m0, s3, 0x2000
	s_nop 0
	global_load_lds_dwordx4 v[222:223], off
	v_lshl_add_u64 v[222:223], s[54:55], 0, v[154:155]
	s_mov_b32 m0, s23
	s_nop 0
	global_load_lds_dwordx4 v[222:223], off
	s_mov_b32 m0, s24
	s_nop 0
	global_load_lds_dwordx4 v[224:225], off
	s_waitcnt vmcnt(8)
	s_waitcnt lgkmcnt(0)
	s_barrier
; #define PG8_STAGE(bufoff, gbase, voff) do { _Pragma("unroll") for (int _i = 0; _i < 2; ++_i) \
;         __builtin_amdgcn_global_load_lds((const unsigned*)((const char*)(gbase) + (voff)[_i]), (LAS unsigned*)(lds + (bufoff) + ldsw + _i * 8192), 16, 0, 0); } while (0)
; #define PG8_LDA(dst, b, h) do { _Pragma("unroll") for (int m = 0; m < 4; ++m) _Pragma("unroll") for (int k = 0; k < 2; ++k) dst[m][k] = *(const LAS bf16x8*)(lds + PG8_SA(b, h) + aoff + m * 2048 + k * 1024); } while (0)
; #define PG8_LDB(dst, b, h) do { _Pragma("unroll") for (int n = 0; n < 2; ++n) _Pragma("unroll") for (int k = 0; k < 2; ++k) dst[n][k] = *(const LAS bf16x8*)(lds + PG8_SB(b, h) + boff + n * 2048 + k * 1024); } while (0)
; #define PG8_MMA(ai, bj, At, Bt) do { __builtin_amdgcn_s_setprio(1); _Pragma("unroll") for (int m = 0; m < 4; ++m) _Pragma("unroll") for (int n = 0; n < 2; ++n) _Pragma("unroll") for (int k = 0; k < 2; ++k) \
;         acc[ai][bj][m][n] = __builtin_amdgcn_mfma_f32_16x16x32_bf16(Bt[n][k], At[m][k], acc[ai][bj][m][n], 0, 0, 0); __builtin_amdgcn_s_setprio(0); } while (0)
; #define PG8_WAIT_V(n) asm volatile("s_waitcnt vmcnt(" #n ")" ::: "memory")
; #define PG8_WAIT_L(n) asm volatile("s_waitcnt lgkmcnt(" #n ")" ::: "memory")
; #define PG8_BAR __builtin_amdgcn_s_barrier()
; #define PG8_SCHED __builtin_amdgcn_sched_barrier(0)
; template <int K, int LDA, int LDB, int KGRP, bool APERM, class Epi>
; __device__ __forceinline__ void gemm_phase(LAS unsigned char* lds, const Gemm g, const StaticOrder& S, const Epi& E, const int tid) {
;     ...
;             PG8_WAIT_V(8); PG8_WAIT_L(0); PG8_BAR; PG8_MMA(1, 0, At, B0); PG8_MMA(1, 1, At, B1); PG8_BAR; PG8_SCHED;
;             PG8_LDB(B0, 1, 0); PG8_LDB(B1, 1, 1); PG8_SCHED; PG8_LDA(At, 1, 0); PG8_STAGE(PG8_SA(0, 1), a2 + hstepA, voffA);
;             PG8_WAIT_V(8); PG8_WAIT_L(0); PG8_BAR; PG8_MMA(0, 0, At, B0); PG8_MMA(0, 1, At, B1); PG8_BAR; PG8_SCHED;
	s_setprio 1
	v_mfma_f32_16x16x32_bf16 v[60:63], v[122:125], v[172:175], v[60:63]
	v_mfma_f32_16x16x32_bf16 v[56:59], v[138:141], v[172:175], v[56:59]
	v_mfma_f32_16x16x32_bf16 v[44:47], v[122:125], v[180:183], v[44:47]
	v_mfma_f32_16x16x32_bf16 v[40:43], v[138:141], v[180:183], v[40:43]
	v_mfma_f32_16x16x32_bf16 v[28:31], v[122:125], v[194:197], v[28:31]
	v_mfma_f32_16x16x32_bf16 v[24:27], v[138:141], v[194:197], v[24:27]
	v_mfma_f32_16x16x32_bf16 v[12:15], v[122:125], v[210:213], v[12:15]
	v_mfma_f32_16x16x32_bf16 v[8:11], v[138:141], v[210:213], v[8:11]
	v_mfma_f32_16x16x32_bf16 v[60:63], v[134:137], v[176:179], v[60:63]
	v_mfma_f32_16x16x32_bf16 v[56:59], v[142:145], v[176:179], v[56:59]
	v_mfma_f32_16x16x32_bf16 v[44:47], v[134:137], v[190:193], v[44:47]
	v_mfma_f32_16x16x32_bf16 v[40:43], v[142:145], v[190:193], v[40:43]
	v_mfma_f32_16x16x32_bf16 v[28:31], v[134:137], v[198:201], v[28:31]
	v_mfma_f32_16x16x32_bf16 v[24:27], v[142:145], v[198:201], v[24:27]
	v_mfma_f32_16x16x32_bf16 v[12:15], v[134:137], v[214:217], v[12:15]
	v_mfma_f32_16x16x32_bf16 v[8:11], v[142:145], v[214:217], v[8:11]
	s_setprio 0
	s_setprio 1
	v_mfma_f32_16x16x32_bf16 v[52:55], v[146:149], v[172:175], v[52:55]
	v_mfma_f32_16x16x32_bf16 v[48:51], v[164:167], v[172:175], v[48:51]
	v_mfma_f32_16x16x32_bf16 v[36:39], v[146:149], v[180:183], v[36:39]
	v_mfma_f32_16x16x32_bf16 v[32:35], v[164:167], v[180:183], v[32:35]
	v_mfma_f32_16x16x32_bf16 v[20:23], v[146:149], v[194:197], v[20:23]
	v_mfma_f32_16x16x32_bf16 v[16:19], v[164:167], v[194:197], v[16:19]
	v_mfma_f32_16x16x32_bf16 v[4:7], v[146:149], v[210:213], v[4:7]
	v_mfma_f32_16x16x32_bf16 v[0:3], v[164:167], v[210:213], v[0:3]
	v_mfma_f32_16x16x32_bf16 v[52:55], v[150:153], v[176:179], v[52:55]
	v_mfma_f32_16x16x32_bf16 v[48:51], v[168:171], v[176:179], v[48:51]
	v_mfma_f32_16x16x32_bf16 v[36:39], v[150:153], v[190:193], v[36:39]
	v_mfma_f32_16x16x32_bf16 v[32:35], v[168:171], v[190:193], v[32:35]
	v_mfma_f32_16x16x32_bf16 v[20:23], v[150:153], v[198:201], v[20:23]
	v_mfma_f32_16x16x32_bf16 v[16:19], v[168:171], v[198:201], v[16:19]
	v_mfma_f32_16x16x32_bf16 v[4:7], v[150:153], v[214:217], v[4:7]
	v_mfma_f32_16x16x32_bf16 v[0:3], v[168:171], v[214:217], v[0:3]
	s_setprio 0
	s_barrier
	s_add_i32 s3, 0, 0x18000
	s_add_i32 s45, 0, 0x1c000
	v_add_u32_e32 v142, s3, v186
	v_add_u32_e32 v168, s45, v186
	ds_read_b128 v[122:125], v142
	ds_read_b128 v[134:137], v142 offset:1024
	ds_read_b128 v[138:141], v142 offset:2048
	ds_read_b128 v[142:145], v142 offset:3072
	ds_read_b128 v[146:149], v168
	ds_read_b128 v[150:153], v168 offset:1024
	ds_read_b128 v[164:167], v168 offset:2048
	ds_read_b128 v[168:171], v168 offset:3072
	s_add_u32 s50, s54, 0x80000
	s_addc_u32 s51, s55, 0
	s_mov_b32 m0, s26
	v_lshl_add_u64 v[226:227], s[50:51], 0, v[154:155]
	ds_read_b128 v[172:175], v188 offset:32768
	ds_read_b128 v[176:179], v188 offset:33792
	ds_read_b128 v[180:183], v188 offset:34816
	ds_read_b128 v[190:193], v188 offset:35840
	ds_read_b128 v[194:197], v188 offset:36864
	ds_read_b128 v[198:201], v188 offset:37888
	ds_read_b128 v[210:213], v188 offset:38912
	ds_read_b128 v[214:217], v188 offset:39936
	global_load_lds_dwordx4 v[226:227], off
	v_lshl_add_u64 v[226:227], s[50:51], 0, v[156:157]
	s_mov_b32 m0, s27
	s_nop 0
	global_load_lds_dwordx4 v[226:227], off
	s_waitcnt vmcnt(8)
	s_waitcnt lgkmcnt(0)
	s_barrier
	s_setprio 1
	v_mfma_f32_16x16x32_bf16 v[130:133], v[122:125], v[172:175], v[130:133]
	v_mfma_f32_16x16x32_bf16 v[126:129], v[138:141], v[172:175], v[126:129]
	v_mfma_f32_16x16x32_bf16 v[110:113], v[122:125], v[180:183], v[110:113]
	v_mfma_f32_16x16x32_bf16 v[106:109], v[138:141], v[180:183], v[106:109]
	v_mfma_f32_16x16x32_bf16 v[92:95], v[122:125], v[194:197], v[92:95]
	v_mfma_f32_16x16x32_bf16 v[88:91], v[138:141], v[194:197], v[88:91]
	v_mfma_f32_16x16x32_bf16 v[76:79], v[122:125], v[210:213], v[76:79]
	v_mfma_f32_16x16x32_bf16 v[72:75], v[138:141], v[210:213], v[72:75]
	v_mfma_f32_16x16x32_bf16 v[130:133], v[134:137], v[176:179], v[130:133]
	v_mfma_f32_16x16x32_bf16 v[126:129], v[142:145], v[176:179], v[126:129]
	v_mfma_f32_16x16x32_bf16 v[110:113], v[134:137], v[190:193], v[110:113]
	v_mfma_f32_16x16x32_bf16 v[106:109], v[142:145], v[190:193], v[106:109]
	v_mfma_f32_16x16x32_bf16 v[92:95], v[134:137], v[198:201], v[92:95]
	v_mfma_f32_16x16x32_bf16 v[88:91], v[142:145], v[198:201], v[88:91]
	v_mfma_f32_16x16x32_bf16 v[76:79], v[134:137], v[214:217], v[76:79]
	v_mfma_f32_16x16x32_bf16 v[72:75], v[142:145], v[214:217], v[72:75]
	s_setprio 0
	s_setprio 1
	v_mfma_f32_16x16x32_bf16 v[118:121], v[146:149], v[172:175], v[118:121]
	v_mfma_f32_16x16x32_bf16 v[114:117], v[164:167], v[172:175], v[114:117]
	v_mfma_f32_16x16x32_bf16 v[102:105], v[146:149], v[180:183], v[102:105]
	v_mfma_f32_16x16x32_bf16 v[98:101], v[164:167], v[180:183], v[98:101]
	v_mfma_f32_16x16x32_bf16 v[84:87], v[146:149], v[194:197], v[84:87]
	v_mfma_f32_16x16x32_bf16 v[80:83], v[164:167], v[194:197], v[80:83]
	v_mfma_f32_16x16x32_bf16 v[68:71], v[146:149], v[210:213], v[68:71]
	v_mfma_f32_16x16x32_bf16 v[64:67], v[164:167], v[210:213], v[64:67]
	v_mfma_f32_16x16x32_bf16 v[118:121], v[150:153], v[176:179], v[118:121]
	v_mfma_f32_16x16x32_bf16 v[114:117], v[168:171], v[176:179], v[114:117]
	v_mfma_f32_16x16x32_bf16 v[102:105], v[150:153], v[190:193], v[102:105]
	v_mfma_f32_16x16x32_bf16 v[98:101], v[168:171], v[190:193], v[98:101]
	v_mfma_f32_16x16x32_bf16 v[84:87], v[150:153], v[198:201], v[84:87]
	v_mfma_f32_16x16x32_bf16 v[80:83], v[168:171], v[198:201], v[80:83]
	v_mfma_f32_16x16x32_bf16 v[68:71], v[150:153], v[214:217], v[68:71]
	v_mfma_f32_16x16x32_bf16 v[64:67], v[168:171], v[214:217], v[64:67]
	s_setprio 0
	s_barrier
; #define PG8_STAGE(bufoff, gbase, voff) do { _Pragma("unroll") for (int _i = 0; _i < 2; ++_i) \
;         __builtin_amdgcn_global_load_lds((const unsigned*)((const char*)(gbase) + (voff)[_i]), (LAS unsigned*)(lds + (bufoff) + ldsw + _i * 8192), 16, 0, 0); } while (0)
; #define PG8_LDA(dst, b, h) do { _Pragma("unroll") for (int m = 0; m < 4; ++m) _Pragma("unroll") for (int k = 0; k < 2; ++k) dst[m][k] = *(const LAS bf16x8*)(lds + PG8_SA(b, h) + aoff + m * 2048 + k * 1024); } while (0)
; #define PG8_MMA(ai, bj, At, Bt) do { __builtin_amdgcn_s_setprio(1); _Pragma("unroll") for (int m = 0; m < 4; ++m) _Pragma("unroll") for (int n = 0; n < 2; ++n) _Pragma("unroll") for (int k = 0; k < 2; ++k) \
;         acc[ai][bj][m][n] = __builtin_amdgcn_mfma_f32_16x16x32_bf16(Bt[n][k], At[m][k], acc[ai][bj][m][n], 0, 0, 0); __builtin_amdgcn_s_setprio(0); } while (0)
; #define PG8_WAIT_V(n) asm volatile("s_waitcnt vmcnt(" #n ")" ::: "memory")
; #define PG8_WAIT_L(n) asm volatile("s_waitcnt lgkmcnt(" #n ")" ::: "memory")
; #define PG8_BAR __builtin_amdgcn_s_barrier()
; #define PG8_SCHED __builtin_amdgcn_sched_barrier(0)
; template <int K, int LDA, int LDB, int KGRP, bool APERM, class Epi>
; __device__ __forceinline__ void gemm_phase(LAS unsigned char* lds, const Gemm g, const StaticOrder& S, const Epi& E, const int tid) {
;     ...
;             PG8_LDA(At, 1, 1); PG8_STAGE(PG8_SB(1, 0), b3, voffB); PG8_STAGE(PG8_SB(1, 1), b3 + hstepB, voffB); PG8_STAGE(PG8_SA(1, 0), a3, voffA);
;             PG8_WAIT_V(8); PG8_WAIT_L(0); PG8_BAR; PG8_MMA(1, 0, At, B0); PG8_MMA(1, 1, At, B1); PG8_BAR; PG8_SCHED;
;         }
;         if (wr == 0) PG8_BAR;
	s_add_i32 s3, s3, s2
	v_lshl_add_u64 v[218:219], v[218:219], 0, s[38:39]
	s_mov_b32 m0, s3
	ds_read_b128 v[172:175], v188 offset:49152
	ds_read_b128 v[176:179], v188 offset:50176
	ds_read_b128 v[180:183], v188 offset:51200
	ds_read_b128 v[190:193], v188 offset:52224
	ds_read_b128 v[194:197], v188 offset:53248
	ds_read_b128 v[198:201], v188 offset:54272
	ds_read_b128 v[210:213], v188 offset:55296
	ds_read_b128 v[214:217], v188 offset:56320
	global_load_lds_dwordx4 v[218:219], off
	s_add_i32 m0, s3, 0x2000
	s_add_u32 s16, s16, 0x20080
	v_lshl_add_u64 v[218:219], v[220:221], 0, s[38:39]
	s_addc_u32 s17, s17, 0
	s_add_i32 s3, s45, s2
	global_load_lds_dwordx4 v[218:219], off
	v_lshl_add_u64 v[218:219], s[16:17], 0, v[96:97]
	s_mov_b32 m0, s3
	s_nop 0
	global_load_lds_dwordx4 v[218:219], off
	v_lshl_add_u64 v[218:219], s[16:17], 0, v[158:159]
	s_add_i32 m0, s3, 0x2000
	s_nop 0
	global_load_lds_dwordx4 v[218:219], off
	v_lshl_add_u64 v[218:219], v[222:223], 0, s[38:39]
	s_mov_b32 m0, s29
	s_nop 0
	global_load_lds_dwordx4 v[218:219], off
	v_lshl_add_u64 v[218:219], v[224:225], 0, s[38:39]
	s_mov_b32 m0, s30
	s_nop 0
	global_load_lds_dwordx4 v[218:219], off
	s_waitcnt vmcnt(8)
	s_waitcnt lgkmcnt(0)
	s_barrier
	s_setprio 1
	v_mfma_f32_16x16x32_bf16 v[60:63], v[122:125], v[172:175], v[60:63]
	v_mfma_f32_16x16x32_bf16 v[56:59], v[138:141], v[172:175], v[56:59]
	v_mfma_f32_16x16x32_bf16 v[44:47], v[122:125], v[180:183], v[44:47]
	v_mfma_f32_16x16x32_bf16 v[40:43], v[138:141], v[180:183], v[40:43]
	v_mfma_f32_16x16x32_bf16 v[28:31], v[122:125], v[194:197], v[28:31]
	v_mfma_f32_16x16x32_bf16 v[24:27], v[138:141], v[194:197], v[24:27]
	v_mfma_f32_16x16x32_bf16 v[12:15], v[122:125], v[210:213], v[12:15]
	v_mfma_f32_16x16x32_bf16 v[8:11], v[138:141], v[210:213], v[8:11]
	v_mfma_f32_16x16x32_bf16 v[60:63], v[134:137], v[176:179], v[60:63]
	v_mfma_f32_16x16x32_bf16 v[56:59], v[142:145], v[176:179], v[56:59]
	v_mfma_f32_16x16x32_bf16 v[44:47], v[134:137], v[190:193], v[44:47]
	v_mfma_f32_16x16x32_bf16 v[40:43], v[142:145], v[190:193], v[40:43]
	v_mfma_f32_16x16x32_bf16 v[28:31], v[134:137], v[198:201], v[28:31]
	v_mfma_f32_16x16x32_bf16 v[24:27], v[142:145], v[198:201], v[24:27]
	v_mfma_f32_16x16x32_bf16 v[12:15], v[134:137], v[214:217], v[12:15]
	v_mfma_f32_16x16x32_bf16 v[8:11], v[142:145], v[214:217], v[8:11]
	s_setprio 0
	s_setprio 1
	v_mfma_f32_16x16x32_bf16 v[52:55], v[146:149], v[172:175], v[52:55]
	v_mfma_f32_16x16x32_bf16 v[48:51], v[164:167], v[172:175], v[48:51]
	v_mfma_f32_16x16x32_bf16 v[36:39], v[146:149], v[180:183], v[36:39]
	v_mfma_f32_16x16x32_bf16 v[32:35], v[164:167], v[180:183], v[32:35]
	v_mfma_f32_16x16x32_bf16 v[20:23], v[146:149], v[194:197], v[20:23]
	v_mfma_f32_16x16x32_bf16 v[16:19], v[164:167], v[194:197], v[16:19]
	v_mfma_f32_16x16x32_bf16 v[4:7], v[146:149], v[210:213], v[4:7]
	v_mfma_f32_16x16x32_bf16 v[0:3], v[164:167], v[210:213], v[0:3]
	v_mfma_f32_16x16x32_bf16 v[52:55], v[150:153], v[176:179], v[52:55]
	v_mfma_f32_16x16x32_bf16 v[48:51], v[168:171], v[176:179], v[48:51]
	v_mfma_f32_16x16x32_bf16 v[36:39], v[150:153], v[190:193], v[36:39]
	v_mfma_f32_16x16x32_bf16 v[32:35], v[168:171], v[190:193], v[32:35]
	v_mfma_f32_16x16x32_bf16 v[20:23], v[150:153], v[198:201], v[20:23]
	v_mfma_f32_16x16x32_bf16 v[16:19], v[168:171], v[198:201], v[16:19]
	v_mfma_f32_16x16x32_bf16 v[4:7], v[150:153], v[214:217], v[4:7]
	v_mfma_f32_16x16x32_bf16 v[0:3], v[168:171], v[214:217], v[0:3]
	s_setprio 0
	s_barrier
	s_add_i32 s44, s44, 2
	s_add_u32 s8, s8, 0x100
	s_addc_u32 s9, s9, 0
	s_add_u32 s42, s42, 0x100
	s_addc_u32 s43, s43, 0
	s_cmp_gt_u32 s44, 5
	s_cbranch_scc0 .LBB0_767
	s_and_b64 vcc, exec, s[64:65]
	s_cbranch_vccz .LBB0_770
	s_barrier

; #define PG8_STAGE(bufoff, gbase, voff) do { _Pragma("unroll") for (int _i = 0; _i < 2; ++_i) \
;         __builtin_amdgcn_global_load_lds((const unsigned*)((const char*)(gbase) + (voff)[_i]), (LAS unsigned*)(lds + (bufoff) + ldsw + _i * 8192), 16, 0, 0); } while (0)
; #define PG8_LDA(dst, b, h) do { _Pragma("unroll") for (int m = 0; m < 4; ++m) _Pragma("unroll") for (int k = 0; k < 2; ++k) dst[m][k] = *(const LAS bf16x8*)(lds + PG8_SA(b, h) + aoff + m * 2048 + k * 1024); } while (0)
; #define PG8_LDB(dst, b, h) do { _Pragma("unroll") for (int n = 0; n < 2; ++n) _Pragma("unroll") for (int k = 0; k < 2; ++k) dst[n][k] = *(const LAS bf16x8*)(lds + PG8_SB(b, h) + boff + n * 2048 + k * 1024); } while (0)
; #define PG8_MMA(ai, bj, At, Bt) do { __builtin_amdgcn_s_setprio(1); _Pragma("unroll") for (int m = 0; m < 4; ++m) _Pragma("unroll") for (int n = 0; n < 2; ++n) _Pragma("unroll") for (int k = 0; k < 2; ++k) \
;         acc[ai][bj][m][n] = __builtin_amdgcn_mfma_f32_16x16x32_bf16(Bt[n][k], At[m][k], acc[ai][bj][m][n], 0, 0, 0); __builtin_amdgcn_s_setprio(0); } while (0)
; #define PG8_WAIT_V(n) asm volatile("s_waitcnt vmcnt(" #n ")" ::: "memory")
; #define PG8_WAIT_L(n) asm volatile("s_waitcnt lgkmcnt(" #n ")" ::: "memory")
; #define PG8_BAR __builtin_amdgcn_s_barrier()
; #define PG8_SCHED __builtin_amdgcn_sched_barrier(0)
; template <int K, int LDA, int LDB, int KGRP, bool APERM, class Epi>
; __device__ __forceinline__ void gemm_phase(LAS unsigned char* lds, const Gemm g, const StaticOrder& S, const Epi& E, const int tid) {
;     ...
;             const bool last = (t == nt - 2);
;             const char* a1 = cA + (size_t)(t + 1) * kstep;
;             const char* a2 = last ? nA : cA + (size_t)(t + 2) * kstep; const char* b2 = last ? nB : cB + (size_t)(t + 2) * kstep;
;             const char* a3 = a2 + kstep; const char* b3 = b2 + kstep;
;             PG8_LDB(B0, 0, 0); PG8_LDB(B1, 0, 1); PG8_SCHED; PG8_LDA(At, 0, 0); PG8_STAGE(PG8_SA(1, 1), a1 + hstepA, voffA);
;             PG8_WAIT_V(8); PG8_WAIT_L(0); PG8_BAR; PG8_MMA(0, 0, At, B0); PG8_MMA(0, 1, At, B1); PG8_BAR; PG8_SCHED;
;             PG8_LDA(At, 0, 1); PG8_STAGE(PG8_SB(0, 0), b2, voffB); PG8_STAGE(PG8_SB(0, 1), b2 + hstepB, voffB); PG8_STAGE(PG8_SA(0, 0), a2, voffA);
;             PG8_WAIT_V(8); PG8_WAIT_L(0); PG8_BAR; PG8_MMA(1, 0, At, B0); PG8_MMA(1, 1, At, B1); PG8_BAR; PG8_SCHED;
.LBB0_893:
	s_add_u32 s3, s8, 0xfff80080
	s_addc_u32 s16, s9, -1
	s_add_i32 s45, 0, 0x10000
	s_cmp_eq_u32 s44, 4
	s_cselect_b32 s55, s77, s16
	s_cselect_b32 s54, s76, s3
	s_cselect_b32 s17, s11, s43
	s_cselect_b32 s16, s18, s42
	s_add_i32 s3, 0, 0x14000
	v_add_u32_e32 v142, s45, v211
	v_add_u32_e32 v158, s3, v211
	ds_read_b128 v[122:125], v142
	ds_read_b128 v[130:133], v142 offset:1024
	ds_read_b128 v[138:141], v142 offset:2048
	ds_read_b128 v[142:145], v142 offset:3072
	ds_read_b128 v[146:149], v158
	ds_read_b128 v[150:153], v158 offset:1024
	ds_read_b128 v[154:157], v158 offset:2048
	ds_read_b128 v[158:161], v158 offset:3072
	v_lshl_add_u64 v[200:201], s[8:9], 0, v[184:185]
	s_add_i32 m0, s23, 0xc000
	ds_read_b128 v[162:165], v213
	ds_read_b128 v[166:169], v213 offset:1024
	ds_read_b128 v[170:173], v213 offset:2048
	ds_read_b128 v[174:177], v213 offset:3072
	ds_read_b128 v[188:191], v213 offset:4096
	ds_read_b128 v[192:195], v213 offset:5120
	ds_read_b128 v[196:199], v213 offset:6144
	ds_read_b128 v[214:217], v213 offset:7168
	global_load_lds_dwordx4 v[200:201], off
	v_lshl_add_u64 v[200:201], s[8:9], 0, v[186:187]
	s_add_i32 m0, s23, 0xe000
	s_nop 0
	global_load_lds_dwordx4 v[200:201], off
	s_waitcnt vmcnt(8)
	s_waitcnt lgkmcnt(0)
	s_barrier
	s_setprio 1
	v_mfma_f32_16x16x32_bf16 v[134:137], v[122:125], v[162:165], v[134:137]
	v_mfma_f32_16x16x32_bf16 v[126:129], v[138:141], v[162:165], v[126:129]
	v_mfma_f32_16x16x32_bf16 v[110:113], v[122:125], v[170:173], v[110:113]
	v_mfma_f32_16x16x32_bf16 v[106:109], v[138:141], v[170:173], v[106:109]
	v_mfma_f32_16x16x32_bf16 v[92:95], v[122:125], v[188:191], v[92:95]
	v_mfma_f32_16x16x32_bf16 v[88:91], v[138:141], v[188:191], v[88:91]
	v_mfma_f32_16x16x32_bf16 v[76:79], v[122:125], v[196:199], v[76:79]
	v_mfma_f32_16x16x32_bf16 v[72:75], v[138:141], v[196:199], v[72:75]
	v_mfma_f32_16x16x32_bf16 v[134:137], v[130:133], v[166:169], v[134:137]
	v_mfma_f32_16x16x32_bf16 v[126:129], v[142:145], v[166:169], v[126:129]
	v_mfma_f32_16x16x32_bf16 v[110:113], v[130:133], v[174:177], v[110:113]
	v_mfma_f32_16x16x32_bf16 v[106:109], v[142:145], v[174:177], v[106:109]
	v_mfma_f32_16x16x32_bf16 v[92:95], v[130:133], v[192:195], v[92:95]
	v_mfma_f32_16x16x32_bf16 v[88:91], v[142:145], v[192:195], v[88:91]
	v_mfma_f32_16x16x32_bf16 v[76:79], v[130:133], v[214:217], v[76:79]
	v_mfma_f32_16x16x32_bf16 v[72:75], v[142:145], v[214:217], v[72:75]
	s_setprio 0
	s_setprio 1
	v_mfma_f32_16x16x32_bf16 v[118:121], v[146:149], v[162:165], v[118:121]
	v_mfma_f32_16x16x32_bf16 v[114:117], v[154:157], v[162:165], v[114:117]
	v_mfma_f32_16x16x32_bf16 v[102:105], v[146:149], v[170:173], v[102:105]
	v_mfma_f32_16x16x32_bf16 v[98:101], v[154:157], v[170:173], v[98:101]
	v_mfma_f32_16x16x32_bf16 v[84:87], v[146:149], v[188:191], v[84:87]
	v_mfma_f32_16x16x32_bf16 v[80:83], v[154:157], v[188:191], v[80:83]
	v_mfma_f32_16x16x32_bf16 v[68:71], v[146:149], v[196:199], v[68:71]
	v_mfma_f32_16x16x32_bf16 v[64:67], v[154:157], v[196:199], v[64:67]
	v_mfma_f32_16x16x32_bf16 v[118:121], v[150:153], v[166:169], v[118:121]
	v_mfma_f32_16x16x32_bf16 v[114:117], v[158:161], v[166:169], v[114:117]
	v_mfma_f32_16x16x32_bf16 v[102:105], v[150:153], v[174:177], v[102:105]
	v_mfma_f32_16x16x32_bf16 v[98:101], v[158:161], v[174:177], v[98:101]
	v_mfma_f32_16x16x32_bf16 v[84:87], v[150:153], v[192:195], v[84:87]
	v_mfma_f32_16x16x32_bf16 v[80:83], v[158:161], v[192:195], v[80:83]
	v_mfma_f32_16x16x32_bf16 v[68:71], v[150:153], v[214:217], v[68:71]
	v_mfma_f32_16x16x32_bf16 v[64:67], v[158:161], v[214:217], v[64:67]
	s_setprio 0
	s_barrier
	s_add_i32 s45, s45, s2
	v_lshl_add_u64 v[200:201], s[16:17], 0, v[96:97]
	s_mov_b32 m0, s45
	ds_read_b128 v[162:165], v213 offset:16384
	ds_read_b128 v[166:169], v213 offset:17408
	ds_read_b128 v[170:173], v213 offset:18432
	ds_read_b128 v[174:177], v213 offset:19456
	ds_read_b128 v[188:191], v213 offset:20480
	ds_read_b128 v[192:195], v213 offset:21504
	ds_read_b128 v[196:199], v213 offset:22528
	ds_read_b128 v[214:217], v213 offset:23552
	global_load_lds_dwordx4 v[200:201], off
	s_add_i32 m0, s45, 0x2000
	s_add_u32 s50, s16, 0x20000
	v_lshl_add_u64 v[218:219], s[16:17], 0, v[182:183]
	s_addc_u32 s51, s17, 0
	s_add_i32 s3, s3, s2
	global_load_lds_dwordx4 v[218:219], off
	v_lshl_add_u64 v[220:221], s[50:51], 0, v[96:97]
	s_mov_b32 m0, s3
	v_lshl_add_u64 v[222:223], s[54:55], 0, v[180:181]
	global_load_lds_dwordx4 v[220:221], off
	v_lshl_add_u64 v[220:221], s[50:51], 0, v[182:183]
	s_add_i32 m0, s3, 0x2000
	s_nop 0
	global_load_lds_dwordx4 v[220:221], off
	v_lshl_add_u64 v[220:221], s[54:55], 0, v[178:179]
	s_mov_b32 m0, s23
	s_nop 0
	global_load_lds_dwordx4 v[220:221], off
	s_mov_b32 m0, s24
	s_nop 0
	global_load_lds_dwordx4 v[222:223], off
	s_waitcnt vmcnt(8)
	s_waitcnt lgkmcnt(0)
	s_barrier
; #define PG8_STAGE(bufoff, gbase, voff) do { _Pragma("unroll") for (int _i = 0; _i < 2; ++_i) \
;         __builtin_amdgcn_global_load_lds((const unsigned*)((const char*)(gbase) + (voff)[_i]), (LAS unsigned*)(lds + (bufoff) + ldsw + _i * 8192), 16, 0, 0); } while (0)
; #define PG8_LDA(dst, b, h) do { _Pragma("unroll") for (int m = 0; m < 4; ++m) _Pragma("unroll") for (int k = 0; k < 2; ++k) dst[m][k] = *(const LAS bf16x8*)(lds + PG8_SA(b, h) + aoff + m * 2048 + k * 1024); } while (0)
; #define PG8_LDB(dst, b, h) do { _Pragma("unroll") for (int n = 0; n < 2; ++n) _Pragma("unroll") for (int k = 0; k < 2; ++k) dst[n][k] = *(const LAS bf16x8*)(lds + PG8_SB(b, h) + boff + n * 2048 + k * 1024); } while (0)
; #define PG8_MMA(ai, bj, At, Bt) do { __builtin_amdgcn_s_setprio(1); _Pragma("unroll") for (int m = 0; m < 4; ++m) _Pragma("unroll") for (int n = 0; n < 2; ++n) _Pragma("unroll") for (int k = 0; k < 2; ++k) \
;         acc[ai][bj][m][n] = __builtin_amdgcn_mfma_f32_16x16x32_bf16(Bt[n][k], At[m][k], acc[ai][bj][m][n], 0, 0, 0); __builtin_amdgcn_s_setprio(0); } while (0)
; #define PG8_WAIT_V(n) asm volatile("s_waitcnt vmcnt(" #n ")" ::: "memory")
; #define PG8_WAIT_L(n) asm volatile("s_waitcnt lgkmcnt(" #n ")" ::: "memory")
; #define PG8_BAR __builtin_amdgcn_s_barrier()
; #define PG8_SCHED __builtin_amdgcn_sched_barrier(0)
; template <int K, int LDA, int LDB, int KGRP, bool APERM, class Epi>
; __device__ __forceinline__ void gemm_phase(LAS unsigned char* lds, const Gemm g, const StaticOrder& S, const Epi& E, const int tid) {
;     ...
;             PG8_WAIT_V(8); PG8_WAIT_L(0); PG8_BAR; PG8_MMA(1, 0, At, B0); PG8_MMA(1, 1, At, B1); PG8_BAR; PG8_SCHED;
;             PG8_LDB(B0, 1, 0); PG8_LDB(B1, 1, 1); PG8_SCHED; PG8_LDA(At, 1, 0); PG8_STAGE(PG8_SA(0, 1), a2 + hstepA, voffA);
;             PG8_WAIT_V(8); PG8_WAIT_L(0); PG8_BAR; PG8_MMA(0, 0, At, B0); PG8_MMA(0, 1, At, B1); PG8_BAR; PG8_SCHED;
	s_setprio 1
	v_mfma_f32_16x16x32_bf16 v[60:63], v[122:125], v[162:165], v[60:63]
	v_mfma_f32_16x16x32_bf16 v[56:59], v[138:141], v[162:165], v[56:59]
	v_mfma_f32_16x16x32_bf16 v[44:47], v[122:125], v[170:173], v[44:47]
	v_mfma_f32_16x16x32_bf16 v[40:43], v[138:141], v[170:173], v[40:43]
	v_mfma_f32_16x16x32_bf16 v[28:31], v[122:125], v[188:191], v[28:31]
	v_mfma_f32_16x16x32_bf16 v[24:27], v[138:141], v[188:191], v[24:27]
	v_mfma_f32_16x16x32_bf16 v[12:15], v[122:125], v[196:199], v[12:15]
	v_mfma_f32_16x16x32_bf16 v[8:11], v[138:141], v[196:199], v[8:11]
	v_mfma_f32_16x16x32_bf16 v[60:63], v[130:133], v[166:169], v[60:63]
	v_mfma_f32_16x16x32_bf16 v[56:59], v[142:145], v[166:169], v[56:59]
	v_mfma_f32_16x16x32_bf16 v[44:47], v[130:133], v[174:177], v[44:47]
	v_mfma_f32_16x16x32_bf16 v[40:43], v[142:145], v[174:177], v[40:43]
	v_mfma_f32_16x16x32_bf16 v[28:31], v[130:133], v[192:195], v[28:31]
	v_mfma_f32_16x16x32_bf16 v[24:27], v[142:145], v[192:195], v[24:27]
	v_mfma_f32_16x16x32_bf16 v[12:15], v[130:133], v[214:217], v[12:15]
	v_mfma_f32_16x16x32_bf16 v[8:11], v[142:145], v[214:217], v[8:11]
	s_setprio 0
	s_setprio 1
	v_mfma_f32_16x16x32_bf16 v[52:55], v[146:149], v[162:165], v[52:55]
	v_mfma_f32_16x16x32_bf16 v[48:51], v[154:157], v[162:165], v[48:51]
	v_mfma_f32_16x16x32_bf16 v[36:39], v[146:149], v[170:173], v[36:39]
	v_mfma_f32_16x16x32_bf16 v[32:35], v[154:157], v[170:173], v[32:35]
	v_mfma_f32_16x16x32_bf16 v[20:23], v[146:149], v[188:191], v[20:23]
	v_mfma_f32_16x16x32_bf16 v[16:19], v[154:157], v[188:191], v[16:19]
	v_mfma_f32_16x16x32_bf16 v[4:7], v[146:149], v[196:199], v[4:7]
	v_mfma_f32_16x16x32_bf16 v[0:3], v[154:157], v[196:199], v[0:3]
	v_mfma_f32_16x16x32_bf16 v[52:55], v[150:153], v[166:169], v[52:55]
	v_mfma_f32_16x16x32_bf16 v[48:51], v[158:161], v[166:169], v[48:51]
	v_mfma_f32_16x16x32_bf16 v[36:39], v[150:153], v[174:177], v[36:39]
	v_mfma_f32_16x16x32_bf16 v[32:35], v[158:161], v[174:177], v[32:35]
	v_mfma_f32_16x16x32_bf16 v[20:23], v[150:153], v[192:195], v[20:23]
	v_mfma_f32_16x16x32_bf16 v[16:19], v[158:161], v[192:195], v[16:19]
	v_mfma_f32_16x16x32_bf16 v[4:7], v[150:153], v[214:217], v[4:7]
	v_mfma_f32_16x16x32_bf16 v[0:3], v[158:161], v[214:217], v[0:3]
	s_setprio 0
	s_barrier
	s_add_i32 s3, 0, 0x18000
	s_add_i32 s45, 0, 0x1c000
	v_add_u32_e32 v142, s3, v211
	v_add_u32_e32 v158, s45, v211
	ds_read_b128 v[122:125], v142
	ds_read_b128 v[130:133], v142 offset:1024
	ds_read_b128 v[138:141], v142 offset:2048
	ds_read_b128 v[142:145], v142 offset:3072
	ds_read_b128 v[146:149], v158
	ds_read_b128 v[150:153], v158 offset:1024
	ds_read_b128 v[154:157], v158 offset:2048
	ds_read_b128 v[158:161], v158 offset:3072
	s_add_u32 s50, s54, 0x80000
	s_addc_u32 s51, s55, 0
	s_mov_b32 m0, s26
	v_lshl_add_u64 v[224:225], s[50:51], 0, v[178:179]
	ds_read_b128 v[162:165], v213 offset:32768
	ds_read_b128 v[166:169], v213 offset:33792
	ds_read_b128 v[170:173], v213 offset:34816
	ds_read_b128 v[174:177], v213 offset:35840
	ds_read_b128 v[188:191], v213 offset:36864
	ds_read_b128 v[192:195], v213 offset:37888
	ds_read_b128 v[196:199], v213 offset:38912
	ds_read_b128 v[214:217], v213 offset:39936
	global_load_lds_dwordx4 v[224:225], off
	v_lshl_add_u64 v[224:225], s[50:51], 0, v[180:181]
	s_mov_b32 m0, s27
	s_nop 0
	global_load_lds_dwordx4 v[224:225], off
	s_waitcnt vmcnt(8)
	s_waitcnt lgkmcnt(0)
	s_barrier
	s_setprio 1
	v_mfma_f32_16x16x32_bf16 v[134:137], v[122:125], v[162:165], v[134:137]
	v_mfma_f32_16x16x32_bf16 v[126:129], v[138:141], v[162:165], v[126:129]
	v_mfma_f32_16x16x32_bf16 v[110:113], v[122:125], v[170:173], v[110:113]
	v_mfma_f32_16x16x32_bf16 v[106:109], v[138:141], v[170:173], v[106:109]
	v_mfma_f32_16x16x32_bf16 v[92:95], v[122:125], v[188:191], v[92:95]
	v_mfma_f32_16x16x32_bf16 v[88:91], v[138:141], v[188:191], v[88:91]
	v_mfma_f32_16x16x32_bf16 v[76:79], v[122:125], v[196:199], v[76:79]
	v_mfma_f32_16x16x32_bf16 v[72:75], v[138:141], v[196:199], v[72:75]
	v_mfma_f32_16x16x32_bf16 v[134:137], v[130:133], v[166:169], v[134:137]
	v_mfma_f32_16x16x32_bf16 v[126:129], v[142:145], v[166:169], v[126:129]
	v_mfma_f32_16x16x32_bf16 v[110:113], v[130:133], v[174:177], v[110:113]
	v_mfma_f32_16x16x32_bf16 v[106:109], v[142:145], v[174:177], v[106:109]
	v_mfma_f32_16x16x32_bf16 v[92:95], v[130:133], v[192:195], v[92:95]
	v_mfma_f32_16x16x32_bf16 v[88:91], v[142:145], v[192:195], v[88:91]
	v_mfma_f32_16x16x32_bf16 v[76:79], v[130:133], v[214:217], v[76:79]
	v_mfma_f32_16x16x32_bf16 v[72:75], v[142:145], v[214:217], v[72:75]
	s_setprio 0
	s_setprio 1
	v_mfma_f32_16x16x32_bf16 v[118:121], v[146:149], v[162:165], v[118:121]
	v_mfma_f32_16x16x32_bf16 v[114:117], v[154:157], v[162:165], v[114:117]
	v_mfma_f32_16x16x32_bf16 v[102:105], v[146:149], v[170:173], v[102:105]
	v_mfma_f32_16x16x32_bf16 v[98:101], v[154:157], v[170:173], v[98:101]
	v_mfma_f32_16x16x32_bf16 v[84:87], v[146:149], v[188:191], v[84:87]
	v_mfma_f32_16x16x32_bf16 v[80:83], v[154:157], v[188:191], v[80:83]
	v_mfma_f32_16x16x32_bf16 v[68:71], v[146:149], v[196:199], v[68:71]
	v_mfma_f32_16x16x32_bf16 v[64:67], v[154:157], v[196:199], v[64:67]
	v_mfma_f32_16x16x32_bf16 v[118:121], v[150:153], v[166:169], v[118:121]
	v_mfma_f32_16x16x32_bf16 v[114:117], v[158:161], v[166:169], v[114:117]
	v_mfma_f32_16x16x32_bf16 v[102:105], v[150:153], v[174:177], v[102:105]
	v_mfma_f32_16x16x32_bf16 v[98:101], v[158:161], v[174:177], v[98:101]
	v_mfma_f32_16x16x32_bf16 v[84:87], v[150:153], v[192:195], v[84:87]
	v_mfma_f32_16x16x32_bf16 v[80:83], v[158:161], v[192:195], v[80:83]
	v_mfma_f32_16x16x32_bf16 v[68:71], v[150:153], v[214:217], v[68:71]
	v_mfma_f32_16x16x32_bf16 v[64:67], v[158:161], v[214:217], v[64:67]
	s_setprio 0
	s_barrier
; #define PG8_STAGE(bufoff, gbase, voff) do { _Pragma("unroll") for (int _i = 0; _i < 2; ++_i) \
;         __builtin_amdgcn_global_load_lds((const unsigned*)((const char*)(gbase) + (voff)[_i]), (LAS unsigned*)(lds + (bufoff) + ldsw + _i * 8192), 16, 0, 0); } while (0)
; #define PG8_LDA(dst, b, h) do { _Pragma("unroll") for (int m = 0; m < 4; ++m) _Pragma("unroll") for (int k = 0; k < 2; ++k) dst[m][k] = *(const LAS bf16x8*)(lds + PG8_SA(b, h) + aoff + m * 2048 + k * 1024); } while (0)
; #define PG8_MMA(ai, bj, At, Bt) do { __builtin_amdgcn_s_setprio(1); _Pragma("unroll") for (int m = 0; m < 4; ++m) _Pragma("unroll") for (int n = 0; n < 2; ++n) _Pragma("unroll") for (int k = 0; k < 2; ++k) \
;         acc[ai][bj][m][n] = __builtin_amdgcn_mfma_f32_16x16x32_bf16(Bt[n][k], At[m][k], acc[ai][bj][m][n], 0, 0, 0); __builtin_amdgcn_s_setprio(0); } while (0)
; #define PG8_WAIT_V(n) asm volatile("s_waitcnt vmcnt(" #n ")" ::: "memory")
; #define PG8_WAIT_L(n) asm volatile("s_waitcnt lgkmcnt(" #n ")" ::: "memory")
; #define PG8_BAR __builtin_amdgcn_s_barrier()
; #define PG8_SCHED __builtin_amdgcn_sched_barrier(0)
; template <int K, int LDA, int LDB, int KGRP, bool APERM, class Epi>
; __device__ __forceinline__ void gemm_phase(LAS unsigned char* lds, const Gemm g, const StaticOrder& S, const Epi& E, const int tid) {
;     ...
;             PG8_LDA(At, 1, 1); PG8_STAGE(PG8_SB(1, 0), b3, voffB); PG8_STAGE(PG8_SB(1, 1), b3 + hstepB, voffB); PG8_STAGE(PG8_SA(1, 0), a3, voffA);
;             PG8_WAIT_V(8); PG8_WAIT_L(0); PG8_BAR; PG8_MMA(1, 0, At, B0); PG8_MMA(1, 1, At, B1); PG8_BAR; PG8_SCHED;
;         }
;         if (wr == 0) PG8_BAR;
	s_add_i32 s3, s3, s2
	v_lshl_add_u64 v[200:201], v[200:201], 0, s[38:39]
	s_mov_b32 m0, s3
	ds_read_b128 v[162:165], v213 offset:49152
	ds_read_b128 v[166:169], v213 offset:50176
	ds_read_b128 v[170:173], v213 offset:51200
	ds_read_b128 v[174:177], v213 offset:52224
	ds_read_b128 v[188:191], v213 offset:53248
	ds_read_b128 v[192:195], v213 offset:54272
	ds_read_b128 v[196:199], v213 offset:55296
	ds_read_b128 v[214:217], v213 offset:56320
	global_load_lds_dwordx4 v[200:201], off
	s_add_i32 m0, s3, 0x2000
	s_add_u32 s16, s16, 0x20080
	v_lshl_add_u64 v[200:201], v[218:219], 0, s[38:39]
	s_addc_u32 s17, s17, 0
	s_add_i32 s3, s45, s2
	global_load_lds_dwordx4 v[200:201], off
	v_lshl_add_u64 v[200:201], s[16:17], 0, v[96:97]
	s_mov_b32 m0, s3
	s_nop 0
	global_load_lds_dwordx4 v[200:201], off
	v_lshl_add_u64 v[200:201], s[16:17], 0, v[182:183]
	s_add_i32 m0, s3, 0x2000
	s_nop 0
	global_load_lds_dwordx4 v[200:201], off
	v_lshl_add_u64 v[200:201], v[220:221], 0, s[38:39]
	s_mov_b32 m0, s29
	s_nop 0
	global_load_lds_dwordx4 v[200:201], off
	v_lshl_add_u64 v[200:201], v[222:223], 0, s[38:39]
	s_mov_b32 m0, s30
	s_nop 0
	global_load_lds_dwordx4 v[200:201], off
	s_waitcnt vmcnt(8)
	s_waitcnt lgkmcnt(0)
	s_barrier
	s_setprio 1
	v_mfma_f32_16x16x32_bf16 v[60:63], v[122:125], v[162:165], v[60:63]
	v_mfma_f32_16x16x32_bf16 v[56:59], v[138:141], v[162:165], v[56:59]
	v_mfma_f32_16x16x32_bf16 v[44:47], v[122:125], v[170:173], v[44:47]
	v_mfma_f32_16x16x32_bf16 v[40:43], v[138:141], v[170:173], v[40:43]
	v_mfma_f32_16x16x32_bf16 v[28:31], v[122:125], v[188:191], v[28:31]
	v_mfma_f32_16x16x32_bf16 v[24:27], v[138:141], v[188:191], v[24:27]
	v_mfma_f32_16x16x32_bf16 v[12:15], v[122:125], v[196:199], v[12:15]
	v_mfma_f32_16x16x32_bf16 v[8:11], v[138:141], v[196:199], v[8:11]
	v_mfma_f32_16x16x32_bf16 v[60:63], v[130:133], v[166:169], v[60:63]
	v_mfma_f32_16x16x32_bf16 v[56:59], v[142:145], v[166:169], v[56:59]
	v_mfma_f32_16x16x32_bf16 v[44:47], v[130:133], v[174:177], v[44:47]
	v_mfma_f32_16x16x32_bf16 v[40:43], v[142:145], v[174:177], v[40:43]
	v_mfma_f32_16x16x32_bf16 v[28:31], v[130:133], v[192:195], v[28:31]
	v_mfma_f32_16x16x32_bf16 v[24:27], v[142:145], v[192:195], v[24:27]
	v_mfma_f32_16x16x32_bf16 v[12:15], v[130:133], v[214:217], v[12:15]
	v_mfma_f32_16x16x32_bf16 v[8:11], v[142:145], v[214:217], v[8:11]
	s_setprio 0
	s_setprio 1
	v_mfma_f32_16x16x32_bf16 v[52:55], v[146:149], v[162:165], v[52:55]
	v_mfma_f32_16x16x32_bf16 v[48:51], v[154:157], v[162:165], v[48:51]
	v_mfma_f32_16x16x32_bf16 v[36:39], v[146:149], v[170:173], v[36:39]
	v_mfma_f32_16x16x32_bf16 v[32:35], v[154:157], v[170:173], v[32:35]
	v_mfma_f32_16x16x32_bf16 v[20:23], v[146:149], v[188:191], v[20:23]
	v_mfma_f32_16x16x32_bf16 v[16:19], v[154:157], v[188:191], v[16:19]
	v_mfma_f32_16x16x32_bf16 v[4:7], v[146:149], v[196:199], v[4:7]
	v_mfma_f32_16x16x32_bf16 v[0:3], v[154:157], v[196:199], v[0:3]
	v_mfma_f32_16x16x32_bf16 v[52:55], v[150:153], v[166:169], v[52:55]
	v_mfma_f32_16x16x32_bf16 v[48:51], v[158:161], v[166:169], v[48:51]
	v_mfma_f32_16x16x32_bf16 v[36:39], v[150:153], v[174:177], v[36:39]
	v_mfma_f32_16x16x32_bf16 v[32:35], v[158:161], v[174:177], v[32:35]
	v_mfma_f32_16x16x32_bf16 v[20:23], v[150:153], v[192:195], v[20:23]
	v_mfma_f32_16x16x32_bf16 v[16:19], v[158:161], v[192:195], v[16:19]
	v_mfma_f32_16x16x32_bf16 v[4:7], v[150:153], v[214:217], v[4:7]
	v_mfma_f32_16x16x32_bf16 v[0:3], v[158:161], v[214:217], v[0:3]
	s_setprio 0
	s_barrier
	s_add_i32 s44, s44, 2
	s_add_u32 s8, s8, 0x100
	s_addc_u32 s9, s9, 0
	s_add_u32 s42, s42, 0x100
	s_addc_u32 s43, s43, 0
	s_cmp_gt_u32 s44, 5
	s_cbranch_scc0 .LBB0_893
	s_and_b64 vcc, exec, s[66:67]
	s_cbranch_vccz .LBB0_896
	s_barrier

; #define PG8_STAGE(bufoff, gbase, voff) do { _Pragma("unroll") for (int _i = 0; _i < 2; ++_i) \
;         __builtin_amdgcn_global_load_lds((const unsigned*)((const char*)(gbase) + (voff)[_i]), (LAS unsigned*)(lds + (bufoff) + ldsw + _i * 8192), 16, 0, 0); } while (0)
; #define PG8_LDA(dst, b, h) do { _Pragma("unroll") for (int m = 0; m < 4; ++m) _Pragma("unroll") for (int k = 0; k < 2; ++k) dst[m][k] = *(const LAS bf16x8*)(lds + PG8_SA(b, h) + aoff + m * 2048 + k * 1024); } while (0)
; #define PG8_LDB(dst, b, h) do { _Pragma("unroll") for (int n = 0; n < 2; ++n) _Pragma("unroll") for (int k = 0; k < 2; ++k) dst[n][k] = *(const LAS bf16x8*)(lds + PG8_SB(b, h) + boff + n * 2048 + k * 1024); } while (0)
; #define PG8_MMA(ai, bj, At, Bt) do { __builtin_amdgcn_s_setprio(1); _Pragma("unroll") for (int m = 0; m < 4; ++m) _Pragma("unroll") for (int n = 0; n < 2; ++n) _Pragma("unroll") for (int k = 0; k < 2; ++k) \
;         acc[ai][bj][m][n] = __builtin_amdgcn_mfma_f32_16x16x32_bf16(Bt[n][k], At[m][k], acc[ai][bj][m][n], 0, 0, 0); __builtin_amdgcn_s_setprio(0); } while (0)
; #define PG8_WAIT_V(n) asm volatile("s_waitcnt vmcnt(" #n ")" ::: "memory")
; #define PG8_WAIT_L(n) asm volatile("s_waitcnt lgkmcnt(" #n ")" ::: "memory")
; #define PG8_BAR __builtin_amdgcn_s_barrier()
; #define PG8_SCHED __builtin_amdgcn_sched_barrier(0)
; template <int K, int LDA, int LDB, int KGRP, bool APERM, class Epi>
; __device__ __forceinline__ void gemm_phase(LAS unsigned char* lds, const Gemm g, const StaticOrder& S, const Epi& E, const int tid) {
;     ...
;             const bool last = (t == nt - 2);
;             const char* a1 = cA + (size_t)(t + 1) * kstep;
;             const char* a2 = last ? nA : cA + (size_t)(t + 2) * kstep; const char* b2 = last ? nB : cB + (size_t)(t + 2) * kstep;
;             const char* a3 = a2 + kstep; const char* b3 = b2 + kstep;
;             PG8_LDB(B0, 0, 0); PG8_LDB(B1, 0, 1); PG8_SCHED; PG8_LDA(At, 0, 0); PG8_STAGE(PG8_SA(1, 1), a1 + hstepA, voffA);
;             PG8_WAIT_V(8); PG8_WAIT_L(0); PG8_BAR; PG8_MMA(0, 0, At, B0); PG8_MMA(0, 1, At, B1); PG8_BAR; PG8_SCHED;
;             PG8_LDA(At, 0, 1); PG8_STAGE(PG8_SB(0, 0), b2, voffB); PG8_STAGE(PG8_SB(0, 1), b2 + hstepB, voffB); PG8_STAGE(PG8_SA(0, 0), a2, voffA);
;             PG8_WAIT_V(8); PG8_WAIT_L(0); PG8_BAR; PG8_MMA(1, 0, At, B0); PG8_MMA(1, 1, At, B1); PG8_BAR; PG8_SCHED;
.LBB0_1066:
	s_add_u32 s14, s96, 0x100
	s_addc_u32 s15, s97, 0
	s_add_i32 s31, 0, 0x10000
	s_cmp_eq_u32 s3, 28
	s_cselect_b32 vcc_hi, s91, s15
	s_cselect_b32 vcc_lo, s93, s14
	s_cselect_b32 s35, s53, s69
	s_cselect_b32 s34, s51, s68
	s_add_i32 s37, 0, 0x14000
	v_add_u32_e32 v36, s31, v253
	v_add_u32_e32 v60, s37, v253
	ds_read_b128 v[24:27], v36
	ds_read_b128 v[28:31], v36 offset:1024
	ds_read_b128 v[32:35], v36 offset:2048
	ds_read_b128 v[36:39], v36 offset:3072
	ds_read_b128 v[40:43], v60
	ds_read_b128 v[48:51], v60 offset:1024
	ds_read_b128 v[52:55], v60 offset:2048
	ds_read_b128 v[60:63], v60 offset:3072
	v_lshl_add_u64 v[158:159], s[96:97], 0, v[218:219]
	s_add_i32 m0, s61, 0xc000
	ds_read_b128 v[106:109], v247
	ds_read_b128 v[126:129], v247 offset:1024
	ds_read_b128 v[130:133], v247 offset:2048
	ds_read_b128 v[134:137], v247 offset:3072
	ds_read_b128 v[138:141], v247 offset:4096
	ds_read_b128 v[142:145], v247 offset:5120
	ds_read_b128 v[146:149], v247 offset:6144
	ds_read_b128 v[154:157], v247 offset:7168
	global_load_lds_dwordx4 v[158:159], off
	v_lshl_add_u64 v[158:159], s[96:97], 0, v[220:221]
	s_add_i32 m0, s61, 0xe000
	s_nop 0
	global_load_lds_dwordx4 v[158:159], off
	s_waitcnt vmcnt(8)
	s_waitcnt lgkmcnt(0)
	s_barrier
	s_setprio 1
	v_mfma_f32_16x16x32_bf16 v[84:87], v[32:35], v[106:109], v[84:87]
	v_mfma_f32_16x16x32_bf16 v[68:71], v[32:35], v[130:133], v[68:71]
	v_mfma_f32_16x16x32_bf16 v[162:165], v[24:27], v[138:141], v[162:165]
	v_mfma_f32_16x16x32_bf16 v[56:59], v[32:35], v[138:141], v[56:59]
	v_mfma_f32_16x16x32_bf16 v[122:125], v[24:27], v[146:149], v[122:125]
	v_mfma_f32_16x16x32_bf16 v[20:23], v[32:35], v[146:149], v[20:23]
	v_mfma_f32_16x16x32_bf16 v[158:161], v[24:27], v[106:109], v[190:193]
	v_mfma_f32_16x16x32_bf16 v[84:87], v[36:39], v[126:129], v[84:87]
	v_mfma_f32_16x16x32_bf16 v[166:169], v[24:27], v[130:133], v[174:177]
	v_mfma_f32_16x16x32_bf16 v[68:71], v[36:39], v[134:137], v[68:71]
	v_mfma_f32_16x16x32_bf16 v[162:165], v[28:31], v[142:145], v[162:165]
	v_mfma_f32_16x16x32_bf16 v[56:59], v[36:39], v[142:145], v[56:59]
	v_mfma_f32_16x16x32_bf16 v[122:125], v[28:31], v[154:157], v[122:125]
	v_mfma_f32_16x16x32_bf16 v[20:23], v[36:39], v[154:157], v[20:23]
	v_mfma_f32_16x16x32_bf16 v[158:161], v[28:31], v[126:129], v[158:161]
	v_mfma_f32_16x16x32_bf16 v[166:169], v[28:31], v[134:137], v[166:169]
	s_setprio 0
	s_setprio 1
	v_mfma_f32_16x16x32_bf16 v[174:177], v[40:43], v[106:109], v[178:181]
	v_mfma_f32_16x16x32_bf16 v[76:79], v[52:55], v[106:109], v[76:79]
	v_mfma_f32_16x16x32_bf16 v[64:67], v[52:55], v[130:133], v[64:67]
	v_mfma_f32_16x16x32_bf16 v[44:47], v[52:55], v[138:141], v[44:47]
	v_mfma_f32_16x16x32_bf16 v[118:121], v[40:43], v[146:149], v[118:121]
	v_mfma_f32_16x16x32_bf16 v[16:19], v[52:55], v[146:149], v[16:19]
	v_mfma_f32_16x16x32_bf16 v[178:181], v[48:51], v[126:129], v[174:177]
	v_mfma_f32_16x16x32_bf16 v[76:79], v[60:63], v[126:129], v[76:79]
	v_mfma_f32_16x16x32_bf16 v[106:109], v[40:43], v[130:133], v[170:173]
	v_mfma_f32_16x16x32_bf16 v[64:67], v[60:63], v[134:137], v[64:67]
	v_mfma_f32_16x16x32_bf16 v[126:129], v[40:43], v[138:141], v[150:153]
	v_mfma_f32_16x16x32_bf16 v[44:47], v[60:63], v[142:145], v[44:47]
	v_mfma_f32_16x16x32_bf16 v[118:121], v[48:51], v[154:157], v[118:121]
	v_mfma_f32_16x16x32_bf16 v[16:19], v[60:63], v[154:157], v[16:19]
	v_mfma_f32_16x16x32_bf16 v[106:109], v[48:51], v[134:137], v[106:109]
	v_mfma_f32_16x16x32_bf16 v[126:129], v[48:51], v[142:145], v[126:129]
	s_setprio 0
	s_barrier
	s_add_i32 s31, s31, s24
	v_lshl_add_u64 v[230:231], s[34:35], 0, v[212:213]
	s_mov_b32 m0, s31
	ds_read_b128 v[130:133], v247 offset:16384
	ds_read_b128 v[134:137], v247 offset:17408
	ds_read_b128 v[138:141], v247 offset:18432
	ds_read_b128 v[142:145], v247 offset:19456
	ds_read_b128 v[146:149], v247 offset:20480
	ds_read_b128 v[150:153], v247 offset:21504
	ds_read_b128 v[154:157], v247 offset:22528
	ds_read_b128 v[170:173], v247 offset:23552
	global_load_lds_dwordx4 v[230:231], off
	s_add_i32 m0, s31, 0x2000
	s_add_u32 s96, s34, 0x80000
	v_lshl_add_u64 v[232:233], s[34:35], 0, v[216:217]
	s_addc_u32 s97, s35, 0
	s_add_i32 s31, s37, s24
	global_load_lds_dwordx4 v[232:233], off
	v_lshl_add_u64 v[174:175], s[96:97], 0, v[212:213]
	s_mov_b32 m0, s31
	v_lshl_add_u64 v[234:235], vcc, 0, v[210:211]
	global_load_lds_dwordx4 v[174:175], off
	v_lshl_add_u64 v[174:175], s[96:97], 0, v[216:217]
	s_add_i32 m0, s31, 0x2000
	v_lshl_add_u64 v[236:237], vcc, 0, v[214:215]
	global_load_lds_dwordx4 v[174:175], off
	s_mov_b32 m0, s61
	s_nop 0
	global_load_lds_dwordx4 v[234:235], off
	s_mov_b32 m0, s95
	s_nop 0
	global_load_lds_dwordx4 v[236:237], off
	s_waitcnt vmcnt(8)
	s_waitcnt lgkmcnt(0)
	s_barrier
; #define PG8_STAGE(bufoff, gbase, voff) do { _Pragma("unroll") for (int _i = 0; _i < 2; ++_i) \
;         __builtin_amdgcn_global_load_lds((const unsigned*)((const char*)(gbase) + (voff)[_i]), (LAS unsigned*)(lds + (bufoff) + ldsw + _i * 8192), 16, 0, 0); } while (0)
; #define PG8_LDA(dst, b, h) do { _Pragma("unroll") for (int m = 0; m < 4; ++m) _Pragma("unroll") for (int k = 0; k < 2; ++k) dst[m][k] = *(const LAS bf16x8*)(lds + PG8_SA(b, h) + aoff + m * 2048 + k * 1024); } while (0)
; #define PG8_LDB(dst, b, h) do { _Pragma("unroll") for (int n = 0; n < 2; ++n) _Pragma("unroll") for (int k = 0; k < 2; ++k) dst[n][k] = *(const LAS bf16x8*)(lds + PG8_SB(b, h) + boff + n * 2048 + k * 1024); } while (0)
; #define PG8_MMA(ai, bj, At, Bt) do { __builtin_amdgcn_s_setprio(1); _Pragma("unroll") for (int m = 0; m < 4; ++m) _Pragma("unroll") for (int n = 0; n < 2; ++n) _Pragma("unroll") for (int k = 0; k < 2; ++k) \
;         acc[ai][bj][m][n] = __builtin_amdgcn_mfma_f32_16x16x32_bf16(Bt[n][k], At[m][k], acc[ai][bj][m][n], 0, 0, 0); __builtin_amdgcn_s_setprio(0); } while (0)
; #define PG8_WAIT_V(n) asm volatile("s_waitcnt vmcnt(" #n ")" ::: "memory")
; #define PG8_WAIT_L(n) asm volatile("s_waitcnt lgkmcnt(" #n ")" ::: "memory")
; #define PG8_BAR __builtin_amdgcn_s_barrier()
; #define PG8_SCHED __builtin_amdgcn_sched_barrier(0)
; template <int K, int LDA, int LDB, int KGRP, bool APERM, class Epi>
; __device__ __forceinline__ void gemm_phase(LAS unsigned char* lds, const Gemm g, const StaticOrder& S, const Epi& E, const int tid) {
;     ...
;             PG8_WAIT_V(8); PG8_WAIT_L(0); PG8_BAR; PG8_MMA(1, 0, At, B0); PG8_MMA(1, 1, At, B1); PG8_BAR; PG8_SCHED;
;             PG8_LDB(B0, 1, 0); PG8_LDB(B1, 1, 1); PG8_SCHED; PG8_LDA(At, 1, 0); PG8_STAGE(PG8_SA(0, 1), a2 + hstepA, voffA);
;             PG8_WAIT_V(8); PG8_WAIT_L(0); PG8_BAR; PG8_MMA(0, 0, At, B0); PG8_MMA(0, 1, At, B1); PG8_BAR; PG8_SCHED;
	s_setprio 1
	v_mfma_f32_16x16x32_bf16 v[114:117], v[24:27], v[130:133], v[114:117]
	v_mfma_f32_16x16x32_bf16 v[12:15], v[32:35], v[130:133], v[12:15]
	v_mfma_f32_16x16x32_bf16 v[102:105], v[24:27], v[138:141], v[102:105]
	v_mfma_f32_16x16x32_bf16 v[4:7], v[32:35], v[138:141], v[4:7]
	v_mfma_f32_16x16x32_bf16 v[174:177], v[24:27], v[146:149], v[198:201]
	v_mfma_f32_16x16x32_bf16 v[92:95], v[32:35], v[146:149], v[92:95]
	v_mfma_f32_16x16x32_bf16 v[24:27], v[24:27], v[154:157], v[194:197]
	v_mfma_f32_16x16x32_bf16 v[114:117], v[28:31], v[134:137], v[114:117]
	v_mfma_f32_16x16x32_bf16 v[12:15], v[36:39], v[134:137], v[12:15]
	v_mfma_f32_16x16x32_bf16 v[102:105], v[28:31], v[142:145], v[102:105]
	v_mfma_f32_16x16x32_bf16 v[4:7], v[36:39], v[142:145], v[4:7]
	v_mfma_f32_16x16x32_bf16 v[198:201], v[28:31], v[150:153], v[174:177]
	v_mfma_f32_16x16x32_bf16 v[92:95], v[36:39], v[150:153], v[92:95]
	v_mfma_f32_16x16x32_bf16 v[24:27], v[28:31], v[170:173], v[24:27]
	v_mfma_f32_16x16x32_bf16 v[28:31], v[32:35], v[154:157], v[88:91]
	v_mfma_f32_16x16x32_bf16 v[28:31], v[36:39], v[170:173], v[28:31]
	s_setprio 0
	s_setprio 1
	v_mfma_f32_16x16x32_bf16 v[32:35], v[40:43], v[130:133], v[110:113]
	v_mfma_f32_16x16x32_bf16 v[8:11], v[52:55], v[130:133], v[8:11]
	v_mfma_f32_16x16x32_bf16 v[36:39], v[40:43], v[138:141], v[98:101]
	v_mfma_f32_16x16x32_bf16 v[0:3], v[52:55], v[138:141], v[0:3]
	v_mfma_f32_16x16x32_bf16 v[88:91], v[40:43], v[146:149], v[186:189]
	v_mfma_f32_16x16x32_bf16 v[80:83], v[52:55], v[146:149], v[80:83]
	v_mfma_f32_16x16x32_bf16 v[40:43], v[40:43], v[154:157], v[182:185]
	v_mfma_f32_16x16x32_bf16 v[32:35], v[48:51], v[134:137], v[32:35]
	v_mfma_f32_16x16x32_bf16 v[8:11], v[60:63], v[134:137], v[8:11]
	v_mfma_f32_16x16x32_bf16 v[36:39], v[48:51], v[142:145], v[36:39]
	v_mfma_f32_16x16x32_bf16 v[0:3], v[60:63], v[142:145], v[0:3]
	v_mfma_f32_16x16x32_bf16 v[130:133], v[48:51], v[150:153], v[88:91]
	v_mfma_f32_16x16x32_bf16 v[80:83], v[60:63], v[150:153], v[80:83]
	v_mfma_f32_16x16x32_bf16 v[40:43], v[48:51], v[170:173], v[40:43]
	v_mfma_f32_16x16x32_bf16 v[48:51], v[52:55], v[154:157], v[72:75]
	v_mfma_f32_16x16x32_bf16 v[48:51], v[60:63], v[170:173], v[48:51]
	s_setprio 0
	s_barrier
	s_add_i32 s31, 0, 0x18000
	s_add_i32 s37, 0, 0x1c000
	v_add_u32_e32 v88, s31, v253
	v_add_u32_e32 v98, s37, v253
	ds_read_b128 v[52:55], v88
	ds_read_b128 v[60:63], v88 offset:1024
	ds_read_b128 v[72:75], v88 offset:2048
	ds_read_b128 v[88:91], v88 offset:3072
	ds_read_b128 v[134:137], v98
	ds_read_b128 v[138:141], v98 offset:1024
	ds_read_b128 v[142:145], v98 offset:2048
	ds_read_b128 v[146:149], v98 offset:3072
	s_add_u32 s96, vcc_lo, 0x4000
	s_addc_u32 s97, vcc_hi, 0
	s_mov_b32 m0, s48
	v_lshl_add_u64 v[170:171], s[96:97], 0, v[210:211]
	ds_read_b128 v[98:101], v247 offset:32768
	ds_read_b128 v[110:113], v247 offset:33792
	ds_read_b128 v[150:153], v247 offset:34816
	ds_read_b128 v[154:157], v247 offset:35840
	ds_read_b128 v[182:185], v247 offset:36864
	ds_read_b128 v[186:189], v247 offset:37888
	ds_read_b128 v[194:197], v247 offset:38912
	ds_read_b128 v[222:225], v247 offset:39936
	global_load_lds_dwordx4 v[170:171], off
	v_lshl_add_u64 v[170:171], s[96:97], 0, v[214:215]
	s_mov_b32 m0, s23
	s_nop 0
	global_load_lds_dwordx4 v[170:171], off
	s_waitcnt vmcnt(8)
	s_waitcnt lgkmcnt(0)
	s_barrier
	s_setprio 1
	v_mfma_f32_16x16x32_bf16 v[158:161], v[52:55], v[98:101], v[158:161]
	v_mfma_f32_16x16x32_bf16 v[190:193], v[60:63], v[110:113], v[158:161]
	v_mfma_f32_16x16x32_bf16 v[158:161], v[52:55], v[150:153], v[166:169]
	v_mfma_f32_16x16x32_bf16 v[84:87], v[72:75], v[98:101], v[84:87]
	v_mfma_f32_16x16x32_bf16 v[174:177], v[60:63], v[154:157], v[158:161]
	v_mfma_f32_16x16x32_bf16 v[68:71], v[72:75], v[150:153], v[68:71]
	v_mfma_f32_16x16x32_bf16 v[158:161], v[52:55], v[182:185], v[162:165]
	v_mfma_f32_16x16x32_bf16 v[56:59], v[72:75], v[182:185], v[56:59]
	v_mfma_f32_16x16x32_bf16 v[122:125], v[52:55], v[194:197], v[122:125]
	v_mfma_f32_16x16x32_bf16 v[20:23], v[72:75], v[194:197], v[20:23]
	v_mfma_f32_16x16x32_bf16 v[84:87], v[88:91], v[110:113], v[84:87]
	v_mfma_f32_16x16x32_bf16 v[68:71], v[88:91], v[154:157], v[68:71]
	v_mfma_f32_16x16x32_bf16 v[162:165], v[60:63], v[186:189], v[158:161]
	v_mfma_f32_16x16x32_bf16 v[56:59], v[88:91], v[186:189], v[56:59]
	v_mfma_f32_16x16x32_bf16 v[122:125], v[60:63], v[222:225], v[122:125]
	v_mfma_f32_16x16x32_bf16 v[20:23], v[88:91], v[222:225], v[20:23]
	s_setprio 0
	s_setprio 1
	v_mfma_f32_16x16x32_bf16 v[158:161], v[134:137], v[98:101], v[178:181]
	v_mfma_f32_16x16x32_bf16 v[76:79], v[142:145], v[98:101], v[76:79]
	v_mfma_f32_16x16x32_bf16 v[98:101], v[134:137], v[150:153], v[106:109]
	v_mfma_f32_16x16x32_bf16 v[170:173], v[138:141], v[154:157], v[98:101]
	v_mfma_f32_16x16x32_bf16 v[98:101], v[134:137], v[182:185], v[126:129]
	v_mfma_f32_16x16x32_bf16 v[64:67], v[142:145], v[150:153], v[64:67]
	v_mfma_f32_16x16x32_bf16 v[150:153], v[138:141], v[186:189], v[98:101]
	v_mfma_f32_16x16x32_bf16 v[44:47], v[142:145], v[182:185], v[44:47]
	v_mfma_f32_16x16x32_bf16 v[98:101], v[134:137], v[194:197], v[118:121]
	v_mfma_f32_16x16x32_bf16 v[16:19], v[142:145], v[194:197], v[16:19]
	v_mfma_f32_16x16x32_bf16 v[178:181], v[138:141], v[110:113], v[158:161]
	v_mfma_f32_16x16x32_bf16 v[76:79], v[146:149], v[110:113], v[76:79]
	v_mfma_f32_16x16x32_bf16 v[64:67], v[146:149], v[154:157], v[64:67]
	v_mfma_f32_16x16x32_bf16 v[44:47], v[146:149], v[186:189], v[44:47]
	v_mfma_f32_16x16x32_bf16 v[118:121], v[138:141], v[222:225], v[98:101]
	v_mfma_f32_16x16x32_bf16 v[16:19], v[146:149], v[222:225], v[16:19]
	s_setprio 0
	s_barrier
; #define PG8_STAGE(bufoff, gbase, voff) do { _Pragma("unroll") for (int _i = 0; _i < 2; ++_i) \
;         __builtin_amdgcn_global_load_lds((const unsigned*)((const char*)(gbase) + (voff)[_i]), (LAS unsigned*)(lds + (bufoff) + ldsw + _i * 8192), 16, 0, 0); } while (0)
; #define PG8_LDA(dst, b, h) do { _Pragma("unroll") for (int m = 0; m < 4; ++m) _Pragma("unroll") for (int k = 0; k < 2; ++k) dst[m][k] = *(const LAS bf16x8*)(lds + PG8_SA(b, h) + aoff + m * 2048 + k * 1024); } while (0)
; #define PG8_MMA(ai, bj, At, Bt) do { __builtin_amdgcn_s_setprio(1); _Pragma("unroll") for (int m = 0; m < 4; ++m) _Pragma("unroll") for (int n = 0; n < 2; ++n) _Pragma("unroll") for (int k = 0; k < 2; ++k) \
;         acc[ai][bj][m][n] = __builtin_amdgcn_mfma_f32_16x16x32_bf16(Bt[n][k], At[m][k], acc[ai][bj][m][n], 0, 0, 0); __builtin_amdgcn_s_setprio(0); } while (0)
; #define PG8_WAIT_V(n) asm volatile("s_waitcnt vmcnt(" #n ")" ::: "memory")
; #define PG8_WAIT_L(n) asm volatile("s_waitcnt lgkmcnt(" #n ")" ::: "memory")
; #define PG8_BAR __builtin_amdgcn_s_barrier()
; #define PG8_SCHED __builtin_amdgcn_sched_barrier(0)
; template <int K, int LDA, int LDB, int KGRP, bool APERM, class Epi>
; __device__ __forceinline__ void gemm_phase(LAS unsigned char* lds, const Gemm g, const StaticOrder& S, const Epi& E, const int tid) {
;     ...
;             PG8_LDA(At, 1, 1); PG8_STAGE(PG8_SB(1, 0), b3, voffB); PG8_STAGE(PG8_SB(1, 1), b3 + hstepB, voffB); PG8_STAGE(PG8_SA(1, 0), a3, voffA);
;             PG8_WAIT_V(8); PG8_WAIT_L(0); PG8_BAR; PG8_MMA(1, 0, At, B0); PG8_MMA(1, 1, At, B1); PG8_BAR; PG8_SCHED;
;         }
;         if (wr == 0) PG8_BAR;
	s_add_i32 s31, s31, s24
	v_lshl_add_u64 v[110:111], v[230:231], 0, s[38:39]
	s_mov_b32 m0, s31
	ds_read_b128 v[98:101], v247 offset:49152
	ds_read_b128 v[106:109], v247 offset:50176
	ds_read_b128 v[126:129], v247 offset:51200
	ds_read_b128 v[154:157], v247 offset:52224
	ds_read_b128 v[158:161], v247 offset:53248
	ds_read_b128 v[166:169], v247 offset:54272
	ds_read_b128 v[222:225], v247 offset:55296
	ds_read_b128 v[226:229], v247 offset:56320
	global_load_lds_dwordx4 v[110:111], off
	s_add_i32 m0, s31, 0x2000
	s_add_u32 s34, s34, 0x80080
	v_lshl_add_u64 v[110:111], v[232:233], 0, s[38:39]
	s_addc_u32 s35, s35, 0
	s_add_i32 s31, s37, s24
	global_load_lds_dwordx4 v[110:111], off
	v_lshl_add_u64 v[110:111], s[34:35], 0, v[212:213]
	s_mov_b32 m0, s31
	s_nop 0
	global_load_lds_dwordx4 v[110:111], off
	v_lshl_add_u64 v[110:111], s[34:35], 0, v[216:217]
	s_add_i32 m0, s31, 0x2000
	s_nop 0
	global_load_lds_dwordx4 v[110:111], off
	v_lshl_add_u64 v[110:111], v[234:235], 0, s[38:39]
	s_mov_b32 m0, s42
	s_nop 0
	global_load_lds_dwordx4 v[110:111], off
	v_lshl_add_u64 v[110:111], v[236:237], 0, s[38:39]
	s_mov_b32 m0, s26
	s_nop 0
	global_load_lds_dwordx4 v[110:111], off
	s_waitcnt vmcnt(8)
	s_waitcnt lgkmcnt(0)
	s_barrier
	s_setprio 1
	v_mfma_f32_16x16x32_bf16 v[110:113], v[52:55], v[98:101], v[114:117]
	v_mfma_f32_16x16x32_bf16 v[24:27], v[52:55], v[222:225], v[24:27]
	v_mfma_f32_16x16x32_bf16 v[114:117], v[60:63], v[106:109], v[110:113]
	v_mfma_f32_16x16x32_bf16 v[12:15], v[72:75], v[98:101], v[12:15]
	v_mfma_f32_16x16x32_bf16 v[102:105], v[52:55], v[126:129], v[102:105]
	v_mfma_f32_16x16x32_bf16 v[4:7], v[72:75], v[126:129], v[4:7]
	v_mfma_f32_16x16x32_bf16 v[110:113], v[52:55], v[158:161], v[198:201]
	v_mfma_f32_16x16x32_bf16 v[92:95], v[72:75], v[158:161], v[92:95]
	v_mfma_f32_16x16x32_bf16 v[194:197], v[60:63], v[226:229], v[24:27]
	v_mfma_f32_16x16x32_bf16 v[24:27], v[72:75], v[222:225], v[28:31]
	v_mfma_f32_16x16x32_bf16 v[12:15], v[88:91], v[106:109], v[12:15]
	v_mfma_f32_16x16x32_bf16 v[102:105], v[60:63], v[154:157], v[102:105]
	v_mfma_f32_16x16x32_bf16 v[4:7], v[88:91], v[154:157], v[4:7]
	v_mfma_f32_16x16x32_bf16 v[198:201], v[60:63], v[166:169], v[110:113]
	v_mfma_f32_16x16x32_bf16 v[92:95], v[88:91], v[166:169], v[92:95]
	v_mfma_f32_16x16x32_bf16 v[88:91], v[88:91], v[226:229], v[24:27]
	s_setprio 0
	s_setprio 1
	v_mfma_f32_16x16x32_bf16 v[24:27], v[134:137], v[98:101], v[32:35]
	v_mfma_f32_16x16x32_bf16 v[110:113], v[138:141], v[106:109], v[24:27]
	v_mfma_f32_16x16x32_bf16 v[24:27], v[134:137], v[126:129], v[36:39]
	v_mfma_f32_16x16x32_bf16 v[8:11], v[142:145], v[98:101], v[8:11]
	v_mfma_f32_16x16x32_bf16 v[98:101], v[138:141], v[154:157], v[24:27]
	v_mfma_f32_16x16x32_bf16 v[24:27], v[134:137], v[158:161], v[130:133]
	v_mfma_f32_16x16x32_bf16 v[186:189], v[138:141], v[166:169], v[24:27]
	v_mfma_f32_16x16x32_bf16 v[24:27], v[142:145], v[158:161], v[80:83]
	v_mfma_f32_16x16x32_bf16 v[80:83], v[146:149], v[166:169], v[24:27]
	v_mfma_f32_16x16x32_bf16 v[24:27], v[134:137], v[222:225], v[40:43]
	v_mfma_f32_16x16x32_bf16 v[0:3], v[142:145], v[126:129], v[0:3]
	v_mfma_f32_16x16x32_bf16 v[182:185], v[138:141], v[226:229], v[24:27]
	v_mfma_f32_16x16x32_bf16 v[24:27], v[142:145], v[222:225], v[48:51]
	v_mfma_f32_16x16x32_bf16 v[8:11], v[146:149], v[106:109], v[8:11]
	v_mfma_f32_16x16x32_bf16 v[0:3], v[146:149], v[154:157], v[0:3]
	v_mfma_f32_16x16x32_bf16 v[72:75], v[146:149], v[226:229], v[24:27]
	s_setprio 0
	s_barrier
	s_add_i32 s3, s3, 2
	s_add_u32 s68, s68, 0x100
	s_addc_u32 s69, s69, 0
	s_cmp_gt_u32 s3, 29
	s_mov_b64 s[96:97], s[14:15]
	s_cbranch_scc0 .LBB0_1066
	s_and_b64 vcc, exec, s[70:71]
	s_cbranch_vccz .LBB0_1069
	s_barrier

; #define PG8_STAGE(bufoff, gbase, voff) do { _Pragma("unroll") for (int _i = 0; _i < 2; ++_i) \
;         __builtin_amdgcn_global_load_lds((const unsigned*)((const char*)(gbase) + (voff)[_i]), (LAS unsigned*)(lds + (bufoff) + ldsw + _i * 8192), 16, 0, 0); } while (0)
; #define PG8_LDA(dst, b, h) do { _Pragma("unroll") for (int m = 0; m < 4; ++m) _Pragma("unroll") for (int k = 0; k < 2; ++k) dst[m][k] = *(const LAS bf16x8*)(lds + PG8_SA(b, h) + aoff + m * 2048 + k * 1024); } while (0)
; #define PG8_LDB(dst, b, h) do { _Pragma("unroll") for (int n = 0; n < 2; ++n) _Pragma("unroll") for (int k = 0; k < 2; ++k) dst[n][k] = *(const LAS bf16x8*)(lds + PG8_SB(b, h) + boff + n * 2048 + k * 1024); } while (0)
; #define PG8_MMA(ai, bj, At, Bt) do { __builtin_amdgcn_s_setprio(1); _Pragma("unroll") for (int m = 0; m < 4; ++m) _Pragma("unroll") for (int n = 0; n < 2; ++n) _Pragma("unroll") for (int k = 0; k < 2; ++k) \
;         acc[ai][bj][m][n] = __builtin_amdgcn_mfma_f32_16x16x32_bf16(Bt[n][k], At[m][k], acc[ai][bj][m][n], 0, 0, 0); __builtin_amdgcn_s_setprio(0); } while (0)
; #define PG8_WAIT_V(n) asm volatile("s_waitcnt vmcnt(" #n ")" ::: "memory")
; #define PG8_WAIT_L(n) asm volatile("s_waitcnt lgkmcnt(" #n ")" ::: "memory")
; #define PG8_BAR __builtin_amdgcn_s_barrier()
; #define PG8_SCHED __builtin_amdgcn_sched_barrier(0)
; template <int K, int LDA, int LDB, int KGRP, bool APERM, class Epi>
; __device__ __forceinline__ void gemm_phase(LAS unsigned char* lds, const Gemm g, const StaticOrder& S, const Epi& E, const int tid) {
;     ...
;             const bool last = (t == nt - 2);
;             const char* a1 = cA + (size_t)(t + 1) * kstep;
;             const char* a2 = last ? nA : cA + (size_t)(t + 2) * kstep; const char* b2 = last ? nB : cB + (size_t)(t + 2) * kstep;
;             const char* a3 = a2 + kstep; const char* b3 = b2 + kstep;
;             PG8_LDB(B0, 0, 0); PG8_LDB(B1, 0, 1); PG8_SCHED; PG8_LDA(At, 0, 0); PG8_STAGE(PG8_SA(1, 1), a1 + hstepA, voffA);
;             PG8_WAIT_V(8); PG8_WAIT_L(0); PG8_BAR; PG8_MMA(0, 0, At, B0); PG8_MMA(0, 1, At, B1); PG8_BAR; PG8_SCHED;
;             PG8_LDA(At, 0, 1); PG8_STAGE(PG8_SB(0, 0), b2, voffB); PG8_STAGE(PG8_SB(0, 1), b2 + hstepB, voffB); PG8_STAGE(PG8_SA(0, 0), a2, voffA);
;             PG8_WAIT_V(8); PG8_WAIT_L(0); PG8_BAR; PG8_MMA(1, 0, At, B0); PG8_MMA(1, 1, At, B1); PG8_BAR; PG8_SCHED;
.LBB0_1370:
	s_add_u32 s8, s54, 0x100
	s_addc_u32 s9, s55, 0
	s_add_i32 s48, 0, 0x10000
	s_cmpk_eq_i32 s45, 0x54
	s_cselect_b32 s61, s53, s9
	s_cselect_b32 s60, s52, s8
	v_add_u32_e32 v153, s48, v150
	s_cselect_b32 s17, s59, s44
	s_cselect_b32 s16, s58, s3
	s_add_i32 s64, 0, 0x14000
	ds_read_b128 v[140:143], v153
	ds_read_b128 v[144:147], v153 offset:1024
	ds_read_b128 v[154:157], v153 offset:2048
	ds_read_b128 v[158:161], v153 offset:3072
	v_add_u32_e32 v153, s64, v150
	ds_read_b128 v[162:165], v153
	ds_read_b128 v[166:169], v153 offset:1024
	ds_read_b128 v[170:173], v153 offset:2048
	ds_read_b128 v[174:177], v153 offset:3072
	v_lshl_add_u64 v[202:203], s[54:55], 0, v[136:137]
	s_add_i32 m0, s24, 0xc000
	ds_read_b128 v[178:181], v152
	ds_read_b128 v[182:185], v152 offset:1024
	ds_read_b128 v[186:189], v152 offset:2048
	ds_read_b128 v[190:193], v152 offset:3072
	ds_read_b128 v[194:197], v152 offset:4096
	ds_read_b128 v[198:201], v152 offset:5120
	ds_read_b128 v[210:213], v152 offset:6144
	ds_read_b128 v[214:217], v152 offset:7168
	global_load_lds_dwordx4 v[202:203], off
	v_lshl_add_u64 v[202:203], s[54:55], 0, v[138:139]
	s_add_i32 m0, s24, 0xe000
	s_nop 0
	global_load_lds_dwordx4 v[202:203], off
	s_waitcnt vmcnt(8)
	s_waitcnt lgkmcnt(0)
	s_barrier
	s_setprio 1
	v_mfma_f32_16x16x32_bf16 v[114:117], v[140:143], v[178:181], v[114:117]
	v_mfma_f32_16x16x32_bf16 v[118:121], v[154:157], v[178:181], v[118:121]
	v_mfma_f32_16x16x32_bf16 v[98:101], v[140:143], v[186:189], v[98:101]
	v_mfma_f32_16x16x32_bf16 v[102:105], v[154:157], v[186:189], v[102:105]
	v_mfma_f32_16x16x32_bf16 v[80:83], v[140:143], v[194:197], v[80:83]
	v_mfma_f32_16x16x32_bf16 v[84:87], v[154:157], v[194:197], v[84:87]
	v_mfma_f32_16x16x32_bf16 v[48:51], v[140:143], v[210:213], v[48:51]
	v_mfma_f32_16x16x32_bf16 v[52:55], v[154:157], v[210:213], v[52:55]
	v_mfma_f32_16x16x32_bf16 v[114:117], v[144:147], v[182:185], v[114:117]
	v_mfma_f32_16x16x32_bf16 v[118:121], v[158:161], v[182:185], v[118:121]
	v_mfma_f32_16x16x32_bf16 v[98:101], v[144:147], v[190:193], v[98:101]
	v_mfma_f32_16x16x32_bf16 v[102:105], v[158:161], v[190:193], v[102:105]
	v_mfma_f32_16x16x32_bf16 v[80:83], v[144:147], v[198:201], v[80:83]
	v_mfma_f32_16x16x32_bf16 v[84:87], v[158:161], v[198:201], v[84:87]
	v_mfma_f32_16x16x32_bf16 v[48:51], v[144:147], v[214:217], v[48:51]
	v_mfma_f32_16x16x32_bf16 v[52:55], v[158:161], v[214:217], v[52:55]
	s_setprio 0
	s_setprio 1
	v_mfma_f32_16x16x32_bf16 v[122:125], v[162:165], v[178:181], v[122:125]
	v_mfma_f32_16x16x32_bf16 v[126:129], v[170:173], v[178:181], v[126:129]
	v_mfma_f32_16x16x32_bf16 v[106:109], v[162:165], v[186:189], v[106:109]
	v_mfma_f32_16x16x32_bf16 v[110:113], v[170:173], v[186:189], v[110:113]
	v_mfma_f32_16x16x32_bf16 v[88:91], v[162:165], v[194:197], v[88:91]
	v_mfma_f32_16x16x32_bf16 v[92:95], v[170:173], v[194:197], v[92:95]
	v_mfma_f32_16x16x32_bf16 v[68:71], v[162:165], v[210:213], v[68:71]
	v_mfma_f32_16x16x32_bf16 v[76:79], v[170:173], v[210:213], v[76:79]
	v_mfma_f32_16x16x32_bf16 v[122:125], v[166:169], v[182:185], v[122:125]
	v_mfma_f32_16x16x32_bf16 v[126:129], v[174:177], v[182:185], v[126:129]
	v_mfma_f32_16x16x32_bf16 v[106:109], v[166:169], v[190:193], v[106:109]
	v_mfma_f32_16x16x32_bf16 v[110:113], v[174:177], v[190:193], v[110:113]
	v_mfma_f32_16x16x32_bf16 v[88:91], v[166:169], v[198:201], v[88:91]
	v_mfma_f32_16x16x32_bf16 v[92:95], v[174:177], v[198:201], v[92:95]
	v_mfma_f32_16x16x32_bf16 v[68:71], v[166:169], v[214:217], v[68:71]
	v_mfma_f32_16x16x32_bf16 v[76:79], v[174:177], v[214:217], v[76:79]
	s_setprio 0
	s_barrier
	s_add_i32 s48, s48, s23
	v_lshl_add_u64 v[202:203], s[16:17], 0, v[96:97]
	s_mov_b32 m0, s48
	ds_read_b128 v[178:181], v152 offset:16384
	ds_read_b128 v[182:185], v152 offset:17408
	ds_read_b128 v[186:189], v152 offset:18432
	ds_read_b128 v[190:193], v152 offset:19456
	ds_read_b128 v[194:197], v152 offset:20480
	ds_read_b128 v[198:201], v152 offset:21504
	ds_read_b128 v[210:213], v152 offset:22528
	ds_read_b128 v[214:217], v152 offset:23552
	global_load_lds_dwordx4 v[202:203], off
	s_add_i32 m0, s48, 0x2000
	s_add_u32 s50, s16, 0x160000
	v_lshl_add_u64 v[218:219], s[16:17], 0, v[134:135]
	s_addc_u32 s51, s17, 0
	s_add_i32 s48, s64, s23
	global_load_lds_dwordx4 v[218:219], off
	v_lshl_add_u64 v[220:221], s[50:51], 0, v[96:97]
	s_mov_b32 m0, s48
	v_lshl_add_u64 v[222:223], s[60:61], 0, v[132:133]
	global_load_lds_dwordx4 v[220:221], off
	v_lshl_add_u64 v[220:221], s[50:51], 0, v[134:135]
	s_add_i32 m0, s48, 0x2000
	s_nop 0
	global_load_lds_dwordx4 v[220:221], off
	v_lshl_add_u64 v[220:221], s[60:61], 0, v[130:131]
	s_mov_b32 m0, s24
	s_nop 0
	global_load_lds_dwordx4 v[220:221], off
	s_mov_b32 m0, s25
	s_nop 0
	global_load_lds_dwordx4 v[222:223], off
	s_waitcnt vmcnt(8)
	s_waitcnt lgkmcnt(0)
	s_barrier
; #define PG8_STAGE(bufoff, gbase, voff) do { _Pragma("unroll") for (int _i = 0; _i < 2; ++_i) \
;         __builtin_amdgcn_global_load_lds((const unsigned*)((const char*)(gbase) + (voff)[_i]), (LAS unsigned*)(lds + (bufoff) + ldsw + _i * 8192), 16, 0, 0); } while (0)
; #define PG8_LDA(dst, b, h) do { _Pragma("unroll") for (int m = 0; m < 4; ++m) _Pragma("unroll") for (int k = 0; k < 2; ++k) dst[m][k] = *(const LAS bf16x8*)(lds + PG8_SA(b, h) + aoff + m * 2048 + k * 1024); } while (0)
; #define PG8_LDB(dst, b, h) do { _Pragma("unroll") for (int n = 0; n < 2; ++n) _Pragma("unroll") for (int k = 0; k < 2; ++k) dst[n][k] = *(const LAS bf16x8*)(lds + PG8_SB(b, h) + boff + n * 2048 + k * 1024); } while (0)
; #define PG8_MMA(ai, bj, At, Bt) do { __builtin_amdgcn_s_setprio(1); _Pragma("unroll") for (int m = 0; m < 4; ++m) _Pragma("unroll") for (int n = 0; n < 2; ++n) _Pragma("unroll") for (int k = 0; k < 2; ++k) \
;         acc[ai][bj][m][n] = __builtin_amdgcn_mfma_f32_16x16x32_bf16(Bt[n][k], At[m][k], acc[ai][bj][m][n], 0, 0, 0); __builtin_amdgcn_s_setprio(0); } while (0)
; #define PG8_WAIT_V(n) asm volatile("s_waitcnt vmcnt(" #n ")" ::: "memory")
; #define PG8_WAIT_L(n) asm volatile("s_waitcnt lgkmcnt(" #n ")" ::: "memory")
; #define PG8_BAR __builtin_amdgcn_s_barrier()
; #define PG8_SCHED __builtin_amdgcn_sched_barrier(0)
; template <int K, int LDA, int LDB, int KGRP, bool APERM, class Epi>
; __device__ __forceinline__ void gemm_phase(LAS unsigned char* lds, const Gemm g, const StaticOrder& S, const Epi& E, const int tid) {
;     ...
;             PG8_WAIT_V(8); PG8_WAIT_L(0); PG8_BAR; PG8_MMA(1, 0, At, B0); PG8_MMA(1, 1, At, B1); PG8_BAR; PG8_SCHED;
;             PG8_LDB(B0, 1, 0); PG8_LDB(B1, 1, 1); PG8_SCHED; PG8_LDA(At, 1, 0); PG8_STAGE(PG8_SA(0, 1), a2 + hstepA, voffA);
;             PG8_WAIT_V(8); PG8_WAIT_L(0); PG8_BAR; PG8_MMA(0, 0, At, B0); PG8_MMA(0, 1, At, B1); PG8_BAR; PG8_SCHED;
	s_setprio 1
	v_mfma_f32_16x16x32_bf16 v[36:39], v[140:143], v[178:181], v[36:39]
	v_mfma_f32_16x16x32_bf16 v[44:47], v[154:157], v[178:181], v[44:47]
	v_mfma_f32_16x16x32_bf16 v[12:15], v[140:143], v[186:189], v[12:15]
	v_mfma_f32_16x16x32_bf16 v[20:23], v[154:157], v[186:189], v[20:23]
	v_mfma_f32_16x16x32_bf16 v[24:27], v[140:143], v[194:197], v[24:27]
	v_mfma_f32_16x16x32_bf16 v[28:31], v[154:157], v[194:197], v[28:31]
	v_mfma_f32_16x16x32_bf16 v[0:3], v[140:143], v[210:213], v[0:3]
	v_mfma_f32_16x16x32_bf16 v[4:7], v[154:157], v[210:213], v[4:7]
	v_mfma_f32_16x16x32_bf16 v[36:39], v[144:147], v[182:185], v[36:39]
	v_mfma_f32_16x16x32_bf16 v[44:47], v[158:161], v[182:185], v[44:47]
	v_mfma_f32_16x16x32_bf16 v[12:15], v[144:147], v[190:193], v[12:15]
	v_mfma_f32_16x16x32_bf16 v[20:23], v[158:161], v[190:193], v[20:23]
	v_mfma_f32_16x16x32_bf16 v[24:27], v[144:147], v[198:201], v[24:27]
	v_mfma_f32_16x16x32_bf16 v[28:31], v[158:161], v[198:201], v[28:31]
	v_mfma_f32_16x16x32_bf16 v[0:3], v[144:147], v[214:217], v[0:3]
	v_mfma_f32_16x16x32_bf16 v[4:7], v[158:161], v[214:217], v[4:7]
	s_setprio 0
	s_setprio 1
	v_mfma_f32_16x16x32_bf16 v[56:59], v[162:165], v[178:181], v[56:59]
	v_mfma_f32_16x16x32_bf16 v[60:63], v[170:173], v[178:181], v[60:63]
	v_mfma_f32_16x16x32_bf16 v[64:67], v[162:165], v[186:189], v[64:67]
	v_mfma_f32_16x16x32_bf16 v[72:75], v[170:173], v[186:189], v[72:75]
	v_mfma_f32_16x16x32_bf16 v[32:35], v[162:165], v[194:197], v[32:35]
	v_mfma_f32_16x16x32_bf16 v[40:43], v[170:173], v[194:197], v[40:43]
	v_mfma_f32_16x16x32_bf16 v[8:11], v[162:165], v[210:213], v[8:11]
	v_mfma_f32_16x16x32_bf16 v[16:19], v[170:173], v[210:213], v[16:19]
	v_mfma_f32_16x16x32_bf16 v[56:59], v[166:169], v[182:185], v[56:59]
	v_mfma_f32_16x16x32_bf16 v[60:63], v[174:177], v[182:185], v[60:63]
	v_mfma_f32_16x16x32_bf16 v[64:67], v[166:169], v[190:193], v[64:67]
	v_mfma_f32_16x16x32_bf16 v[72:75], v[174:177], v[190:193], v[72:75]
	v_mfma_f32_16x16x32_bf16 v[32:35], v[166:169], v[198:201], v[32:35]
	v_mfma_f32_16x16x32_bf16 v[40:43], v[174:177], v[198:201], v[40:43]
	v_mfma_f32_16x16x32_bf16 v[8:11], v[166:169], v[214:217], v[8:11]
	v_mfma_f32_16x16x32_bf16 v[16:19], v[174:177], v[214:217], v[16:19]
	s_setprio 0
	s_barrier
	s_add_i32 s48, 0, 0x18000
	v_add_u32_e32 v153, s48, v150
	s_add_i32 s54, 0, 0x1c000
	ds_read_b128 v[140:143], v153
	ds_read_b128 v[144:147], v153 offset:1024
	ds_read_b128 v[154:157], v153 offset:2048
	ds_read_b128 v[158:161], v153 offset:3072
	v_add_u32_e32 v153, s54, v150
	ds_read_b128 v[162:165], v153
	ds_read_b128 v[166:169], v153 offset:1024
	ds_read_b128 v[170:173], v153 offset:2048
	ds_read_b128 v[174:177], v153 offset:3072
	s_add_u32 s50, s60, 0x160000
	s_addc_u32 s51, s61, 0
	s_mov_b32 m0, s26
	v_lshl_add_u64 v[224:225], s[50:51], 0, v[130:131]
	ds_read_b128 v[178:181], v152 offset:32768
	ds_read_b128 v[182:185], v152 offset:33792
	ds_read_b128 v[186:189], v152 offset:34816
	ds_read_b128 v[190:193], v152 offset:35840
	ds_read_b128 v[194:197], v152 offset:36864
	ds_read_b128 v[198:201], v152 offset:37888
	ds_read_b128 v[210:213], v152 offset:38912
	ds_read_b128 v[214:217], v152 offset:39936
	global_load_lds_dwordx4 v[224:225], off
	v_lshl_add_u64 v[224:225], s[50:51], 0, v[132:133]
	s_mov_b32 m0, s27
	s_nop 0
	global_load_lds_dwordx4 v[224:225], off
	s_waitcnt vmcnt(8)
	s_waitcnt lgkmcnt(0)
	s_barrier
	s_setprio 1
	v_mfma_f32_16x16x32_bf16 v[114:117], v[140:143], v[178:181], v[114:117]
	v_mfma_f32_16x16x32_bf16 v[118:121], v[154:157], v[178:181], v[118:121]
	v_mfma_f32_16x16x32_bf16 v[98:101], v[140:143], v[186:189], v[98:101]
	v_mfma_f32_16x16x32_bf16 v[102:105], v[154:157], v[186:189], v[102:105]
	v_mfma_f32_16x16x32_bf16 v[80:83], v[140:143], v[194:197], v[80:83]
	v_mfma_f32_16x16x32_bf16 v[84:87], v[154:157], v[194:197], v[84:87]
	v_mfma_f32_16x16x32_bf16 v[48:51], v[140:143], v[210:213], v[48:51]
	v_mfma_f32_16x16x32_bf16 v[52:55], v[154:157], v[210:213], v[52:55]
	v_mfma_f32_16x16x32_bf16 v[114:117], v[144:147], v[182:185], v[114:117]
	v_mfma_f32_16x16x32_bf16 v[118:121], v[158:161], v[182:185], v[118:121]
	v_mfma_f32_16x16x32_bf16 v[98:101], v[144:147], v[190:193], v[98:101]
	v_mfma_f32_16x16x32_bf16 v[102:105], v[158:161], v[190:193], v[102:105]
	v_mfma_f32_16x16x32_bf16 v[80:83], v[144:147], v[198:201], v[80:83]
	v_mfma_f32_16x16x32_bf16 v[84:87], v[158:161], v[198:201], v[84:87]
	v_mfma_f32_16x16x32_bf16 v[48:51], v[144:147], v[214:217], v[48:51]
	v_mfma_f32_16x16x32_bf16 v[52:55], v[158:161], v[214:217], v[52:55]
	s_setprio 0
	s_setprio 1
	v_mfma_f32_16x16x32_bf16 v[122:125], v[162:165], v[178:181], v[122:125]
	v_mfma_f32_16x16x32_bf16 v[126:129], v[170:173], v[178:181], v[126:129]
	v_mfma_f32_16x16x32_bf16 v[106:109], v[162:165], v[186:189], v[106:109]
	v_mfma_f32_16x16x32_bf16 v[110:113], v[170:173], v[186:189], v[110:113]
	v_mfma_f32_16x16x32_bf16 v[88:91], v[162:165], v[194:197], v[88:91]
	v_mfma_f32_16x16x32_bf16 v[92:95], v[170:173], v[194:197], v[92:95]
	v_mfma_f32_16x16x32_bf16 v[68:71], v[162:165], v[210:213], v[68:71]
	v_mfma_f32_16x16x32_bf16 v[76:79], v[170:173], v[210:213], v[76:79]
	v_mfma_f32_16x16x32_bf16 v[122:125], v[166:169], v[182:185], v[122:125]
	v_mfma_f32_16x16x32_bf16 v[126:129], v[174:177], v[182:185], v[126:129]
	v_mfma_f32_16x16x32_bf16 v[106:109], v[166:169], v[190:193], v[106:109]
	v_mfma_f32_16x16x32_bf16 v[110:113], v[174:177], v[190:193], v[110:113]
	v_mfma_f32_16x16x32_bf16 v[88:91], v[166:169], v[198:201], v[88:91]
	v_mfma_f32_16x16x32_bf16 v[92:95], v[174:177], v[198:201], v[92:95]
	v_mfma_f32_16x16x32_bf16 v[68:71], v[166:169], v[214:217], v[68:71]
	v_mfma_f32_16x16x32_bf16 v[76:79], v[174:177], v[214:217], v[76:79]
	s_setprio 0
	s_barrier
; #define PG8_STAGE(bufoff, gbase, voff) do { _Pragma("unroll") for (int _i = 0; _i < 2; ++_i) \
;         __builtin_amdgcn_global_load_lds((const unsigned*)((const char*)(gbase) + (voff)[_i]), (LAS unsigned*)(lds + (bufoff) + ldsw + _i * 8192), 16, 0, 0); } while (0)
; #define PG8_LDA(dst, b, h) do { _Pragma("unroll") for (int m = 0; m < 4; ++m) _Pragma("unroll") for (int k = 0; k < 2; ++k) dst[m][k] = *(const LAS bf16x8*)(lds + PG8_SA(b, h) + aoff + m * 2048 + k * 1024); } while (0)
; #define PG8_MMA(ai, bj, At, Bt) do { __builtin_amdgcn_s_setprio(1); _Pragma("unroll") for (int m = 0; m < 4; ++m) _Pragma("unroll") for (int n = 0; n < 2; ++n) _Pragma("unroll") for (int k = 0; k < 2; ++k) \
;         acc[ai][bj][m][n] = __builtin_amdgcn_mfma_f32_16x16x32_bf16(Bt[n][k], At[m][k], acc[ai][bj][m][n], 0, 0, 0); __builtin_amdgcn_s_setprio(0); } while (0)
; #define PG8_WAIT_V(n) asm volatile("s_waitcnt vmcnt(" #n ")" ::: "memory")
; #define PG8_WAIT_L(n) asm volatile("s_waitcnt lgkmcnt(" #n ")" ::: "memory")
; #define PG8_BAR __builtin_amdgcn_s_barrier()
; #define PG8_SCHED __builtin_amdgcn_sched_barrier(0)
; template <int K, int LDA, int LDB, int KGRP, bool APERM, class Epi>
; __device__ __forceinline__ void gemm_phase(LAS unsigned char* lds, const Gemm g, const StaticOrder& S, const Epi& E, const int tid) {
;     ...
;             PG8_LDA(At, 1, 1); PG8_STAGE(PG8_SB(1, 0), b3, voffB); PG8_STAGE(PG8_SB(1, 1), b3 + hstepB, voffB); PG8_STAGE(PG8_SA(1, 0), a3, voffA);
;             PG8_WAIT_V(8); PG8_WAIT_L(0); PG8_BAR; PG8_MMA(1, 0, At, B0); PG8_MMA(1, 1, At, B1); PG8_BAR; PG8_SCHED;
;         }
;         if (wr == 0) PG8_BAR;
	s_add_i32 s48, s48, s23
	v_lshl_add_u64 v[202:203], v[202:203], 0, s[38:39]
	s_mov_b32 m0, s48
	ds_read_b128 v[178:181], v152 offset:49152
	ds_read_b128 v[182:185], v152 offset:50176
	ds_read_b128 v[186:189], v152 offset:51200
	ds_read_b128 v[190:193], v152 offset:52224
	ds_read_b128 v[194:197], v152 offset:53248
	ds_read_b128 v[198:201], v152 offset:54272
	ds_read_b128 v[210:213], v152 offset:55296
	ds_read_b128 v[214:217], v152 offset:56320
	global_load_lds_dwordx4 v[202:203], off
	s_add_i32 m0, s48, 0x2000
	s_add_u32 s16, s16, 0x160080
	v_lshl_add_u64 v[202:203], v[218:219], 0, s[38:39]
	s_addc_u32 s17, s17, 0
	s_add_i32 s48, s54, s23
	global_load_lds_dwordx4 v[202:203], off
	v_lshl_add_u64 v[202:203], s[16:17], 0, v[96:97]
	s_mov_b32 m0, s48
	s_nop 0
	global_load_lds_dwordx4 v[202:203], off
	v_lshl_add_u64 v[202:203], s[16:17], 0, v[134:135]
	s_add_i32 m0, s48, 0x2000
	s_nop 0
	global_load_lds_dwordx4 v[202:203], off
	v_lshl_add_u64 v[202:203], v[220:221], 0, s[38:39]
	s_mov_b32 m0, s28
	s_nop 0
	global_load_lds_dwordx4 v[202:203], off
	v_lshl_add_u64 v[202:203], v[222:223], 0, s[38:39]
	s_mov_b32 m0, s29
	s_nop 0
	global_load_lds_dwordx4 v[202:203], off
	s_waitcnt vmcnt(8)
	s_waitcnt lgkmcnt(0)
	s_barrier
	s_setprio 1
	v_mfma_f32_16x16x32_bf16 v[36:39], v[140:143], v[178:181], v[36:39]
	v_mfma_f32_16x16x32_bf16 v[44:47], v[154:157], v[178:181], v[44:47]
	v_mfma_f32_16x16x32_bf16 v[12:15], v[140:143], v[186:189], v[12:15]
	v_mfma_f32_16x16x32_bf16 v[20:23], v[154:157], v[186:189], v[20:23]
	v_mfma_f32_16x16x32_bf16 v[24:27], v[140:143], v[194:197], v[24:27]
	v_mfma_f32_16x16x32_bf16 v[28:31], v[154:157], v[194:197], v[28:31]
	v_mfma_f32_16x16x32_bf16 v[0:3], v[140:143], v[210:213], v[0:3]
	v_mfma_f32_16x16x32_bf16 v[4:7], v[154:157], v[210:213], v[4:7]
	v_mfma_f32_16x16x32_bf16 v[36:39], v[144:147], v[182:185], v[36:39]
	v_mfma_f32_16x16x32_bf16 v[44:47], v[158:161], v[182:185], v[44:47]
	v_mfma_f32_16x16x32_bf16 v[12:15], v[144:147], v[190:193], v[12:15]
	v_mfma_f32_16x16x32_bf16 v[20:23], v[158:161], v[190:193], v[20:23]
	v_mfma_f32_16x16x32_bf16 v[24:27], v[144:147], v[198:201], v[24:27]
	v_mfma_f32_16x16x32_bf16 v[28:31], v[158:161], v[198:201], v[28:31]
	v_mfma_f32_16x16x32_bf16 v[0:3], v[144:147], v[214:217], v[0:3]
	v_mfma_f32_16x16x32_bf16 v[4:7], v[158:161], v[214:217], v[4:7]
	s_setprio 0
	s_setprio 1
	v_mfma_f32_16x16x32_bf16 v[56:59], v[162:165], v[178:181], v[56:59]
	v_mfma_f32_16x16x32_bf16 v[60:63], v[170:173], v[178:181], v[60:63]
	v_mfma_f32_16x16x32_bf16 v[64:67], v[162:165], v[186:189], v[64:67]
	v_mfma_f32_16x16x32_bf16 v[72:75], v[170:173], v[186:189], v[72:75]
	v_mfma_f32_16x16x32_bf16 v[32:35], v[162:165], v[194:197], v[32:35]
	v_mfma_f32_16x16x32_bf16 v[40:43], v[170:173], v[194:197], v[40:43]
	v_mfma_f32_16x16x32_bf16 v[8:11], v[162:165], v[210:213], v[8:11]
	v_mfma_f32_16x16x32_bf16 v[16:19], v[170:173], v[210:213], v[16:19]
	v_mfma_f32_16x16x32_bf16 v[56:59], v[166:169], v[182:185], v[56:59]
	v_mfma_f32_16x16x32_bf16 v[60:63], v[174:177], v[182:185], v[60:63]
	v_mfma_f32_16x16x32_bf16 v[64:67], v[166:169], v[190:193], v[64:67]
	v_mfma_f32_16x16x32_bf16 v[72:75], v[174:177], v[190:193], v[72:75]
	v_mfma_f32_16x16x32_bf16 v[32:35], v[166:169], v[198:201], v[32:35]
	v_mfma_f32_16x16x32_bf16 v[40:43], v[174:177], v[198:201], v[40:43]
	v_mfma_f32_16x16x32_bf16 v[8:11], v[166:169], v[214:217], v[8:11]
	v_mfma_f32_16x16x32_bf16 v[16:19], v[174:177], v[214:217], v[16:19]
	s_setprio 0
	s_barrier
	s_add_i32 s45, s45, 2
	s_add_u32 s3, s3, 0x100
	s_addc_u32 s44, s44, 0
	s_cmpk_gt_u32 s45, 0x55
	s_mov_b64 s[54:55], s[8:9]
	s_cbranch_scc0 .LBB0_1370
	s_and_b64 vcc, exec, s[34:35]
	s_cbranch_vccz .LBB0_1373
	s_barrier

; #define PG8_STAGE(bufoff, gbase, voff) do { _Pragma("unroll") for (int _i = 0; _i < 2; ++_i) \
;         __builtin_amdgcn_global_load_lds((const unsigned*)((const char*)(gbase) + (voff)[_i]), (LAS unsigned*)(lds + (bufoff) + ldsw + _i * 8192), 16, 0, 0); } while (0)
; #define PG8_LDA(dst, b, h) do { _Pragma("unroll") for (int m = 0; m < 4; ++m) _Pragma("unroll") for (int k = 0; k < 2; ++k) dst[m][k] = *(const LAS bf16x8*)(lds + PG8_SA(b, h) + aoff + m * 2048 + k * 1024); } while (0)
; #define PG8_LDB(dst, b, h) do { _Pragma("unroll") for (int n = 0; n < 2; ++n) _Pragma("unroll") for (int k = 0; k < 2; ++k) dst[n][k] = *(const LAS bf16x8*)(lds + PG8_SB(b, h) + boff + n * 2048 + k * 1024); } while (0)
; #define PG8_MMA(ai, bj, At, Bt) do { __builtin_amdgcn_s_setprio(1); _Pragma("unroll") for (int m = 0; m < 4; ++m) _Pragma("unroll") for (int n = 0; n < 2; ++n) _Pragma("unroll") for (int k = 0; k < 2; ++k) \
;         acc[ai][bj][m][n] = __builtin_amdgcn_mfma_f32_16x16x32_bf16(Bt[n][k], At[m][k], acc[ai][bj][m][n], 0, 0, 0); __builtin_amdgcn_s_setprio(0); } while (0)
; #define PG8_WAIT_V(n) asm volatile("s_waitcnt vmcnt(" #n ")" ::: "memory")
; #define PG8_WAIT_L(n) asm volatile("s_waitcnt lgkmcnt(" #n ")" ::: "memory")
; #define PG8_BAR __builtin_amdgcn_s_barrier()
; #define PG8_SCHED __builtin_amdgcn_sched_barrier(0)
; template <int K, int LDA, int LDB, int KGRP, bool APERM, class Epi>
; __device__ __forceinline__ void gemm_phase(LAS unsigned char* lds, const Gemm g, const StaticOrder& S, const Epi& E, const int tid) {
;     ...
;             const bool last = (t == nt - 2);
;             const char* a1 = cA + (size_t)(t + 1) * kstep;
;             const char* a2 = last ? nA : cA + (size_t)(t + 2) * kstep; const char* b2 = last ? nB : cB + (size_t)(t + 2) * kstep;
;             const char* a3 = a2 + kstep; const char* b3 = b2 + kstep;
;             PG8_LDB(B0, 0, 0); PG8_LDB(B1, 0, 1); PG8_SCHED; PG8_LDA(At, 0, 0); PG8_STAGE(PG8_SA(1, 1), a1 + hstepA, voffA);
;             PG8_WAIT_V(8); PG8_WAIT_L(0); PG8_BAR; PG8_MMA(0, 0, At, B0); PG8_MMA(0, 1, At, B1); PG8_BAR; PG8_SCHED;
;             PG8_LDA(At, 0, 1); PG8_STAGE(PG8_SB(0, 0), b2, voffB); PG8_STAGE(PG8_SB(0, 1), b2 + hstepB, voffB); PG8_STAGE(PG8_SA(0, 0), a2, voffA);
;             PG8_WAIT_V(8); PG8_WAIT_L(0); PG8_BAR; PG8_MMA(1, 0, At, B0); PG8_MMA(1, 1, At, B1); PG8_BAR; PG8_SCHED;
.LBB0_1432:
	s_add_u32 s16, s52, 0x100
	s_addc_u32 s17, s53, 0
	s_add_i32 s45, 0, 0x10000
	s_cmpk_eq_i32 s44, 0x54
	s_cselect_b32 s57, s7, s17
	s_cselect_b32 s56, s6, s16
	v_add_u32_e32 v140, s45, v143
	s_cselect_b32 s55, s35, s43
	s_cselect_b32 s54, s34, s3
	s_add_i32 s48, 0, 0x14000
	ds_read_b128 v[146:149], v140
	ds_read_b128 v[150:153], v140 offset:1024
	ds_read_b128 v[154:157], v140 offset:2048
	ds_read_b128 v[158:161], v140 offset:3072
	v_add_u32_e32 v140, s48, v143
	ds_read_b128 v[162:165], v140
	ds_read_b128 v[166:169], v140 offset:1024
	ds_read_b128 v[170:173], v140 offset:2048
	ds_read_b128 v[174:177], v140 offset:3072
	v_lshl_add_u64 v[140:141], s[52:53], 0, v[136:137]
	s_add_i32 m0, s23, 0xc000
	ds_read_b128 v[178:181], v145
	ds_read_b128 v[182:185], v145 offset:1024
	ds_read_b128 v[186:189], v145 offset:2048
	ds_read_b128 v[190:193], v145 offset:3072
	ds_read_b128 v[194:197], v145 offset:4096
	ds_read_b128 v[198:201], v145 offset:5120
	ds_read_b128 v[210:213], v145 offset:6144
	ds_read_b128 v[214:217], v145 offset:7168
	global_load_lds_dwordx4 v[140:141], off
	v_lshl_add_u64 v[140:141], s[52:53], 0, v[138:139]
	s_add_i32 m0, s23, 0xe000
	s_nop 0
	global_load_lds_dwordx4 v[140:141], off
	s_waitcnt vmcnt(8)
	s_waitcnt lgkmcnt(0)
	s_barrier
	s_setprio 1
	v_mfma_f32_16x16x32_bf16 v[28:31], v[146:149], v[178:181], v[28:31]
	v_mfma_f32_16x16x32_bf16 v[24:27], v[154:157], v[178:181], v[24:27]
	v_mfma_f32_16x16x32_bf16 v[16:19], v[146:149], v[186:189], v[16:19]
	v_mfma_f32_16x16x32_bf16 v[20:23], v[154:157], v[186:189], v[20:23]
	v_mfma_f32_16x16x32_bf16 v[8:11], v[146:149], v[194:197], v[8:11]
	v_mfma_f32_16x16x32_bf16 v[12:15], v[154:157], v[194:197], v[12:15]
	v_mfma_f32_16x16x32_bf16 v[0:3], v[146:149], v[210:213], v[0:3]
	v_mfma_f32_16x16x32_bf16 v[4:7], v[154:157], v[210:213], v[4:7]
	v_mfma_f32_16x16x32_bf16 v[28:31], v[150:153], v[182:185], v[28:31]
	v_mfma_f32_16x16x32_bf16 v[24:27], v[158:161], v[182:185], v[24:27]
	v_mfma_f32_16x16x32_bf16 v[16:19], v[150:153], v[190:193], v[16:19]
	v_mfma_f32_16x16x32_bf16 v[20:23], v[158:161], v[190:193], v[20:23]
	v_mfma_f32_16x16x32_bf16 v[8:11], v[150:153], v[198:201], v[8:11]
	v_mfma_f32_16x16x32_bf16 v[12:15], v[158:161], v[198:201], v[12:15]
	v_mfma_f32_16x16x32_bf16 v[0:3], v[150:153], v[214:217], v[0:3]
	v_mfma_f32_16x16x32_bf16 v[4:7], v[158:161], v[214:217], v[4:7]
	s_setprio 0
	s_setprio 1
	v_mfma_f32_16x16x32_bf16 v[88:91], v[162:165], v[178:181], v[88:91]
	v_mfma_f32_16x16x32_bf16 v[92:95], v[170:173], v[178:181], v[92:95]
	v_mfma_f32_16x16x32_bf16 v[80:83], v[162:165], v[186:189], v[80:83]
	v_mfma_f32_16x16x32_bf16 v[84:87], v[170:173], v[186:189], v[84:87]
	v_mfma_f32_16x16x32_bf16 v[68:71], v[162:165], v[194:197], v[68:71]
	v_mfma_f32_16x16x32_bf16 v[76:79], v[170:173], v[194:197], v[76:79]
	v_mfma_f32_16x16x32_bf16 v[56:59], v[162:165], v[210:213], v[56:59]
	v_mfma_f32_16x16x32_bf16 v[64:67], v[170:173], v[210:213], v[64:67]
	v_mfma_f32_16x16x32_bf16 v[88:91], v[166:169], v[182:185], v[88:91]
	v_mfma_f32_16x16x32_bf16 v[92:95], v[174:177], v[182:185], v[92:95]
	v_mfma_f32_16x16x32_bf16 v[80:83], v[166:169], v[190:193], v[80:83]
	v_mfma_f32_16x16x32_bf16 v[84:87], v[174:177], v[190:193], v[84:87]
	v_mfma_f32_16x16x32_bf16 v[68:71], v[166:169], v[198:201], v[68:71]
	v_mfma_f32_16x16x32_bf16 v[76:79], v[174:177], v[198:201], v[76:79]
	v_mfma_f32_16x16x32_bf16 v[56:59], v[166:169], v[214:217], v[56:59]
	v_mfma_f32_16x16x32_bf16 v[64:67], v[174:177], v[214:217], v[64:67]
	s_setprio 0
	s_barrier
	s_add_i32 s45, s45, s18
	v_lshl_add_u64 v[140:141], s[54:55], 0, v[96:97]
	s_mov_b32 m0, s45
	ds_read_b128 v[178:181], v145 offset:16384
	ds_read_b128 v[182:185], v145 offset:17408
	ds_read_b128 v[186:189], v145 offset:18432
	ds_read_b128 v[190:193], v145 offset:19456
	ds_read_b128 v[194:197], v145 offset:20480
	ds_read_b128 v[198:201], v145 offset:21504
	ds_read_b128 v[210:213], v145 offset:22528
	ds_read_b128 v[214:217], v145 offset:23552
	global_load_lds_dwordx4 v[140:141], off
	s_add_i32 m0, s45, 0x2000
	s_add_u32 s50, s54, 0x160000
	v_lshl_add_u64 v[202:203], s[54:55], 0, v[134:135]
	s_addc_u32 s51, s55, 0
	s_add_i32 s45, s48, s18
	global_load_lds_dwordx4 v[202:203], off
	v_lshl_add_u64 v[218:219], s[50:51], 0, v[96:97]
	s_mov_b32 m0, s45
	v_lshl_add_u64 v[220:221], s[56:57], 0, v[132:133]
	global_load_lds_dwordx4 v[218:219], off
	v_lshl_add_u64 v[218:219], s[50:51], 0, v[134:135]
	s_add_i32 m0, s45, 0x2000
	s_nop 0
	global_load_lds_dwordx4 v[218:219], off
	v_lshl_add_u64 v[218:219], s[56:57], 0, v[130:131]
	s_mov_b32 m0, s23
	s_nop 0
	global_load_lds_dwordx4 v[218:219], off
	s_mov_b32 m0, s24
	s_nop 0
	global_load_lds_dwordx4 v[220:221], off
	s_waitcnt vmcnt(8)
	s_waitcnt lgkmcnt(0)
	s_barrier
; #define PG8_STAGE(bufoff, gbase, voff) do { _Pragma("unroll") for (int _i = 0; _i < 2; ++_i) \
;         __builtin_amdgcn_global_load_lds((const unsigned*)((const char*)(gbase) + (voff)[_i]), (LAS unsigned*)(lds + (bufoff) + ldsw + _i * 8192), 16, 0, 0); } while (0)
; #define PG8_LDA(dst, b, h) do { _Pragma("unroll") for (int m = 0; m < 4; ++m) _Pragma("unroll") for (int k = 0; k < 2; ++k) dst[m][k] = *(const LAS bf16x8*)(lds + PG8_SA(b, h) + aoff + m * 2048 + k * 1024); } while (0)
; #define PG8_LDB(dst, b, h) do { _Pragma("unroll") for (int n = 0; n < 2; ++n) _Pragma("unroll") for (int k = 0; k < 2; ++k) dst[n][k] = *(const LAS bf16x8*)(lds + PG8_SB(b, h) + boff + n * 2048 + k * 1024); } while (0)
; #define PG8_MMA(ai, bj, At, Bt) do { __builtin_amdgcn_s_setprio(1); _Pragma("unroll") for (int m = 0; m < 4; ++m) _Pragma("unroll") for (int n = 0; n < 2; ++n) _Pragma("unroll") for (int k = 0; k < 2; ++k) \
;         acc[ai][bj][m][n] = __builtin_amdgcn_mfma_f32_16x16x32_bf16(Bt[n][k], At[m][k], acc[ai][bj][m][n], 0, 0, 0); __builtin_amdgcn_s_setprio(0); } while (0)
; #define PG8_WAIT_V(n) asm volatile("s_waitcnt vmcnt(" #n ")" ::: "memory")
; #define PG8_WAIT_L(n) asm volatile("s_waitcnt lgkmcnt(" #n ")" ::: "memory")
; #define PG8_BAR __builtin_amdgcn_s_barrier()
; #define PG8_SCHED __builtin_amdgcn_sched_barrier(0)
; template <int K, int LDA, int LDB, int KGRP, bool APERM, class Epi>
; __device__ __forceinline__ void gemm_phase(LAS unsigned char* lds, const Gemm g, const StaticOrder& S, const Epi& E, const int tid) {
;     ...
;             PG8_WAIT_V(8); PG8_WAIT_L(0); PG8_BAR; PG8_MMA(1, 0, At, B0); PG8_MMA(1, 1, At, B1); PG8_BAR; PG8_SCHED;
;             PG8_LDB(B0, 1, 0); PG8_LDB(B1, 1, 1); PG8_SCHED; PG8_LDA(At, 1, 0); PG8_STAGE(PG8_SA(0, 1), a2 + hstepA, voffA);
;             PG8_WAIT_V(8); PG8_WAIT_L(0); PG8_BAR; PG8_MMA(0, 0, At, B0); PG8_MMA(0, 1, At, B1); PG8_BAR; PG8_SCHED;
	s_setprio 1
	v_mfma_f32_16x16x32_bf16 v[72:75], v[146:149], v[178:181], v[72:75]
	v_mfma_f32_16x16x32_bf16 v[60:63], v[154:157], v[178:181], v[60:63]
	v_mfma_f32_16x16x32_bf16 v[48:51], v[146:149], v[186:189], v[48:51]
	v_mfma_f32_16x16x32_bf16 v[52:55], v[154:157], v[186:189], v[52:55]
	v_mfma_f32_16x16x32_bf16 v[40:43], v[146:149], v[194:197], v[40:43]
	v_mfma_f32_16x16x32_bf16 v[44:47], v[154:157], v[194:197], v[44:47]
	v_mfma_f32_16x16x32_bf16 v[32:35], v[146:149], v[210:213], v[32:35]
	v_mfma_f32_16x16x32_bf16 v[36:39], v[154:157], v[210:213], v[36:39]
	v_mfma_f32_16x16x32_bf16 v[72:75], v[150:153], v[182:185], v[72:75]
	v_mfma_f32_16x16x32_bf16 v[60:63], v[158:161], v[182:185], v[60:63]
	v_mfma_f32_16x16x32_bf16 v[48:51], v[150:153], v[190:193], v[48:51]
	v_mfma_f32_16x16x32_bf16 v[52:55], v[158:161], v[190:193], v[52:55]
	v_mfma_f32_16x16x32_bf16 v[40:43], v[150:153], v[198:201], v[40:43]
	v_mfma_f32_16x16x32_bf16 v[44:47], v[158:161], v[198:201], v[44:47]
	v_mfma_f32_16x16x32_bf16 v[32:35], v[150:153], v[214:217], v[32:35]
	v_mfma_f32_16x16x32_bf16 v[36:39], v[158:161], v[214:217], v[36:39]
	s_setprio 0
	s_setprio 1
	v_mfma_f32_16x16x32_bf16 v[122:125], v[162:165], v[178:181], v[122:125]
	v_mfma_f32_16x16x32_bf16 v[126:129], v[170:173], v[178:181], v[126:129]
	v_mfma_f32_16x16x32_bf16 v[114:117], v[162:165], v[186:189], v[114:117]
	v_mfma_f32_16x16x32_bf16 v[118:121], v[170:173], v[186:189], v[118:121]
	v_mfma_f32_16x16x32_bf16 v[106:109], v[162:165], v[194:197], v[106:109]
	v_mfma_f32_16x16x32_bf16 v[110:113], v[170:173], v[194:197], v[110:113]
	v_mfma_f32_16x16x32_bf16 v[98:101], v[162:165], v[210:213], v[98:101]
	v_mfma_f32_16x16x32_bf16 v[102:105], v[170:173], v[210:213], v[102:105]
	v_mfma_f32_16x16x32_bf16 v[122:125], v[166:169], v[182:185], v[122:125]
	v_mfma_f32_16x16x32_bf16 v[126:129], v[174:177], v[182:185], v[126:129]
	v_mfma_f32_16x16x32_bf16 v[114:117], v[166:169], v[190:193], v[114:117]
	v_mfma_f32_16x16x32_bf16 v[118:121], v[174:177], v[190:193], v[118:121]
	v_mfma_f32_16x16x32_bf16 v[106:109], v[166:169], v[198:201], v[106:109]
	v_mfma_f32_16x16x32_bf16 v[110:113], v[174:177], v[198:201], v[110:113]
	v_mfma_f32_16x16x32_bf16 v[98:101], v[166:169], v[214:217], v[98:101]
	v_mfma_f32_16x16x32_bf16 v[102:105], v[174:177], v[214:217], v[102:105]
	s_setprio 0
	s_barrier
	s_add_i32 s45, 0, 0x18000
	s_add_i32 s48, 0, 0x1c000
	v_add_u32_e32 v158, s45, v143
	v_add_u32_e32 v174, s48, v143
	ds_read_b128 v[146:149], v158
	ds_read_b128 v[150:153], v158 offset:1024
	ds_read_b128 v[154:157], v158 offset:2048
	ds_read_b128 v[158:161], v158 offset:3072
	ds_read_b128 v[162:165], v174
	ds_read_b128 v[166:169], v174 offset:1024
	ds_read_b128 v[170:173], v174 offset:2048
	ds_read_b128 v[174:177], v174 offset:3072
	s_add_u32 s50, s56, 0x160000
	s_addc_u32 s51, s57, 0
	s_mov_b32 m0, s25
	v_lshl_add_u64 v[222:223], s[50:51], 0, v[130:131]
	ds_read_b128 v[178:181], v145 offset:32768
	ds_read_b128 v[182:185], v145 offset:33792
	ds_read_b128 v[186:189], v145 offset:34816
	ds_read_b128 v[190:193], v145 offset:35840
	ds_read_b128 v[194:197], v145 offset:36864
	ds_read_b128 v[198:201], v145 offset:37888
	ds_read_b128 v[210:213], v145 offset:38912
	ds_read_b128 v[214:217], v145 offset:39936
	global_load_lds_dwordx4 v[222:223], off
	v_lshl_add_u64 v[222:223], s[50:51], 0, v[132:133]
	s_mov_b32 m0, s26
	s_nop 0
	global_load_lds_dwordx4 v[222:223], off
	s_waitcnt vmcnt(8)
	s_waitcnt lgkmcnt(0)
	s_barrier
	s_setprio 1
	v_mfma_f32_16x16x32_bf16 v[28:31], v[146:149], v[178:181], v[28:31]
	v_mfma_f32_16x16x32_bf16 v[24:27], v[154:157], v[178:181], v[24:27]
	v_mfma_f32_16x16x32_bf16 v[16:19], v[146:149], v[186:189], v[16:19]
	v_mfma_f32_16x16x32_bf16 v[20:23], v[154:157], v[186:189], v[20:23]
	v_mfma_f32_16x16x32_bf16 v[8:11], v[146:149], v[194:197], v[8:11]
	v_mfma_f32_16x16x32_bf16 v[12:15], v[154:157], v[194:197], v[12:15]
	v_mfma_f32_16x16x32_bf16 v[0:3], v[146:149], v[210:213], v[0:3]
	v_mfma_f32_16x16x32_bf16 v[4:7], v[154:157], v[210:213], v[4:7]
	v_mfma_f32_16x16x32_bf16 v[28:31], v[150:153], v[182:185], v[28:31]
	v_mfma_f32_16x16x32_bf16 v[24:27], v[158:161], v[182:185], v[24:27]
	v_mfma_f32_16x16x32_bf16 v[16:19], v[150:153], v[190:193], v[16:19]
	v_mfma_f32_16x16x32_bf16 v[20:23], v[158:161], v[190:193], v[20:23]
	v_mfma_f32_16x16x32_bf16 v[8:11], v[150:153], v[198:201], v[8:11]
	v_mfma_f32_16x16x32_bf16 v[12:15], v[158:161], v[198:201], v[12:15]
	v_mfma_f32_16x16x32_bf16 v[0:3], v[150:153], v[214:217], v[0:3]
	v_mfma_f32_16x16x32_bf16 v[4:7], v[158:161], v[214:217], v[4:7]
	s_setprio 0
	s_setprio 1
	v_mfma_f32_16x16x32_bf16 v[88:91], v[162:165], v[178:181], v[88:91]
	v_mfma_f32_16x16x32_bf16 v[92:95], v[170:173], v[178:181], v[92:95]
	v_mfma_f32_16x16x32_bf16 v[80:83], v[162:165], v[186:189], v[80:83]
	v_mfma_f32_16x16x32_bf16 v[84:87], v[170:173], v[186:189], v[84:87]
	v_mfma_f32_16x16x32_bf16 v[68:71], v[162:165], v[194:197], v[68:71]
	v_mfma_f32_16x16x32_bf16 v[76:79], v[170:173], v[194:197], v[76:79]
	v_mfma_f32_16x16x32_bf16 v[56:59], v[162:165], v[210:213], v[56:59]
	v_mfma_f32_16x16x32_bf16 v[64:67], v[170:173], v[210:213], v[64:67]
	v_mfma_f32_16x16x32_bf16 v[88:91], v[166:169], v[182:185], v[88:91]
	v_mfma_f32_16x16x32_bf16 v[92:95], v[174:177], v[182:185], v[92:95]
	v_mfma_f32_16x16x32_bf16 v[80:83], v[166:169], v[190:193], v[80:83]
	v_mfma_f32_16x16x32_bf16 v[84:87], v[174:177], v[190:193], v[84:87]
	v_mfma_f32_16x16x32_bf16 v[68:71], v[166:169], v[198:201], v[68:71]
	v_mfma_f32_16x16x32_bf16 v[76:79], v[174:177], v[198:201], v[76:79]
	v_mfma_f32_16x16x32_bf16 v[56:59], v[166:169], v[214:217], v[56:59]
	v_mfma_f32_16x16x32_bf16 v[64:67], v[174:177], v[214:217], v[64:67]
	s_setprio 0
	s_barrier
; #define PG8_STAGE(bufoff, gbase, voff) do { _Pragma("unroll") for (int _i = 0; _i < 2; ++_i) \
;         __builtin_amdgcn_global_load_lds((const unsigned*)((const char*)(gbase) + (voff)[_i]), (LAS unsigned*)(lds + (bufoff) + ldsw + _i * 8192), 16, 0, 0); } while (0)
; #define PG8_LDA(dst, b, h) do { _Pragma("unroll") for (int m = 0; m < 4; ++m) _Pragma("unroll") for (int k = 0; k < 2; ++k) dst[m][k] = *(const LAS bf16x8*)(lds + PG8_SA(b, h) + aoff + m * 2048 + k * 1024); } while (0)
; #define PG8_MMA(ai, bj, At, Bt) do { __builtin_amdgcn_s_setprio(1); _Pragma("unroll") for (int m = 0; m < 4; ++m) _Pragma("unroll") for (int n = 0; n < 2; ++n) _Pragma("unroll") for (int k = 0; k < 2; ++k) \
;         acc[ai][bj][m][n] = __builtin_amdgcn_mfma_f32_16x16x32_bf16(Bt[n][k], At[m][k], acc[ai][bj][m][n], 0, 0, 0); __builtin_amdgcn_s_setprio(0); } while (0)
; #define PG8_WAIT_V(n) asm volatile("s_waitcnt vmcnt(" #n ")" ::: "memory")
; #define PG8_WAIT_L(n) asm volatile("s_waitcnt lgkmcnt(" #n ")" ::: "memory")
; #define PG8_BAR __builtin_amdgcn_s_barrier()
; #define PG8_SCHED __builtin_amdgcn_sched_barrier(0)
; template <int K, int LDA, int LDB, int KGRP, bool APERM, class Epi>
; __device__ __forceinline__ void gemm_phase(LAS unsigned char* lds, const Gemm g, const StaticOrder& S, const Epi& E, const int tid) {
;     ...
;             PG8_LDA(At, 1, 1); PG8_STAGE(PG8_SB(1, 0), b3, voffB); PG8_STAGE(PG8_SB(1, 1), b3 + hstepB, voffB); PG8_STAGE(PG8_SA(1, 0), a3, voffA);
;             PG8_WAIT_V(8); PG8_WAIT_L(0); PG8_BAR; PG8_MMA(1, 0, At, B0); PG8_MMA(1, 1, At, B1); PG8_BAR; PG8_SCHED;
;         }
;         if (wr == 0) PG8_BAR;
	s_add_i32 s45, s45, s18
	v_lshl_add_u64 v[140:141], v[140:141], 0, s[38:39]
	s_mov_b32 m0, s45
	ds_read_b128 v[178:181], v145 offset:49152
	ds_read_b128 v[182:185], v145 offset:50176
	ds_read_b128 v[186:189], v145 offset:51200
	ds_read_b128 v[190:193], v145 offset:52224
	ds_read_b128 v[194:197], v145 offset:53248
	ds_read_b128 v[198:201], v145 offset:54272
	ds_read_b128 v[210:213], v145 offset:55296
	ds_read_b128 v[214:217], v145 offset:56320
	global_load_lds_dwordx4 v[140:141], off
	s_add_i32 m0, s45, 0x2000
	s_add_u32 s50, s54, 0x160080
	v_lshl_add_u64 v[140:141], v[202:203], 0, s[38:39]
	s_addc_u32 s51, s55, 0
	s_add_i32 s45, s48, s18
	global_load_lds_dwordx4 v[140:141], off
	v_lshl_add_u64 v[140:141], s[50:51], 0, v[96:97]
	s_mov_b32 m0, s45
	s_nop 0
	global_load_lds_dwordx4 v[140:141], off
	v_lshl_add_u64 v[140:141], s[50:51], 0, v[134:135]
	s_add_i32 m0, s45, 0x2000
	s_nop 0
	global_load_lds_dwordx4 v[140:141], off
	v_lshl_add_u64 v[140:141], v[218:219], 0, s[38:39]
	s_mov_b32 m0, s27
	s_nop 0
	global_load_lds_dwordx4 v[140:141], off
	v_lshl_add_u64 v[140:141], v[220:221], 0, s[38:39]
	s_mov_b32 m0, s28
	s_nop 0
	global_load_lds_dwordx4 v[140:141], off
	s_waitcnt vmcnt(8)
	s_waitcnt lgkmcnt(0)
	s_barrier
	s_setprio 1
	v_mfma_f32_16x16x32_bf16 v[72:75], v[146:149], v[178:181], v[72:75]
	v_mfma_f32_16x16x32_bf16 v[60:63], v[154:157], v[178:181], v[60:63]
	v_mfma_f32_16x16x32_bf16 v[48:51], v[146:149], v[186:189], v[48:51]
	v_mfma_f32_16x16x32_bf16 v[52:55], v[154:157], v[186:189], v[52:55]
	v_mfma_f32_16x16x32_bf16 v[40:43], v[146:149], v[194:197], v[40:43]
	v_mfma_f32_16x16x32_bf16 v[44:47], v[154:157], v[194:197], v[44:47]
	v_mfma_f32_16x16x32_bf16 v[32:35], v[146:149], v[210:213], v[32:35]
	v_mfma_f32_16x16x32_bf16 v[36:39], v[154:157], v[210:213], v[36:39]
	v_mfma_f32_16x16x32_bf16 v[72:75], v[150:153], v[182:185], v[72:75]
	v_mfma_f32_16x16x32_bf16 v[60:63], v[158:161], v[182:185], v[60:63]
	v_mfma_f32_16x16x32_bf16 v[48:51], v[150:153], v[190:193], v[48:51]
	v_mfma_f32_16x16x32_bf16 v[52:55], v[158:161], v[190:193], v[52:55]
	v_mfma_f32_16x16x32_bf16 v[40:43], v[150:153], v[198:201], v[40:43]
	v_mfma_f32_16x16x32_bf16 v[44:47], v[158:161], v[198:201], v[44:47]
	v_mfma_f32_16x16x32_bf16 v[32:35], v[150:153], v[214:217], v[32:35]
	v_mfma_f32_16x16x32_bf16 v[36:39], v[158:161], v[214:217], v[36:39]
	s_setprio 0
	s_setprio 1
	v_mfma_f32_16x16x32_bf16 v[122:125], v[162:165], v[178:181], v[122:125]
	v_mfma_f32_16x16x32_bf16 v[126:129], v[170:173], v[178:181], v[126:129]
	v_mfma_f32_16x16x32_bf16 v[114:117], v[162:165], v[186:189], v[114:117]
	v_mfma_f32_16x16x32_bf16 v[118:121], v[170:173], v[186:189], v[118:121]
	v_mfma_f32_16x16x32_bf16 v[106:109], v[162:165], v[194:197], v[106:109]
	v_mfma_f32_16x16x32_bf16 v[110:113], v[170:173], v[194:197], v[110:113]
	v_mfma_f32_16x16x32_bf16 v[98:101], v[162:165], v[210:213], v[98:101]
	v_mfma_f32_16x16x32_bf16 v[102:105], v[170:173], v[210:213], v[102:105]
	v_mfma_f32_16x16x32_bf16 v[122:125], v[166:169], v[182:185], v[122:125]
	v_mfma_f32_16x16x32_bf16 v[126:129], v[174:177], v[182:185], v[126:129]
	v_mfma_f32_16x16x32_bf16 v[114:117], v[166:169], v[190:193], v[114:117]
	v_mfma_f32_16x16x32_bf16 v[118:121], v[174:177], v[190:193], v[118:121]
	v_mfma_f32_16x16x32_bf16 v[106:109], v[166:169], v[198:201], v[106:109]
	v_mfma_f32_16x16x32_bf16 v[110:113], v[174:177], v[198:201], v[110:113]
	v_mfma_f32_16x16x32_bf16 v[98:101], v[166:169], v[214:217], v[98:101]
	v_mfma_f32_16x16x32_bf16 v[102:105], v[174:177], v[214:217], v[102:105]
	s_setprio 0
	s_barrier
	s_add_i32 s44, s44, 2
	s_add_u32 s3, s3, 0x100
	s_addc_u32 s43, s43, 0
	s_cmpk_gt_u32 s44, 0x55
	s_mov_b64 s[52:53], s[16:17]
	s_cbranch_scc0 .LBB0_1432
	s_and_b64 vcc, exec, s[14:15]
	s_cbranch_vccz .LBB0_1435
	s_barrier
